# all six K-loops: LDS-DMA loads in SGPR-base + VGPR-offset form, B-fragment ds_reads via one base + immediate offsets, C=0 first-iteration peel
# speedup vs baseline: 1.0178x; 1.0052x over previous
; #define PG8_STAGE(bufoff, gbase, voff) do { _Pragma("unroll") for (int _i = 0; _i < 2; ++_i) \
;         __builtin_amdgcn_global_load_lds((const unsigned*)((const char*)(gbase) + (voff)[_i]), (PG8_LAS unsigned*)(lds + (bufoff) + ldsw + _i * 8192), 16, 0, 0); } while (0)
; #define PG8_LDA(dst, b, h) do { _Pragma("unroll") for (int m = 0; m < 4; ++m) _Pragma("unroll") for (int k = 0; k < 2; ++k) dst[m][k] = *(const PG8_LAS bf16x8*)(lds + PG8_SA(b, h) + aoff + m * 2048 + k * 1024); } while (0)
; #define PG8_LDB(dst, b, h) do { _Pragma("unroll") for (int n = 0; n < 2; ++n) _Pragma("unroll") for (int k = 0; k < 2; ++k) dst[n][k] = *(const PG8_LAS bf16x8*)(lds + PG8_SB(b, h) + boff + n * 2048 + k * 1024); } while (0)
; #define PG8_WAIT_V(n) asm volatile("s_waitcnt vmcnt(" #n ")" ::: "memory")
; #define PG8_WAIT_L(n) asm volatile("s_waitcnt lgkmcnt(" #n ")" ::: "memory")
; #define PG8_BAR __builtin_amdgcn_s_barrier()
; #define PG8_SCHED __builtin_amdgcn_sched_barrier(0)
; template <class Epi, class Sched, bool ALIGN_EPI = false, bool SP2 = false>
; __device__ __forceinline__ void gemm_phase(PG8_LAS unsigned char* lds, const Gemm g, const Sched& S, const Epi& E) {
;     ...
;         const bool has_next = S.next(ui + 1, nxt);
;         const char* nA = has_next ? (const char*)g.A + (size_t)nxt.pm * tstep : cA; const char* nB = has_next ? (const char*)g.Bt + (size_t)nxt.pn * tstep : cB;
;         for (int t = 0; t < nt; t += 2) {
;             const bool last = (t == nt - 2);
;             const char* a1 = cA + (size_t)(t + 1) * kstep;
;             const char* a2 = last ? nA : cA + (size_t)(t + 2) * kstep; const char* b2 = last ? nB : cB + (size_t)(t + 2) * kstep;
;             const char* a3 = a2 + kstep; const char* b3 = b2 + kstep;
;             if (last && has_next) S.a_ready(nxt);
;             if constexpr (SP2) {
;             PG8_LDB(B0, 0, 0); PG8_LDB(B1, 0, 1); PG8_SCHED; PG8_LDA(At, 0, 0); PG8_STAGE(PG8_SA(1, 1), a1 + hstep, voffA);
;             PG8_WAIT_V(8); PG8_WAIT_L(0); PG8_BAR; PG8_MMA(0, 0, At, B0); PG8_MMA(0, 1, At, B1); PG8_BAR; PG8_SCHED;
;             PG8_LDA(At, 0, 1); PG8_STAGE(PG8_SB(0, 0), b2, voffB); PG8_STAGE(PG8_SB(0, 1), b2 + hstep, voffB); PG8_STAGE(PG8_SA(0, 0), a2, voffA);
;             PG8_WAIT_V(8); PG8_WAIT_L(0); PG8_BAR; PG8_MMA(1, 0, At, B0); PG8_MMA(1, 1, At, B1); PG8_BAR; PG8_SCHED;
.LBB0_326:
	s_ashr_i32 s27, s26, 31
	s_lshl_b64 s[4:5], s[26:27], 19
	s_add_u32 s36, s7, s4
	s_addc_u32 s37, s8, s5
	s_and_b64 s[4:5], s[10:11], exec
	s_cselect_b32 s27, s37, s1
	s_cselect_b32 s52, s36, s0
	s_ashr_i32 s25, s24, 31
	s_lshl_b64 s[4:5], s[24:25], 19
	s_add_u32 s38, s9, s4
	s_addc_u32 s39, s28, s5
	s_and_b64 s[4:5], s[10:11], exec
	s_cselect_b32 s25, s39, s3
	s_cselect_b32 s53, s38, s2
	s_add_u32 s0, s0, 0x40080
	s_addc_u32 s1, s1, 0
	s_add_u32 s54, s2, 0x100
	v_mov_b32_e32 v0, 0
	s_addc_u32 s55, s3, 0
	s_mov_b32 s56, -2
	s_waitcnt lgkmcnt(0)
	v_add_u32_e32 v254, 0x10000, v180
.Labo_peel:
	ds_read_b128 v[68:71], v254
	ds_read_b128 v[72:75], v254 offset:1024
	ds_read_b128 v[76:79], v254 offset:2048
	ds_read_b128 v[80:83], v254 offset:3072
	ds_read_b128 v[174:177], v254 offset:16384
	ds_read_b128 v[182:185], v254 offset:17408
	ds_read_b128 v[186:189], v254 offset:18432
	ds_read_b128 v[210:213], v254 offset:19456
	s_add_u32 s2, s0, 0xfffc0080
	s_addc_u32 s3, s1, -1
	s_cmp_eq_u32 s56, 12
	s_cselect_b32 s5, s27, s3
	s_cselect_b32 s4, s52, s2
	s_cselect_b32 s3, s25, s55
	s_cselect_b32 s2, s53, s54
	s_add_i32 m0, s29, 0xc000
	ds_read_b128 v[214:217], v179
	ds_read_b128 v[218:221], v179 offset:1024
	ds_read_b128 v[222:225], v179 offset:2048
	ds_read_b128 v[226:229], v179 offset:3072
	ds_read_b128 v[230:233], v179 offset:4096
	ds_read_b128 v[234:237], v179 offset:5120
	ds_read_b128 v[238:241], v179 offset:6144
	ds_read_b128 v[242:245], v179 offset:7168
	global_load_lds_dwordx4 v170, s[0:1]
	s_add_i32 m0, s29, 0xe000
	s_nop 0
	global_load_lds_dwordx4 v172, s[0:1]
	s_waitcnt vmcnt(8)
	s_waitcnt lgkmcnt(0)
	s_barrier
	s_setprio 1
	s_waitcnt lgkmcnt(0)
	v_mfma_f32_16x16x32_bf16 v[140:143], v[68:71], v[214:217], 0
	v_mfma_f32_16x16x32_bf16 v[136:139], v[76:79], v[214:217], 0
	v_mfma_f32_16x16x32_bf16 v[124:127], v[68:71], v[222:225], 0
	v_mfma_f32_16x16x32_bf16 v[120:123], v[76:79], v[222:225], 0
	v_mfma_f32_16x16x32_bf16 v[108:111], v[68:71], v[230:233], 0
	v_mfma_f32_16x16x32_bf16 v[104:107], v[76:79], v[230:233], 0
	v_mfma_f32_16x16x32_bf16 v[92:95], v[68:71], v[238:241], 0
	v_mfma_f32_16x16x32_bf16 v[88:91], v[76:79], v[238:241], 0
	v_mfma_f32_16x16x32_bf16 v[140:143], v[72:75], v[218:221], v[140:143]
	v_mfma_f32_16x16x32_bf16 v[136:139], v[80:83], v[218:221], v[136:139]
	v_mfma_f32_16x16x32_bf16 v[124:127], v[72:75], v[226:229], v[124:127]
	v_mfma_f32_16x16x32_bf16 v[120:123], v[80:83], v[226:229], v[120:123]
	v_mfma_f32_16x16x32_bf16 v[108:111], v[72:75], v[234:237], v[108:111]
	v_mfma_f32_16x16x32_bf16 v[104:107], v[80:83], v[234:237], v[104:107]
	v_mfma_f32_16x16x32_bf16 v[92:95], v[72:75], v[242:245], v[92:95]
	v_mfma_f32_16x16x32_bf16 v[88:91], v[80:83], v[242:245], v[88:91]
	s_setprio 0
	s_setprio 1
	v_mfma_f32_16x16x32_bf16 v[132:135], v[174:177], v[214:217], 0
	v_mfma_f32_16x16x32_bf16 v[128:131], v[186:189], v[214:217], 0
	v_mfma_f32_16x16x32_bf16 v[116:119], v[174:177], v[222:225], 0
	v_mfma_f32_16x16x32_bf16 v[112:115], v[186:189], v[222:225], 0
	v_mfma_f32_16x16x32_bf16 v[100:103], v[174:177], v[230:233], 0
	v_mfma_f32_16x16x32_bf16 v[96:99], v[186:189], v[230:233], 0
	v_mfma_f32_16x16x32_bf16 v[84:87], v[174:177], v[238:241], 0
	v_mfma_f32_16x16x32_bf16 v[64:67], v[186:189], v[238:241], 0
	v_mfma_f32_16x16x32_bf16 v[132:135], v[182:185], v[218:221], v[132:135]
	v_mfma_f32_16x16x32_bf16 v[128:131], v[210:213], v[218:221], v[128:131]
	v_mfma_f32_16x16x32_bf16 v[116:119], v[182:185], v[226:229], v[116:119]
	v_mfma_f32_16x16x32_bf16 v[112:115], v[210:213], v[226:229], v[112:115]
	v_mfma_f32_16x16x32_bf16 v[100:103], v[182:185], v[234:237], v[100:103]
	v_mfma_f32_16x16x32_bf16 v[96:99], v[210:213], v[234:237], v[96:99]
	v_mfma_f32_16x16x32_bf16 v[84:87], v[182:185], v[242:245], v[84:87]
	v_mfma_f32_16x16x32_bf16 v[64:67], v[210:213], v[242:245], v[64:67]
	s_setprio 0
	s_barrier
	s_mov_b32 m0, s30
	s_add_u32 s58, s2, 0x40000
	s_addc_u32 s59, s3, 0
	ds_read_b128 v[214:217], v179 offset:16384
	ds_read_b128 v[218:221], v179 offset:17408
	ds_read_b128 v[222:225], v179 offset:18432
	ds_read_b128 v[226:229], v179 offset:19456
	ds_read_b128 v[230:233], v179 offset:20480
	ds_read_b128 v[234:237], v179 offset:21504
	ds_read_b128 v[238:241], v179 offset:22528
	ds_read_b128 v[242:245], v179 offset:23552
	global_load_lds_dwordx4 v166, s[2:3]
	s_mov_b32 m0, s31
	s_nop 0
	global_load_lds_dwordx4 v162, s[2:3]
	s_mov_b32 m0, s33
	s_nop 0
	global_load_lds_dwordx4 v166, s[58:59]
	s_mov_b32 m0, s34
	s_nop 0
	global_load_lds_dwordx4 v162, s[58:59]
	s_mov_b32 m0, s29
	s_nop 0
	global_load_lds_dwordx4 v168, s[4:5]
	s_mov_b32 m0, s35
	s_nop 0
	global_load_lds_dwordx4 v164, s[4:5]
	s_waitcnt vmcnt(8)
	s_waitcnt lgkmcnt(0)
	s_barrier
; #define PG8_STAGE(bufoff, gbase, voff) do { _Pragma("unroll") for (int _i = 0; _i < 2; ++_i) \
;         __builtin_amdgcn_global_load_lds((const unsigned*)((const char*)(gbase) + (voff)[_i]), (PG8_LAS unsigned*)(lds + (bufoff) + ldsw + _i * 8192), 16, 0, 0); } while (0)
; #define PG8_LDA(dst, b, h) do { _Pragma("unroll") for (int m = 0; m < 4; ++m) _Pragma("unroll") for (int k = 0; k < 2; ++k) dst[m][k] = *(const PG8_LAS bf16x8*)(lds + PG8_SA(b, h) + aoff + m * 2048 + k * 1024); } while (0)
; #define PG8_LDB(dst, b, h) do { _Pragma("unroll") for (int n = 0; n < 2; ++n) _Pragma("unroll") for (int k = 0; k < 2; ++k) dst[n][k] = *(const PG8_LAS bf16x8*)(lds + PG8_SB(b, h) + boff + n * 2048 + k * 1024); } while (0)
; #define PG8_MMA(ai, bj, At, Bt) do { __builtin_amdgcn_s_setprio(1); _Pragma("unroll") for (int m = 0; m < 4; ++m) _Pragma("unroll") for (int n = 0; n < 2; ++n) _Pragma("unroll") for (int k = 0; k < 2; ++k) \
;         acc[ai][bj][m][n] = __builtin_amdgcn_mfma_f32_16x16x32_bf16(Bt[n][k], At[m][k], acc[ai][bj][m][n], 0, 0, 0); __builtin_amdgcn_s_setprio(0); } while (0)
; #define PG8_WAIT_V(n) asm volatile("s_waitcnt vmcnt(" #n ")" ::: "memory")
; #define PG8_WAIT_L(n) asm volatile("s_waitcnt lgkmcnt(" #n ")" ::: "memory")
; #define PG8_BAR __builtin_amdgcn_s_barrier()
; #define PG8_SCHED __builtin_amdgcn_sched_barrier(0)
; template <class Epi, class Sched, bool ALIGN_EPI = false, bool SP2 = false>
; __device__ __forceinline__ void gemm_phase(PG8_LAS unsigned char* lds, const Gemm g, const Sched& S, const Epi& E) {
;     ...
;             PG8_WAIT_V(8); PG8_WAIT_L(0); PG8_BAR; PG8_MMA(1, 0, At, B0); PG8_MMA(1, 1, At, B1); PG8_BAR; PG8_SCHED;
;             PG8_LDB(B0, 1, 0); PG8_LDB(B1, 1, 1); PG8_SCHED; PG8_LDA(At, 1, 0); PG8_STAGE(PG8_SA(0, 1), a2 + hstep, voffA);
;             PG8_WAIT_V(8); PG8_WAIT_L(0); PG8_BAR; PG8_MMA(0, 0, At, B0); PG8_MMA(0, 1, At, B1); PG8_BAR; PG8_SCHED;
	s_setprio 1
	s_waitcnt lgkmcnt(0)
	v_mfma_f32_16x16x32_bf16 v[60:63], v[68:71], v[214:217], 0
	v_mfma_f32_16x16x32_bf16 v[56:59], v[76:79], v[214:217], 0
	v_mfma_f32_16x16x32_bf16 v[44:47], v[68:71], v[222:225], 0
	v_mfma_f32_16x16x32_bf16 v[40:43], v[76:79], v[222:225], 0
	v_mfma_f32_16x16x32_bf16 v[28:31], v[68:71], v[230:233], 0
	v_mfma_f32_16x16x32_bf16 v[24:27], v[76:79], v[230:233], 0
	v_mfma_f32_16x16x32_bf16 v[12:15], v[68:71], v[238:241], 0
	v_mfma_f32_16x16x32_bf16 v[8:11], v[76:79], v[238:241], 0
	v_mfma_f32_16x16x32_bf16 v[60:63], v[72:75], v[218:221], v[60:63]
	v_mfma_f32_16x16x32_bf16 v[56:59], v[80:83], v[218:221], v[56:59]
	v_mfma_f32_16x16x32_bf16 v[44:47], v[72:75], v[226:229], v[44:47]
	v_mfma_f32_16x16x32_bf16 v[40:43], v[80:83], v[226:229], v[40:43]
	v_mfma_f32_16x16x32_bf16 v[28:31], v[72:75], v[234:237], v[28:31]
	v_mfma_f32_16x16x32_bf16 v[24:27], v[80:83], v[234:237], v[24:27]
	v_mfma_f32_16x16x32_bf16 v[12:15], v[72:75], v[242:245], v[12:15]
	v_mfma_f32_16x16x32_bf16 v[8:11], v[80:83], v[242:245], v[8:11]
	s_setprio 0
	s_setprio 1
	v_mfma_f32_16x16x32_bf16 v[52:55], v[174:177], v[214:217], 0
	v_mfma_f32_16x16x32_bf16 v[48:51], v[186:189], v[214:217], 0
	v_mfma_f32_16x16x32_bf16 v[36:39], v[174:177], v[222:225], 0
	v_mfma_f32_16x16x32_bf16 v[32:35], v[186:189], v[222:225], 0
	v_mfma_f32_16x16x32_bf16 v[20:23], v[174:177], v[230:233], 0
	v_mfma_f32_16x16x32_bf16 v[16:19], v[186:189], v[230:233], 0
	v_mfma_f32_16x16x32_bf16 v[4:7], v[174:177], v[238:241], 0
	v_mfma_f32_16x16x32_bf16 v[0:3], v[186:189], v[238:241], 0
	v_mfma_f32_16x16x32_bf16 v[52:55], v[182:185], v[218:221], v[52:55]
	v_mfma_f32_16x16x32_bf16 v[48:51], v[210:213], v[218:221], v[48:51]
	v_mfma_f32_16x16x32_bf16 v[36:39], v[182:185], v[226:229], v[36:39]
	v_mfma_f32_16x16x32_bf16 v[32:35], v[210:213], v[226:229], v[32:35]
	v_mfma_f32_16x16x32_bf16 v[20:23], v[182:185], v[234:237], v[20:23]
	v_mfma_f32_16x16x32_bf16 v[16:19], v[210:213], v[234:237], v[16:19]
	v_mfma_f32_16x16x32_bf16 v[4:7], v[182:185], v[242:245], v[4:7]
	v_mfma_f32_16x16x32_bf16 v[0:3], v[210:213], v[242:245], v[0:3]
	s_setprio 0
	s_barrier
	ds_read_b128 v[68:71], v254 offset:32768
	ds_read_b128 v[72:75], v254 offset:33792
	ds_read_b128 v[76:79], v254 offset:34816
	ds_read_b128 v[80:83], v254 offset:35840
	ds_read_b128 v[174:177], v254 offset:49152
	ds_read_b128 v[182:185], v254 offset:50176
	ds_read_b128 v[186:189], v254 offset:51200
	ds_read_b128 v[210:213], v254 offset:52224
	s_add_u32 s4, s4, 0x40000
	s_addc_u32 s5, s5, 0
	s_mov_b32 m0, s40
	ds_read_b128 v[214:217], v179 offset:32768
	ds_read_b128 v[218:221], v179 offset:33792
	ds_read_b128 v[222:225], v179 offset:34816
	ds_read_b128 v[226:229], v179 offset:35840
	ds_read_b128 v[230:233], v179 offset:36864
	ds_read_b128 v[234:237], v179 offset:37888
	ds_read_b128 v[238:241], v179 offset:38912
	ds_read_b128 v[242:245], v179 offset:39936
	global_load_lds_dwordx4 v168, s[4:5]
	s_mov_b32 m0, s41
	s_nop 0
	global_load_lds_dwordx4 v164, s[4:5]
	s_waitcnt vmcnt(8)
	s_waitcnt lgkmcnt(0)
	s_barrier
	s_setprio 1
	s_waitcnt lgkmcnt(0)
	v_mfma_f32_16x16x32_bf16 v[140:143], v[68:71], v[214:217], v[140:143]
	v_mfma_f32_16x16x32_bf16 v[136:139], v[76:79], v[214:217], v[136:139]
	v_mfma_f32_16x16x32_bf16 v[124:127], v[68:71], v[222:225], v[124:127]
	v_mfma_f32_16x16x32_bf16 v[120:123], v[76:79], v[222:225], v[120:123]
	v_mfma_f32_16x16x32_bf16 v[108:111], v[68:71], v[230:233], v[108:111]
	v_mfma_f32_16x16x32_bf16 v[104:107], v[76:79], v[230:233], v[104:107]
	v_mfma_f32_16x16x32_bf16 v[92:95], v[68:71], v[238:241], v[92:95]
	v_mfma_f32_16x16x32_bf16 v[88:91], v[76:79], v[238:241], v[88:91]
	v_mfma_f32_16x16x32_bf16 v[140:143], v[72:75], v[218:221], v[140:143]
	v_mfma_f32_16x16x32_bf16 v[136:139], v[80:83], v[218:221], v[136:139]
	v_mfma_f32_16x16x32_bf16 v[124:127], v[72:75], v[226:229], v[124:127]
	v_mfma_f32_16x16x32_bf16 v[120:123], v[80:83], v[226:229], v[120:123]
	v_mfma_f32_16x16x32_bf16 v[108:111], v[72:75], v[234:237], v[108:111]
	v_mfma_f32_16x16x32_bf16 v[104:107], v[80:83], v[234:237], v[104:107]
	v_mfma_f32_16x16x32_bf16 v[92:95], v[72:75], v[242:245], v[92:95]
	v_mfma_f32_16x16x32_bf16 v[88:91], v[80:83], v[242:245], v[88:91]
	s_setprio 0
	s_setprio 1
	v_mfma_f32_16x16x32_bf16 v[132:135], v[174:177], v[214:217], v[132:135]
	v_mfma_f32_16x16x32_bf16 v[128:131], v[186:189], v[214:217], v[128:131]
	v_mfma_f32_16x16x32_bf16 v[116:119], v[174:177], v[222:225], v[116:119]
	v_mfma_f32_16x16x32_bf16 v[112:115], v[186:189], v[222:225], v[112:115]
	v_mfma_f32_16x16x32_bf16 v[100:103], v[174:177], v[230:233], v[100:103]
	v_mfma_f32_16x16x32_bf16 v[96:99], v[186:189], v[230:233], v[96:99]
	v_mfma_f32_16x16x32_bf16 v[84:87], v[174:177], v[238:241], v[84:87]
	v_mfma_f32_16x16x32_bf16 v[64:67], v[186:189], v[238:241], v[64:67]
	v_mfma_f32_16x16x32_bf16 v[132:135], v[182:185], v[218:221], v[132:135]
	v_mfma_f32_16x16x32_bf16 v[128:131], v[210:213], v[218:221], v[128:131]
	v_mfma_f32_16x16x32_bf16 v[116:119], v[182:185], v[226:229], v[116:119]
	v_mfma_f32_16x16x32_bf16 v[112:115], v[210:213], v[226:229], v[112:115]
	v_mfma_f32_16x16x32_bf16 v[100:103], v[182:185], v[234:237], v[100:103]
	v_mfma_f32_16x16x32_bf16 v[96:99], v[210:213], v[234:237], v[96:99]
	v_mfma_f32_16x16x32_bf16 v[84:87], v[182:185], v[242:245], v[84:87]
	v_mfma_f32_16x16x32_bf16 v[64:67], v[210:213], v[242:245], v[64:67]
	s_setprio 0
	s_barrier
; #define PG8_STAGE(bufoff, gbase, voff) do { _Pragma("unroll") for (int _i = 0; _i < 2; ++_i) \
;         __builtin_amdgcn_global_load_lds((const unsigned*)((const char*)(gbase) + (voff)[_i]), (PG8_LAS unsigned*)(lds + (bufoff) + ldsw + _i * 8192), 16, 0, 0); } while (0)
; #define PG8_LDA(dst, b, h) do { _Pragma("unroll") for (int m = 0; m < 4; ++m) _Pragma("unroll") for (int k = 0; k < 2; ++k) dst[m][k] = *(const PG8_LAS bf16x8*)(lds + PG8_SA(b, h) + aoff + m * 2048 + k * 1024); } while (0)
; #define PG8_LDB(dst, b, h) do { _Pragma("unroll") for (int n = 0; n < 2; ++n) _Pragma("unroll") for (int k = 0; k < 2; ++k) dst[n][k] = *(const PG8_LAS bf16x8*)(lds + PG8_SB(b, h) + boff + n * 2048 + k * 1024); } while (0)
; #define PG8_MMA(ai, bj, At, Bt) do { __builtin_amdgcn_s_setprio(1); _Pragma("unroll") for (int m = 0; m < 4; ++m) _Pragma("unroll") for (int n = 0; n < 2; ++n) _Pragma("unroll") for (int k = 0; k < 2; ++k) \
;         acc[ai][bj][m][n] = __builtin_amdgcn_mfma_f32_16x16x32_bf16(Bt[n][k], At[m][k], acc[ai][bj][m][n], 0, 0, 0); __builtin_amdgcn_s_setprio(0); } while (0)
; #define PG8_WAIT_V(n) asm volatile("s_waitcnt vmcnt(" #n ")" ::: "memory")
; #define PG8_WAIT_L(n) asm volatile("s_waitcnt lgkmcnt(" #n ")" ::: "memory")
; #define PG8_BAR __builtin_amdgcn_s_barrier()
; #define PG8_SCHED __builtin_amdgcn_sched_barrier(0)
; template <class Epi, class Sched, bool ALIGN_EPI = false, bool SP2 = false>
; __device__ __forceinline__ void gemm_phase(PG8_LAS unsigned char* lds, const Gemm g, const Sched& S, const Epi& E) {
;     ...
;             PG8_LDB(B0, 0, 0); PG8_LDB(B1, 0, 1); PG8_SCHED; PG8_LDA(At, 0, 0); PG8_STAGE(PG8_SA(1, 1), a1 + hstep, voffA);
;             PG8_WAIT_V(8); PG8_WAIT_L(0); PG8_BAR; PG8_MMA(0, 0, At, B0); PG8_MMA(0, 1, At, B1); PG8_BAR; PG8_SCHED;
;     ...
;             PG8_LDA(At, 1, 1); PG8_STAGE(PG8_SB(1, 0), b3, voffB); PG8_STAGE(PG8_SB(1, 1), b3 + hstep, voffB); PG8_STAGE(PG8_SA(1, 0), a3, voffA);
;             PG8_WAIT_V(8); PG8_WAIT_L(0); PG8_BAR; PG8_MMA(1, 0, At, B0); PG8_MMA(1, 1, At, B1); PG8_BAR; PG8_SCHED;
	s_mov_b32 m0, s45
	s_add_u32 s2, s2, 0x40080
	s_addc_u32 s3, s3, 0
	ds_read_b128 v[214:217], v179 offset:49152
	ds_read_b128 v[218:221], v179 offset:50176
	ds_read_b128 v[222:225], v179 offset:51200
	ds_read_b128 v[226:229], v179 offset:52224
	ds_read_b128 v[230:233], v179 offset:53248
	ds_read_b128 v[234:237], v179 offset:54272
	ds_read_b128 v[238:241], v179 offset:55296
	ds_read_b128 v[242:245], v179 offset:56320
	s_add_u32 s98, s2, 0xfffc0000
	s_addc_u32 s99, s3, -1
	global_load_lds_dwordx4 v166, s[98:99]
	s_mov_b32 m0, s46
	s_nop 0
	global_load_lds_dwordx4 v162, s[98:99]
	s_mov_b32 m0, s49
	s_nop 0
	global_load_lds_dwordx4 v166, s[2:3]
	s_mov_b32 m0, s50
	s_nop 0
	global_load_lds_dwordx4 v162, s[2:3]
	s_mov_b32 m0, s47
	s_nop 0
	s_add_u32 s100, s4, 0xfffc0080
	s_addc_u32 s101, s5, -1
	global_load_lds_dwordx4 v168, s[100:101]
	s_mov_b32 m0, s48
	s_nop 0
	global_load_lds_dwordx4 v164, s[100:101]
	s_waitcnt vmcnt(8)
	s_waitcnt lgkmcnt(0)
	s_barrier
	s_setprio 1
	s_waitcnt lgkmcnt(0)
	v_mfma_f32_16x16x32_bf16 v[60:63], v[68:71], v[214:217], v[60:63]
	v_mfma_f32_16x16x32_bf16 v[56:59], v[76:79], v[214:217], v[56:59]
	v_mfma_f32_16x16x32_bf16 v[44:47], v[68:71], v[222:225], v[44:47]
	v_mfma_f32_16x16x32_bf16 v[40:43], v[76:79], v[222:225], v[40:43]
	v_mfma_f32_16x16x32_bf16 v[28:31], v[68:71], v[230:233], v[28:31]
	v_mfma_f32_16x16x32_bf16 v[24:27], v[76:79], v[230:233], v[24:27]
	v_mfma_f32_16x16x32_bf16 v[12:15], v[68:71], v[238:241], v[12:15]
	v_mfma_f32_16x16x32_bf16 v[8:11], v[76:79], v[238:241], v[8:11]
	v_mfma_f32_16x16x32_bf16 v[60:63], v[72:75], v[218:221], v[60:63]
	v_mfma_f32_16x16x32_bf16 v[56:59], v[80:83], v[218:221], v[56:59]
	v_mfma_f32_16x16x32_bf16 v[44:47], v[72:75], v[226:229], v[44:47]
	v_mfma_f32_16x16x32_bf16 v[40:43], v[80:83], v[226:229], v[40:43]
	v_mfma_f32_16x16x32_bf16 v[28:31], v[72:75], v[234:237], v[28:31]
	v_mfma_f32_16x16x32_bf16 v[24:27], v[80:83], v[234:237], v[24:27]
	v_mfma_f32_16x16x32_bf16 v[12:15], v[72:75], v[242:245], v[12:15]
	v_mfma_f32_16x16x32_bf16 v[8:11], v[80:83], v[242:245], v[8:11]
	s_setprio 0
	s_setprio 1
	v_mfma_f32_16x16x32_bf16 v[52:55], v[174:177], v[214:217], v[52:55]
	v_mfma_f32_16x16x32_bf16 v[48:51], v[186:189], v[214:217], v[48:51]
	v_mfma_f32_16x16x32_bf16 v[36:39], v[174:177], v[222:225], v[36:39]
	v_mfma_f32_16x16x32_bf16 v[32:35], v[186:189], v[222:225], v[32:35]
	v_mfma_f32_16x16x32_bf16 v[20:23], v[174:177], v[230:233], v[20:23]
	v_mfma_f32_16x16x32_bf16 v[16:19], v[186:189], v[230:233], v[16:19]
	v_mfma_f32_16x16x32_bf16 v[4:7], v[174:177], v[238:241], v[4:7]
	v_mfma_f32_16x16x32_bf16 v[0:3], v[186:189], v[238:241], v[0:3]
	v_mfma_f32_16x16x32_bf16 v[52:55], v[182:185], v[218:221], v[52:55]
	v_mfma_f32_16x16x32_bf16 v[48:51], v[210:213], v[218:221], v[48:51]
	v_mfma_f32_16x16x32_bf16 v[36:39], v[182:185], v[226:229], v[36:39]
	v_mfma_f32_16x16x32_bf16 v[32:35], v[210:213], v[226:229], v[32:35]
	v_mfma_f32_16x16x32_bf16 v[20:23], v[182:185], v[234:237], v[20:23]
	v_mfma_f32_16x16x32_bf16 v[16:19], v[210:213], v[234:237], v[16:19]
	v_mfma_f32_16x16x32_bf16 v[4:7], v[182:185], v[242:245], v[4:7]
	v_mfma_f32_16x16x32_bf16 v[0:3], v[210:213], v[242:245], v[0:3]
	s_setprio 0
	s_barrier
	s_add_i32 s56, s56, 2
	s_add_u32 s0, s0, 0x100
	s_addc_u32 s1, s1, 0
	s_add_u32 s54, s54, 0x100
	s_addc_u32 s55, s55, 0
	s_cmp_gt_u32 s56, 13
.LBB0_327:
	ds_read_b128 v[68:71], v254
	ds_read_b128 v[72:75], v254 offset:1024
	ds_read_b128 v[76:79], v254 offset:2048
	ds_read_b128 v[80:83], v254 offset:3072
	ds_read_b128 v[174:177], v254 offset:16384
	ds_read_b128 v[182:185], v254 offset:17408
	ds_read_b128 v[186:189], v254 offset:18432
	ds_read_b128 v[210:213], v254 offset:19456
	s_add_u32 s2, s0, 0xfffc0080
	s_addc_u32 s3, s1, -1
	s_cmp_eq_u32 s56, 12
	s_cselect_b32 s5, s27, s3
	s_cselect_b32 s4, s52, s2
	s_cselect_b32 s3, s25, s55
	s_cselect_b32 s2, s53, s54
	s_add_i32 m0, s29, 0xc000
	ds_read_b128 v[214:217], v179
	ds_read_b128 v[218:221], v179 offset:1024
	ds_read_b128 v[222:225], v179 offset:2048
	ds_read_b128 v[226:229], v179 offset:3072
	ds_read_b128 v[230:233], v179 offset:4096
	ds_read_b128 v[234:237], v179 offset:5120
	ds_read_b128 v[238:241], v179 offset:6144
	ds_read_b128 v[242:245], v179 offset:7168
	global_load_lds_dwordx4 v170, s[0:1]
	s_add_i32 m0, s29, 0xe000
	s_nop 0
	global_load_lds_dwordx4 v172, s[0:1]
	s_waitcnt vmcnt(8)
	s_waitcnt lgkmcnt(0)
	s_barrier
	s_setprio 1
	s_waitcnt lgkmcnt(0)
	v_mfma_f32_16x16x32_bf16 v[140:143], v[68:71], v[214:217], v[140:143]
	v_mfma_f32_16x16x32_bf16 v[136:139], v[76:79], v[214:217], v[136:139]
	v_mfma_f32_16x16x32_bf16 v[124:127], v[68:71], v[222:225], v[124:127]
	v_mfma_f32_16x16x32_bf16 v[120:123], v[76:79], v[222:225], v[120:123]
	v_mfma_f32_16x16x32_bf16 v[108:111], v[68:71], v[230:233], v[108:111]
	v_mfma_f32_16x16x32_bf16 v[104:107], v[76:79], v[230:233], v[104:107]
	v_mfma_f32_16x16x32_bf16 v[92:95], v[68:71], v[238:241], v[92:95]
	v_mfma_f32_16x16x32_bf16 v[88:91], v[76:79], v[238:241], v[88:91]
	v_mfma_f32_16x16x32_bf16 v[140:143], v[72:75], v[218:221], v[140:143]
	v_mfma_f32_16x16x32_bf16 v[136:139], v[80:83], v[218:221], v[136:139]
	v_mfma_f32_16x16x32_bf16 v[124:127], v[72:75], v[226:229], v[124:127]
	v_mfma_f32_16x16x32_bf16 v[120:123], v[80:83], v[226:229], v[120:123]
	v_mfma_f32_16x16x32_bf16 v[108:111], v[72:75], v[234:237], v[108:111]
	v_mfma_f32_16x16x32_bf16 v[104:107], v[80:83], v[234:237], v[104:107]
	v_mfma_f32_16x16x32_bf16 v[92:95], v[72:75], v[242:245], v[92:95]
	v_mfma_f32_16x16x32_bf16 v[88:91], v[80:83], v[242:245], v[88:91]
	s_setprio 0
	s_setprio 1
	v_mfma_f32_16x16x32_bf16 v[132:135], v[174:177], v[214:217], v[132:135]
	v_mfma_f32_16x16x32_bf16 v[128:131], v[186:189], v[214:217], v[128:131]
	v_mfma_f32_16x16x32_bf16 v[116:119], v[174:177], v[222:225], v[116:119]
	v_mfma_f32_16x16x32_bf16 v[112:115], v[186:189], v[222:225], v[112:115]
	v_mfma_f32_16x16x32_bf16 v[100:103], v[174:177], v[230:233], v[100:103]
	v_mfma_f32_16x16x32_bf16 v[96:99], v[186:189], v[230:233], v[96:99]
	v_mfma_f32_16x16x32_bf16 v[84:87], v[174:177], v[238:241], v[84:87]
	v_mfma_f32_16x16x32_bf16 v[64:67], v[186:189], v[238:241], v[64:67]
	v_mfma_f32_16x16x32_bf16 v[132:135], v[182:185], v[218:221], v[132:135]
	v_mfma_f32_16x16x32_bf16 v[128:131], v[210:213], v[218:221], v[128:131]
	v_mfma_f32_16x16x32_bf16 v[116:119], v[182:185], v[226:229], v[116:119]
	v_mfma_f32_16x16x32_bf16 v[112:115], v[210:213], v[226:229], v[112:115]
	v_mfma_f32_16x16x32_bf16 v[100:103], v[182:185], v[234:237], v[100:103]
	v_mfma_f32_16x16x32_bf16 v[96:99], v[210:213], v[234:237], v[96:99]
	v_mfma_f32_16x16x32_bf16 v[84:87], v[182:185], v[242:245], v[84:87]
	v_mfma_f32_16x16x32_bf16 v[64:67], v[210:213], v[242:245], v[64:67]
	s_setprio 0
	s_barrier
; #define PG8_STAGE(bufoff, gbase, voff) do { _Pragma("unroll") for (int _i = 0; _i < 2; ++_i) \
;         __builtin_amdgcn_global_load_lds((const unsigned*)((const char*)(gbase) + (voff)[_i]), (PG8_LAS unsigned*)(lds + (bufoff) + ldsw + _i * 8192), 16, 0, 0); } while (0)
; #define PG8_LDA(dst, b, h) do { _Pragma("unroll") for (int m = 0; m < 4; ++m) _Pragma("unroll") for (int k = 0; k < 2; ++k) dst[m][k] = *(const PG8_LAS bf16x8*)(lds + PG8_SA(b, h) + aoff + m * 2048 + k * 1024); } while (0)
; #define PG8_LDB(dst, b, h) do { _Pragma("unroll") for (int n = 0; n < 2; ++n) _Pragma("unroll") for (int k = 0; k < 2; ++k) dst[n][k] = *(const PG8_LAS bf16x8*)(lds + PG8_SB(b, h) + boff + n * 2048 + k * 1024); } while (0)
; #define PG8_MMA(ai, bj, At, Bt) do { __builtin_amdgcn_s_setprio(1); _Pragma("unroll") for (int m = 0; m < 4; ++m) _Pragma("unroll") for (int n = 0; n < 2; ++n) _Pragma("unroll") for (int k = 0; k < 2; ++k) \
;         acc[ai][bj][m][n] = __builtin_amdgcn_mfma_f32_16x16x32_bf16(Bt[n][k], At[m][k], acc[ai][bj][m][n], 0, 0, 0); __builtin_amdgcn_s_setprio(0); } while (0)
; #define PG8_WAIT_V(n) asm volatile("s_waitcnt vmcnt(" #n ")" ::: "memory")
; #define PG8_WAIT_L(n) asm volatile("s_waitcnt lgkmcnt(" #n ")" ::: "memory")
; #define PG8_BAR __builtin_amdgcn_s_barrier()
; #define PG8_SCHED __builtin_amdgcn_sched_barrier(0)
; template <class Epi, class Sched, bool ALIGN_EPI = false, bool SP2 = false>
; __device__ __forceinline__ void gemm_phase(PG8_LAS unsigned char* lds, const Gemm g, const Sched& S, const Epi& E) {
;     ...
;             PG8_LDA(At, 0, 1); PG8_STAGE(PG8_SB(0, 0), b2, voffB); PG8_STAGE(PG8_SB(0, 1), b2 + hstep, voffB); PG8_STAGE(PG8_SA(0, 0), a2, voffA);
;             PG8_WAIT_V(8); PG8_WAIT_L(0); PG8_BAR; PG8_MMA(1, 0, At, B0); PG8_MMA(1, 1, At, B1); PG8_BAR; PG8_SCHED;
;             PG8_LDB(B0, 1, 0); PG8_LDB(B1, 1, 1); PG8_SCHED; PG8_LDA(At, 1, 0); PG8_STAGE(PG8_SA(0, 1), a2 + hstep, voffA);
;             PG8_WAIT_V(8); PG8_WAIT_L(0); PG8_BAR; PG8_MMA(0, 0, At, B0); PG8_MMA(0, 1, At, B1); PG8_BAR; PG8_SCHED;
	s_mov_b32 m0, s30
	s_add_u32 s58, s2, 0x40000
	s_addc_u32 s59, s3, 0
	ds_read_b128 v[214:217], v179 offset:16384
	ds_read_b128 v[218:221], v179 offset:17408
	ds_read_b128 v[222:225], v179 offset:18432
	ds_read_b128 v[226:229], v179 offset:19456
	ds_read_b128 v[230:233], v179 offset:20480
	ds_read_b128 v[234:237], v179 offset:21504
	ds_read_b128 v[238:241], v179 offset:22528
	ds_read_b128 v[242:245], v179 offset:23552
	global_load_lds_dwordx4 v166, s[2:3]
	s_mov_b32 m0, s31
	s_nop 0
	global_load_lds_dwordx4 v162, s[2:3]
	s_mov_b32 m0, s33
	s_nop 0
	global_load_lds_dwordx4 v166, s[58:59]
	s_mov_b32 m0, s34
	s_nop 0
	global_load_lds_dwordx4 v162, s[58:59]
	s_mov_b32 m0, s29
	s_nop 0
	global_load_lds_dwordx4 v168, s[4:5]
	s_mov_b32 m0, s35
	s_nop 0
	global_load_lds_dwordx4 v164, s[4:5]
	s_waitcnt vmcnt(8)
	s_waitcnt lgkmcnt(0)
	s_barrier
	s_setprio 1
	s_waitcnt lgkmcnt(0)
	v_mfma_f32_16x16x32_bf16 v[60:63], v[68:71], v[214:217], v[60:63]
	v_mfma_f32_16x16x32_bf16 v[56:59], v[76:79], v[214:217], v[56:59]
	v_mfma_f32_16x16x32_bf16 v[44:47], v[68:71], v[222:225], v[44:47]
	v_mfma_f32_16x16x32_bf16 v[40:43], v[76:79], v[222:225], v[40:43]
	v_mfma_f32_16x16x32_bf16 v[28:31], v[68:71], v[230:233], v[28:31]
	v_mfma_f32_16x16x32_bf16 v[24:27], v[76:79], v[230:233], v[24:27]
	v_mfma_f32_16x16x32_bf16 v[12:15], v[68:71], v[238:241], v[12:15]
	v_mfma_f32_16x16x32_bf16 v[8:11], v[76:79], v[238:241], v[8:11]
	v_mfma_f32_16x16x32_bf16 v[60:63], v[72:75], v[218:221], v[60:63]
	v_mfma_f32_16x16x32_bf16 v[56:59], v[80:83], v[218:221], v[56:59]
	v_mfma_f32_16x16x32_bf16 v[44:47], v[72:75], v[226:229], v[44:47]
	v_mfma_f32_16x16x32_bf16 v[40:43], v[80:83], v[226:229], v[40:43]
	v_mfma_f32_16x16x32_bf16 v[28:31], v[72:75], v[234:237], v[28:31]
	v_mfma_f32_16x16x32_bf16 v[24:27], v[80:83], v[234:237], v[24:27]
	v_mfma_f32_16x16x32_bf16 v[12:15], v[72:75], v[242:245], v[12:15]
	v_mfma_f32_16x16x32_bf16 v[8:11], v[80:83], v[242:245], v[8:11]
	s_setprio 0
	s_setprio 1
	v_mfma_f32_16x16x32_bf16 v[52:55], v[174:177], v[214:217], v[52:55]
	v_mfma_f32_16x16x32_bf16 v[48:51], v[186:189], v[214:217], v[48:51]
	v_mfma_f32_16x16x32_bf16 v[36:39], v[174:177], v[222:225], v[36:39]
	v_mfma_f32_16x16x32_bf16 v[32:35], v[186:189], v[222:225], v[32:35]
	v_mfma_f32_16x16x32_bf16 v[20:23], v[174:177], v[230:233], v[20:23]
	v_mfma_f32_16x16x32_bf16 v[16:19], v[186:189], v[230:233], v[16:19]
	v_mfma_f32_16x16x32_bf16 v[4:7], v[174:177], v[238:241], v[4:7]
	v_mfma_f32_16x16x32_bf16 v[0:3], v[186:189], v[238:241], v[0:3]
	v_mfma_f32_16x16x32_bf16 v[52:55], v[182:185], v[218:221], v[52:55]
	v_mfma_f32_16x16x32_bf16 v[48:51], v[210:213], v[218:221], v[48:51]
	v_mfma_f32_16x16x32_bf16 v[36:39], v[182:185], v[226:229], v[36:39]
	v_mfma_f32_16x16x32_bf16 v[32:35], v[210:213], v[226:229], v[32:35]
	v_mfma_f32_16x16x32_bf16 v[20:23], v[182:185], v[234:237], v[20:23]
	v_mfma_f32_16x16x32_bf16 v[16:19], v[210:213], v[234:237], v[16:19]
	v_mfma_f32_16x16x32_bf16 v[4:7], v[182:185], v[242:245], v[4:7]
	v_mfma_f32_16x16x32_bf16 v[0:3], v[210:213], v[242:245], v[0:3]
	s_setprio 0
	s_barrier
	ds_read_b128 v[68:71], v254 offset:32768
	ds_read_b128 v[72:75], v254 offset:33792
	ds_read_b128 v[76:79], v254 offset:34816
	ds_read_b128 v[80:83], v254 offset:35840
	ds_read_b128 v[174:177], v254 offset:49152
	ds_read_b128 v[182:185], v254 offset:50176
	ds_read_b128 v[186:189], v254 offset:51200
	ds_read_b128 v[210:213], v254 offset:52224
	s_add_u32 s4, s4, 0x40000
	s_addc_u32 s5, s5, 0
	s_mov_b32 m0, s40
	ds_read_b128 v[214:217], v179 offset:32768
	ds_read_b128 v[218:221], v179 offset:33792
	ds_read_b128 v[222:225], v179 offset:34816
	ds_read_b128 v[226:229], v179 offset:35840
	ds_read_b128 v[230:233], v179 offset:36864
	ds_read_b128 v[234:237], v179 offset:37888
	ds_read_b128 v[238:241], v179 offset:38912
	ds_read_b128 v[242:245], v179 offset:39936
	global_load_lds_dwordx4 v168, s[4:5]
	s_mov_b32 m0, s41
	s_nop 0
	global_load_lds_dwordx4 v164, s[4:5]
	s_waitcnt vmcnt(8)
	s_waitcnt lgkmcnt(0)
	s_barrier
; #define PG8_STAGE(bufoff, gbase, voff) do { _Pragma("unroll") for (int _i = 0; _i < 2; ++_i) \
;         __builtin_amdgcn_global_load_lds((const unsigned*)((const char*)(gbase) + (voff)[_i]), (PG8_LAS unsigned*)(lds + (bufoff) + ldsw + _i * 8192), 16, 0, 0); } while (0)
; #define PG8_LDA(dst, b, h) do { _Pragma("unroll") for (int m = 0; m < 4; ++m) _Pragma("unroll") for (int k = 0; k < 2; ++k) dst[m][k] = *(const PG8_LAS bf16x8*)(lds + PG8_SA(b, h) + aoff + m * 2048 + k * 1024); } while (0)
; #define PG8_MMA(ai, bj, At, Bt) do { __builtin_amdgcn_s_setprio(1); _Pragma("unroll") for (int m = 0; m < 4; ++m) _Pragma("unroll") for (int n = 0; n < 2; ++n) _Pragma("unroll") for (int k = 0; k < 2; ++k) \
;         acc[ai][bj][m][n] = __builtin_amdgcn_mfma_f32_16x16x32_bf16(Bt[n][k], At[m][k], acc[ai][bj][m][n], 0, 0, 0); __builtin_amdgcn_s_setprio(0); } while (0)
; #define PG8_WAIT_V(n) asm volatile("s_waitcnt vmcnt(" #n ")" ::: "memory")
; #define PG8_WAIT_L(n) asm volatile("s_waitcnt lgkmcnt(" #n ")" ::: "memory")
; #define PG8_BAR __builtin_amdgcn_s_barrier()
; #define PG8_SCHED __builtin_amdgcn_sched_barrier(0)
; template <class Epi, class Sched, bool ALIGN_EPI = false, bool SP2 = false>
; __device__ __forceinline__ void gemm_phase(PG8_LAS unsigned char* lds, const Gemm g, const Sched& S, const Epi& E) {
;     ...
;             PG8_WAIT_V(8); PG8_WAIT_L(0); PG8_BAR; PG8_MMA(0, 0, At, B0); PG8_MMA(0, 1, At, B1); PG8_BAR; PG8_SCHED;
;             PG8_LDA(At, 1, 1); PG8_STAGE(PG8_SB(1, 0), b3, voffB); PG8_STAGE(PG8_SB(1, 1), b3 + hstep, voffB); PG8_STAGE(PG8_SA(1, 0), a3, voffA);
;             PG8_WAIT_V(8); PG8_WAIT_L(0); PG8_BAR; PG8_MMA(1, 0, At, B0); PG8_MMA(1, 1, At, B1); PG8_BAR; PG8_SCHED;
;     ...
;         if constexpr (ALIGN_EPI) { if (wr == 0) PG8_BAR; }
	s_setprio 1
	s_waitcnt lgkmcnt(0)
	v_mfma_f32_16x16x32_bf16 v[140:143], v[68:71], v[214:217], v[140:143]
	v_mfma_f32_16x16x32_bf16 v[136:139], v[76:79], v[214:217], v[136:139]
	v_mfma_f32_16x16x32_bf16 v[124:127], v[68:71], v[222:225], v[124:127]
	v_mfma_f32_16x16x32_bf16 v[120:123], v[76:79], v[222:225], v[120:123]
	v_mfma_f32_16x16x32_bf16 v[108:111], v[68:71], v[230:233], v[108:111]
	v_mfma_f32_16x16x32_bf16 v[104:107], v[76:79], v[230:233], v[104:107]
	v_mfma_f32_16x16x32_bf16 v[92:95], v[68:71], v[238:241], v[92:95]
	v_mfma_f32_16x16x32_bf16 v[88:91], v[76:79], v[238:241], v[88:91]
	v_mfma_f32_16x16x32_bf16 v[140:143], v[72:75], v[218:221], v[140:143]
	v_mfma_f32_16x16x32_bf16 v[136:139], v[80:83], v[218:221], v[136:139]
	v_mfma_f32_16x16x32_bf16 v[124:127], v[72:75], v[226:229], v[124:127]
	v_mfma_f32_16x16x32_bf16 v[120:123], v[80:83], v[226:229], v[120:123]
	v_mfma_f32_16x16x32_bf16 v[108:111], v[72:75], v[234:237], v[108:111]
	v_mfma_f32_16x16x32_bf16 v[104:107], v[80:83], v[234:237], v[104:107]
	v_mfma_f32_16x16x32_bf16 v[92:95], v[72:75], v[242:245], v[92:95]
	v_mfma_f32_16x16x32_bf16 v[88:91], v[80:83], v[242:245], v[88:91]
	s_setprio 0
	s_setprio 1
	v_mfma_f32_16x16x32_bf16 v[132:135], v[174:177], v[214:217], v[132:135]
	v_mfma_f32_16x16x32_bf16 v[128:131], v[186:189], v[214:217], v[128:131]
	v_mfma_f32_16x16x32_bf16 v[116:119], v[174:177], v[222:225], v[116:119]
	v_mfma_f32_16x16x32_bf16 v[112:115], v[186:189], v[222:225], v[112:115]
	v_mfma_f32_16x16x32_bf16 v[100:103], v[174:177], v[230:233], v[100:103]
	v_mfma_f32_16x16x32_bf16 v[96:99], v[186:189], v[230:233], v[96:99]
	v_mfma_f32_16x16x32_bf16 v[84:87], v[174:177], v[238:241], v[84:87]
	v_mfma_f32_16x16x32_bf16 v[64:67], v[186:189], v[238:241], v[64:67]
	v_mfma_f32_16x16x32_bf16 v[132:135], v[182:185], v[218:221], v[132:135]
	v_mfma_f32_16x16x32_bf16 v[128:131], v[210:213], v[218:221], v[128:131]
	v_mfma_f32_16x16x32_bf16 v[116:119], v[182:185], v[226:229], v[116:119]
	v_mfma_f32_16x16x32_bf16 v[112:115], v[210:213], v[226:229], v[112:115]
	v_mfma_f32_16x16x32_bf16 v[100:103], v[182:185], v[234:237], v[100:103]
	v_mfma_f32_16x16x32_bf16 v[96:99], v[210:213], v[234:237], v[96:99]
	v_mfma_f32_16x16x32_bf16 v[84:87], v[182:185], v[242:245], v[84:87]
	v_mfma_f32_16x16x32_bf16 v[64:67], v[210:213], v[242:245], v[64:67]
	s_setprio 0
	s_barrier
	s_mov_b32 m0, s45
	s_add_u32 s2, s2, 0x40080
	s_addc_u32 s3, s3, 0
	ds_read_b128 v[214:217], v179 offset:49152
	ds_read_b128 v[218:221], v179 offset:50176
	ds_read_b128 v[222:225], v179 offset:51200
	ds_read_b128 v[226:229], v179 offset:52224
	ds_read_b128 v[230:233], v179 offset:53248
	ds_read_b128 v[234:237], v179 offset:54272
	ds_read_b128 v[238:241], v179 offset:55296
	ds_read_b128 v[242:245], v179 offset:56320
	s_add_u32 s98, s2, 0xfffc0000
	s_addc_u32 s99, s3, -1
	global_load_lds_dwordx4 v166, s[98:99]
	s_mov_b32 m0, s46
	s_nop 0
	global_load_lds_dwordx4 v162, s[98:99]
	s_mov_b32 m0, s49
	s_nop 0
	global_load_lds_dwordx4 v166, s[2:3]
	s_mov_b32 m0, s50
	s_nop 0
	global_load_lds_dwordx4 v162, s[2:3]
	s_mov_b32 m0, s47
	s_nop 0
	s_add_u32 s100, s4, 0xfffc0080
	s_addc_u32 s101, s5, -1
	global_load_lds_dwordx4 v168, s[100:101]
	s_mov_b32 m0, s48
	s_nop 0
	global_load_lds_dwordx4 v164, s[100:101]
	s_waitcnt vmcnt(8)
	s_waitcnt lgkmcnt(0)
	s_barrier
	s_setprio 1
	s_waitcnt lgkmcnt(0)
	v_mfma_f32_16x16x32_bf16 v[60:63], v[68:71], v[214:217], v[60:63]
	v_mfma_f32_16x16x32_bf16 v[56:59], v[76:79], v[214:217], v[56:59]
	v_mfma_f32_16x16x32_bf16 v[44:47], v[68:71], v[222:225], v[44:47]
	v_mfma_f32_16x16x32_bf16 v[40:43], v[76:79], v[222:225], v[40:43]
	v_mfma_f32_16x16x32_bf16 v[28:31], v[68:71], v[230:233], v[28:31]
	v_mfma_f32_16x16x32_bf16 v[24:27], v[76:79], v[230:233], v[24:27]
	v_mfma_f32_16x16x32_bf16 v[12:15], v[68:71], v[238:241], v[12:15]
	v_mfma_f32_16x16x32_bf16 v[8:11], v[76:79], v[238:241], v[8:11]
	v_mfma_f32_16x16x32_bf16 v[60:63], v[72:75], v[218:221], v[60:63]
	v_mfma_f32_16x16x32_bf16 v[56:59], v[80:83], v[218:221], v[56:59]
	v_mfma_f32_16x16x32_bf16 v[44:47], v[72:75], v[226:229], v[44:47]
	v_mfma_f32_16x16x32_bf16 v[40:43], v[80:83], v[226:229], v[40:43]
	v_mfma_f32_16x16x32_bf16 v[28:31], v[72:75], v[234:237], v[28:31]
	v_mfma_f32_16x16x32_bf16 v[24:27], v[80:83], v[234:237], v[24:27]
	v_mfma_f32_16x16x32_bf16 v[12:15], v[72:75], v[242:245], v[12:15]
	v_mfma_f32_16x16x32_bf16 v[8:11], v[80:83], v[242:245], v[8:11]
	s_setprio 0
	s_setprio 1
	v_mfma_f32_16x16x32_bf16 v[52:55], v[174:177], v[214:217], v[52:55]
	v_mfma_f32_16x16x32_bf16 v[48:51], v[186:189], v[214:217], v[48:51]
	v_mfma_f32_16x16x32_bf16 v[36:39], v[174:177], v[222:225], v[36:39]
	v_mfma_f32_16x16x32_bf16 v[32:35], v[186:189], v[222:225], v[32:35]
	v_mfma_f32_16x16x32_bf16 v[20:23], v[174:177], v[230:233], v[20:23]
	v_mfma_f32_16x16x32_bf16 v[16:19], v[186:189], v[230:233], v[16:19]
	v_mfma_f32_16x16x32_bf16 v[4:7], v[174:177], v[238:241], v[4:7]
	v_mfma_f32_16x16x32_bf16 v[0:3], v[186:189], v[238:241], v[0:3]
	v_mfma_f32_16x16x32_bf16 v[52:55], v[182:185], v[218:221], v[52:55]
	v_mfma_f32_16x16x32_bf16 v[48:51], v[210:213], v[218:221], v[48:51]
	v_mfma_f32_16x16x32_bf16 v[36:39], v[182:185], v[226:229], v[36:39]
	v_mfma_f32_16x16x32_bf16 v[32:35], v[210:213], v[226:229], v[32:35]
	v_mfma_f32_16x16x32_bf16 v[20:23], v[182:185], v[234:237], v[20:23]
	v_mfma_f32_16x16x32_bf16 v[16:19], v[210:213], v[234:237], v[16:19]
	v_mfma_f32_16x16x32_bf16 v[4:7], v[182:185], v[242:245], v[4:7]
	v_mfma_f32_16x16x32_bf16 v[0:3], v[210:213], v[242:245], v[0:3]
	s_setprio 0
	s_barrier
	s_add_i32 s56, s56, 2
	s_add_u32 s0, s0, 0x100
	s_addc_u32 s1, s1, 0
	s_add_u32 s54, s54, 0x100
	s_addc_u32 s55, s55, 0
	s_cmp_gt_u32 s56, 13
	s_cbranch_scc0 .LBB0_327
	s_and_b64 vcc, exec, s[22:23]
	s_cbranch_vccz .LBB0_330
	s_barrier

; #define PG8_STAGE(bufoff, gbase, voff) do { _Pragma("unroll") for (int _i = 0; _i < 2; ++_i) \
;         __builtin_amdgcn_global_load_lds((const unsigned*)((const char*)(gbase) + (voff)[_i]), (PG8_LAS unsigned*)(lds + (bufoff) + ldsw + _i * 8192), 16, 0, 0); } while (0)
; #define PG8_LDA(dst, b, h) do { _Pragma("unroll") for (int m = 0; m < 4; ++m) _Pragma("unroll") for (int k = 0; k < 2; ++k) dst[m][k] = *(const PG8_LAS bf16x8*)(lds + PG8_SA(b, h) + aoff + m * 2048 + k * 1024); } while (0)
; #define PG8_LDB(dst, b, h) do { _Pragma("unroll") for (int n = 0; n < 2; ++n) _Pragma("unroll") for (int k = 0; k < 2; ++k) dst[n][k] = *(const PG8_LAS bf16x8*)(lds + PG8_SB(b, h) + boff + n * 2048 + k * 1024); } while (0)
; #define PG8_WAIT_V(n) asm volatile("s_waitcnt vmcnt(" #n ")" ::: "memory")
; #define PG8_WAIT_L(n) asm volatile("s_waitcnt lgkmcnt(" #n ")" ::: "memory")
; #define PG8_BAR __builtin_amdgcn_s_barrier()
; #define PG8_SCHED __builtin_amdgcn_sched_barrier(0)
; template <class Epi, class Sched, bool ALIGN_EPI = false, bool SP2 = false>
; __device__ __forceinline__ void gemm_phase(PG8_LAS unsigned char* lds, const Gemm g, const Sched& S, const Epi& E) {
;     ...
;         const char* nA = has_next ? (const char*)g.A + (size_t)nxt.pm * tstep : cA; const char* nB = has_next ? (const char*)g.Bt + (size_t)nxt.pn * tstep : cB;
;         for (int t = 0; t < nt; t += 2) {
;             const bool last = (t == nt - 2);
;             const char* a1 = cA + (size_t)(t + 1) * kstep;
;             const char* a2 = last ? nA : cA + (size_t)(t + 2) * kstep; const char* b2 = last ? nB : cB + (size_t)(t + 2) * kstep;
;             const char* a3 = a2 + kstep; const char* b3 = b2 + kstep;
;             if (last && has_next) S.a_ready(nxt);
;             if constexpr (SP2) {
;             PG8_LDB(B0, 0, 0); PG8_LDB(B1, 0, 1); PG8_SCHED; PG8_LDA(At, 0, 0); PG8_STAGE(PG8_SA(1, 1), a1 + hstep, voffA);
;             PG8_WAIT_V(8); PG8_WAIT_L(0); PG8_BAR; PG8_MMA(0, 0, At, B0); PG8_MMA(0, 1, At, B1); PG8_BAR; PG8_SCHED;
;             PG8_LDA(At, 0, 1); PG8_STAGE(PG8_SB(0, 0), b2, voffB); PG8_STAGE(PG8_SB(0, 1), b2 + hstep, voffB); PG8_STAGE(PG8_SA(0, 0), a2, voffA);
;             PG8_WAIT_V(8); PG8_WAIT_L(0); PG8_BAR; PG8_MMA(1, 0, At, B0); PG8_MMA(1, 1, At, B1); PG8_BAR; PG8_SCHED;
.LBB0_544:
	s_add_u32 s10, s2, 0x100
	v_mov_b32_e32 v0, 0
	s_addc_u32 s11, s3, 0
	s_mov_b32 s13, -2
	s_waitcnt lgkmcnt(0)
	v_add_u32_e32 v254, 0x10000, v182
.Ldn_peel:
	ds_read_b128 v[128:131], v254
	ds_read_b128 v[132:135], v254 offset:1024
	ds_read_b128 v[136:139], v254 offset:2048
	ds_read_b128 v[140:143], v254 offset:3072
	ds_read_b128 v[174:177], v254 offset:16384
	ds_read_b128 v[184:187], v254 offset:17408
	ds_read_b128 v[188:191], v254 offset:18432
	ds_read_b128 v[210:213], v254 offset:19456
	s_add_u32 s2, s0, 0x100
	s_addc_u32 s3, s1, 0
	s_cmp_eq_u32 s13, 40
	s_cselect_b32 s7, s27, s3
	s_cselect_b32 s6, s26, s2
	s_cselect_b32 s5, s37, s11
	s_cselect_b32 s4, s36, s10
	s_add_i32 m0, s29, 0xc000
	ds_read_b128 v[214:217], v181
	ds_read_b128 v[218:221], v181 offset:1024
	ds_read_b128 v[222:225], v181 offset:2048
	ds_read_b128 v[226:229], v181 offset:3072
	ds_read_b128 v[230:233], v181 offset:4096
	ds_read_b128 v[234:237], v181 offset:5120
	ds_read_b128 v[238:241], v181 offset:6144
	ds_read_b128 v[242:245], v181 offset:7168
	global_load_lds_dwordx4 v170, s[0:1]
	s_add_i32 m0, s29, 0xe000
	s_nop 0
	global_load_lds_dwordx4 v172, s[0:1]
	s_waitcnt vmcnt(8)
	s_waitcnt lgkmcnt(0)
	s_barrier
	s_setprio 1
	s_waitcnt lgkmcnt(0)
	v_mfma_f32_16x16x32_bf16 v[124:127], v[128:131], v[214:217], 0
	v_mfma_f32_16x16x32_bf16 v[120:123], v[136:139], v[214:217], 0
	v_mfma_f32_16x16x32_bf16 v[108:111], v[128:131], v[222:225], 0
	v_mfma_f32_16x16x32_bf16 v[104:107], v[136:139], v[222:225], 0
	v_mfma_f32_16x16x32_bf16 v[92:95], v[128:131], v[230:233], 0
	v_mfma_f32_16x16x32_bf16 v[88:91], v[136:139], v[230:233], 0
	v_mfma_f32_16x16x32_bf16 v[76:79], v[128:131], v[238:241], 0
	v_mfma_f32_16x16x32_bf16 v[72:75], v[136:139], v[238:241], 0
	v_mfma_f32_16x16x32_bf16 v[124:127], v[132:135], v[218:221], v[124:127]
	v_mfma_f32_16x16x32_bf16 v[120:123], v[140:143], v[218:221], v[120:123]
	v_mfma_f32_16x16x32_bf16 v[108:111], v[132:135], v[226:229], v[108:111]
	v_mfma_f32_16x16x32_bf16 v[104:107], v[140:143], v[226:229], v[104:107]
	v_mfma_f32_16x16x32_bf16 v[92:95], v[132:135], v[234:237], v[92:95]
	v_mfma_f32_16x16x32_bf16 v[88:91], v[140:143], v[234:237], v[88:91]
	v_mfma_f32_16x16x32_bf16 v[76:79], v[132:135], v[242:245], v[76:79]
	v_mfma_f32_16x16x32_bf16 v[72:75], v[140:143], v[242:245], v[72:75]
	s_setprio 0
	s_setprio 1
	v_mfma_f32_16x16x32_bf16 v[116:119], v[174:177], v[214:217], 0
	v_mfma_f32_16x16x32_bf16 v[112:115], v[188:191], v[214:217], 0
	v_mfma_f32_16x16x32_bf16 v[100:103], v[174:177], v[222:225], 0
	v_mfma_f32_16x16x32_bf16 v[96:99], v[188:191], v[222:225], 0
	v_mfma_f32_16x16x32_bf16 v[84:87], v[174:177], v[230:233], 0
	v_mfma_f32_16x16x32_bf16 v[80:83], v[188:191], v[230:233], 0
	v_mfma_f32_16x16x32_bf16 v[68:71], v[174:177], v[238:241], 0
	v_mfma_f32_16x16x32_bf16 v[64:67], v[188:191], v[238:241], 0
	v_mfma_f32_16x16x32_bf16 v[116:119], v[184:187], v[218:221], v[116:119]
	v_mfma_f32_16x16x32_bf16 v[112:115], v[210:213], v[218:221], v[112:115]
	v_mfma_f32_16x16x32_bf16 v[100:103], v[184:187], v[226:229], v[100:103]
	v_mfma_f32_16x16x32_bf16 v[96:99], v[210:213], v[226:229], v[96:99]
	v_mfma_f32_16x16x32_bf16 v[84:87], v[184:187], v[234:237], v[84:87]
	v_mfma_f32_16x16x32_bf16 v[80:83], v[210:213], v[234:237], v[80:83]
	v_mfma_f32_16x16x32_bf16 v[68:71], v[184:187], v[242:245], v[68:71]
	v_mfma_f32_16x16x32_bf16 v[64:67], v[210:213], v[242:245], v[64:67]
	s_setprio 0
	s_barrier
	s_mov_b32 m0, s35
	s_add_u32 s0, s4, 0xb0000
	s_addc_u32 s1, s5, 0
	ds_read_b128 v[214:217], v181 offset:16384
	ds_read_b128 v[218:221], v181 offset:17408
	ds_read_b128 v[222:225], v181 offset:18432
	ds_read_b128 v[226:229], v181 offset:19456
	ds_read_b128 v[230:233], v181 offset:20480
	ds_read_b128 v[234:237], v181 offset:21504
	ds_read_b128 v[238:241], v181 offset:22528
	ds_read_b128 v[242:245], v181 offset:23552
	global_load_lds_dwordx4 v166, s[4:5]
	s_mov_b32 m0, s38
	s_nop 0
	global_load_lds_dwordx4 v162, s[4:5]
	s_mov_b32 m0, s39
	s_nop 0
	global_load_lds_dwordx4 v166, s[0:1]
	s_mov_b32 m0, s40
	s_nop 0
	global_load_lds_dwordx4 v162, s[0:1]
	s_mov_b32 m0, s29
	s_nop 0
	global_load_lds_dwordx4 v168, s[6:7]
	s_mov_b32 m0, s41
	s_nop 0
	global_load_lds_dwordx4 v164, s[6:7]
	s_waitcnt vmcnt(8)
	s_waitcnt lgkmcnt(0)
	s_barrier
	s_setprio 1
	s_waitcnt lgkmcnt(0)
	v_mfma_f32_16x16x32_bf16 v[60:63], v[128:131], v[214:217], 0
	v_mfma_f32_16x16x32_bf16 v[56:59], v[136:139], v[214:217], 0
	v_mfma_f32_16x16x32_bf16 v[44:47], v[128:131], v[222:225], 0
	v_mfma_f32_16x16x32_bf16 v[40:43], v[136:139], v[222:225], 0
	v_mfma_f32_16x16x32_bf16 v[28:31], v[128:131], v[230:233], 0
	v_mfma_f32_16x16x32_bf16 v[24:27], v[136:139], v[230:233], 0
	v_mfma_f32_16x16x32_bf16 v[12:15], v[128:131], v[238:241], 0
	v_mfma_f32_16x16x32_bf16 v[8:11], v[136:139], v[238:241], 0
	v_mfma_f32_16x16x32_bf16 v[60:63], v[132:135], v[218:221], v[60:63]
	v_mfma_f32_16x16x32_bf16 v[56:59], v[140:143], v[218:221], v[56:59]
	v_mfma_f32_16x16x32_bf16 v[44:47], v[132:135], v[226:229], v[44:47]
	v_mfma_f32_16x16x32_bf16 v[40:43], v[140:143], v[226:229], v[40:43]
	v_mfma_f32_16x16x32_bf16 v[28:31], v[132:135], v[234:237], v[28:31]
	v_mfma_f32_16x16x32_bf16 v[24:27], v[140:143], v[234:237], v[24:27]
	v_mfma_f32_16x16x32_bf16 v[12:15], v[132:135], v[242:245], v[12:15]
	v_mfma_f32_16x16x32_bf16 v[8:11], v[140:143], v[242:245], v[8:11]
	s_setprio 0
	s_setprio 1
	v_mfma_f32_16x16x32_bf16 v[52:55], v[174:177], v[214:217], 0
	v_mfma_f32_16x16x32_bf16 v[48:51], v[188:191], v[214:217], 0
	v_mfma_f32_16x16x32_bf16 v[36:39], v[174:177], v[222:225], 0
	v_mfma_f32_16x16x32_bf16 v[32:35], v[188:191], v[222:225], 0
	v_mfma_f32_16x16x32_bf16 v[20:23], v[174:177], v[230:233], 0
	v_mfma_f32_16x16x32_bf16 v[16:19], v[188:191], v[230:233], 0
	v_mfma_f32_16x16x32_bf16 v[4:7], v[174:177], v[238:241], 0
	v_mfma_f32_16x16x32_bf16 v[0:3], v[188:191], v[238:241], 0
	v_mfma_f32_16x16x32_bf16 v[52:55], v[184:187], v[218:221], v[52:55]
	v_mfma_f32_16x16x32_bf16 v[48:51], v[210:213], v[218:221], v[48:51]
	v_mfma_f32_16x16x32_bf16 v[36:39], v[184:187], v[226:229], v[36:39]
	v_mfma_f32_16x16x32_bf16 v[32:35], v[210:213], v[226:229], v[32:35]
	v_mfma_f32_16x16x32_bf16 v[20:23], v[184:187], v[234:237], v[20:23]
	v_mfma_f32_16x16x32_bf16 v[16:19], v[210:213], v[234:237], v[16:19]
	v_mfma_f32_16x16x32_bf16 v[4:7], v[184:187], v[242:245], v[4:7]
	v_mfma_f32_16x16x32_bf16 v[0:3], v[210:213], v[242:245], v[0:3]
	s_setprio 0
	s_barrier
; #define PG8_STAGE(bufoff, gbase, voff) do { _Pragma("unroll") for (int _i = 0; _i < 2; ++_i) \
;         __builtin_amdgcn_global_load_lds((const unsigned*)((const char*)(gbase) + (voff)[_i]), (PG8_LAS unsigned*)(lds + (bufoff) + ldsw + _i * 8192), 16, 0, 0); } while (0)
; #define PG8_LDA(dst, b, h) do { _Pragma("unroll") for (int m = 0; m < 4; ++m) _Pragma("unroll") for (int k = 0; k < 2; ++k) dst[m][k] = *(const PG8_LAS bf16x8*)(lds + PG8_SA(b, h) + aoff + m * 2048 + k * 1024); } while (0)
; #define PG8_LDB(dst, b, h) do { _Pragma("unroll") for (int n = 0; n < 2; ++n) _Pragma("unroll") for (int k = 0; k < 2; ++k) dst[n][k] = *(const PG8_LAS bf16x8*)(lds + PG8_SB(b, h) + boff + n * 2048 + k * 1024); } while (0)
; #define PG8_MMA(ai, bj, At, Bt) do { __builtin_amdgcn_s_setprio(1); _Pragma("unroll") for (int m = 0; m < 4; ++m) _Pragma("unroll") for (int n = 0; n < 2; ++n) _Pragma("unroll") for (int k = 0; k < 2; ++k) \
;         acc[ai][bj][m][n] = __builtin_amdgcn_mfma_f32_16x16x32_bf16(Bt[n][k], At[m][k], acc[ai][bj][m][n], 0, 0, 0); __builtin_amdgcn_s_setprio(0); } while (0)
; #define PG8_WAIT_V(n) asm volatile("s_waitcnt vmcnt(" #n ")" ::: "memory")
; #define PG8_WAIT_L(n) asm volatile("s_waitcnt lgkmcnt(" #n ")" ::: "memory")
; #define PG8_BAR __builtin_amdgcn_s_barrier()
; #define PG8_SCHED __builtin_amdgcn_sched_barrier(0)
; template <class Epi, class Sched, bool ALIGN_EPI = false, bool SP2 = false>
; __device__ __forceinline__ void gemm_phase(PG8_LAS unsigned char* lds, const Gemm g, const Sched& S, const Epi& E) {
;     ...
;             PG8_LDB(B0, 1, 0); PG8_LDB(B1, 1, 1); PG8_SCHED; PG8_LDA(At, 1, 0); PG8_STAGE(PG8_SA(0, 1), a2 + hstep, voffA);
;             PG8_WAIT_V(8); PG8_WAIT_L(0); PG8_BAR; PG8_MMA(0, 0, At, B0); PG8_MMA(0, 1, At, B1); PG8_BAR; PG8_SCHED;
;             PG8_LDA(At, 1, 1); PG8_STAGE(PG8_SB(1, 0), b3, voffB); PG8_STAGE(PG8_SB(1, 1), b3 + hstep, voffB); PG8_STAGE(PG8_SA(1, 0), a3, voffA);
;             PG8_WAIT_V(8); PG8_WAIT_L(0); PG8_BAR; PG8_MMA(1, 0, At, B0); PG8_MMA(1, 1, At, B1); PG8_BAR; PG8_SCHED;
	ds_read_b128 v[128:131], v254 offset:32768
	ds_read_b128 v[132:135], v254 offset:33792
	ds_read_b128 v[136:139], v254 offset:34816
	ds_read_b128 v[140:143], v254 offset:35840
	ds_read_b128 v[174:177], v254 offset:49152
	ds_read_b128 v[184:187], v254 offset:50176
	ds_read_b128 v[188:191], v254 offset:51200
	ds_read_b128 v[210:213], v254 offset:52224
	s_add_u32 s0, s6, 0xb0000
	s_addc_u32 s1, s7, 0
	s_mov_b32 m0, s42
	ds_read_b128 v[214:217], v181 offset:32768
	ds_read_b128 v[218:221], v181 offset:33792
	ds_read_b128 v[222:225], v181 offset:34816
	ds_read_b128 v[226:229], v181 offset:35840
	ds_read_b128 v[230:233], v181 offset:36864
	ds_read_b128 v[234:237], v181 offset:37888
	ds_read_b128 v[238:241], v181 offset:38912
	ds_read_b128 v[242:245], v181 offset:39936
	global_load_lds_dwordx4 v168, s[0:1]
	s_mov_b32 m0, s43
	s_nop 0
	global_load_lds_dwordx4 v164, s[0:1]
	s_waitcnt vmcnt(8)
	s_waitcnt lgkmcnt(0)
	s_barrier
	s_setprio 1
	s_waitcnt lgkmcnt(0)
	v_mfma_f32_16x16x32_bf16 v[124:127], v[128:131], v[214:217], v[124:127]
	v_mfma_f32_16x16x32_bf16 v[120:123], v[136:139], v[214:217], v[120:123]
	v_mfma_f32_16x16x32_bf16 v[108:111], v[128:131], v[222:225], v[108:111]
	v_mfma_f32_16x16x32_bf16 v[104:107], v[136:139], v[222:225], v[104:107]
	v_mfma_f32_16x16x32_bf16 v[92:95], v[128:131], v[230:233], v[92:95]
	v_mfma_f32_16x16x32_bf16 v[88:91], v[136:139], v[230:233], v[88:91]
	v_mfma_f32_16x16x32_bf16 v[76:79], v[128:131], v[238:241], v[76:79]
	v_mfma_f32_16x16x32_bf16 v[72:75], v[136:139], v[238:241], v[72:75]
	v_mfma_f32_16x16x32_bf16 v[124:127], v[132:135], v[218:221], v[124:127]
	v_mfma_f32_16x16x32_bf16 v[120:123], v[140:143], v[218:221], v[120:123]
	v_mfma_f32_16x16x32_bf16 v[108:111], v[132:135], v[226:229], v[108:111]
	v_mfma_f32_16x16x32_bf16 v[104:107], v[140:143], v[226:229], v[104:107]
	v_mfma_f32_16x16x32_bf16 v[92:95], v[132:135], v[234:237], v[92:95]
	v_mfma_f32_16x16x32_bf16 v[88:91], v[140:143], v[234:237], v[88:91]
	v_mfma_f32_16x16x32_bf16 v[76:79], v[132:135], v[242:245], v[76:79]
	v_mfma_f32_16x16x32_bf16 v[72:75], v[140:143], v[242:245], v[72:75]
	s_setprio 0
	s_setprio 1
	v_mfma_f32_16x16x32_bf16 v[116:119], v[174:177], v[214:217], v[116:119]
	v_mfma_f32_16x16x32_bf16 v[112:115], v[188:191], v[214:217], v[112:115]
	v_mfma_f32_16x16x32_bf16 v[100:103], v[174:177], v[222:225], v[100:103]
	v_mfma_f32_16x16x32_bf16 v[96:99], v[188:191], v[222:225], v[96:99]
	v_mfma_f32_16x16x32_bf16 v[84:87], v[174:177], v[230:233], v[84:87]
	v_mfma_f32_16x16x32_bf16 v[80:83], v[188:191], v[230:233], v[80:83]
	v_mfma_f32_16x16x32_bf16 v[68:71], v[174:177], v[238:241], v[68:71]
	v_mfma_f32_16x16x32_bf16 v[64:67], v[188:191], v[238:241], v[64:67]
	v_mfma_f32_16x16x32_bf16 v[116:119], v[184:187], v[218:221], v[116:119]
	v_mfma_f32_16x16x32_bf16 v[112:115], v[210:213], v[218:221], v[112:115]
	v_mfma_f32_16x16x32_bf16 v[100:103], v[184:187], v[226:229], v[100:103]
	v_mfma_f32_16x16x32_bf16 v[96:99], v[210:213], v[226:229], v[96:99]
	v_mfma_f32_16x16x32_bf16 v[84:87], v[184:187], v[234:237], v[84:87]
	v_mfma_f32_16x16x32_bf16 v[80:83], v[210:213], v[234:237], v[80:83]
	v_mfma_f32_16x16x32_bf16 v[68:71], v[184:187], v[242:245], v[68:71]
	v_mfma_f32_16x16x32_bf16 v[64:67], v[210:213], v[242:245], v[64:67]
	s_setprio 0
	s_barrier
	s_mov_b32 m0, s47
	s_add_u32 s0, s4, 0xb0080
	s_addc_u32 s1, s5, 0
	ds_read_b128 v[214:217], v181 offset:49152
	ds_read_b128 v[218:221], v181 offset:50176
	ds_read_b128 v[222:225], v181 offset:51200
	ds_read_b128 v[226:229], v181 offset:52224
	ds_read_b128 v[230:233], v181 offset:53248
	ds_read_b128 v[234:237], v181 offset:54272
	ds_read_b128 v[238:241], v181 offset:55296
	ds_read_b128 v[242:245], v181 offset:56320
	s_add_u32 s98, s4, 0x80
	s_addc_u32 s99, s5, 0
	global_load_lds_dwordx4 v166, s[98:99]
	s_mov_b32 m0, s48
	s_nop 0
	global_load_lds_dwordx4 v162, s[98:99]
	s_mov_b32 m0, s51
	s_nop 0
	global_load_lds_dwordx4 v166, s[0:1]
	s_mov_b32 m0, s52
	s_nop 0
	global_load_lds_dwordx4 v162, s[0:1]
	s_mov_b32 m0, s49
	s_nop 0
	s_add_u32 s100, s6, 0x80
	s_addc_u32 s101, s7, 0
	global_load_lds_dwordx4 v168, s[100:101]
	s_mov_b32 m0, s50
	s_nop 0
	global_load_lds_dwordx4 v164, s[100:101]
	s_waitcnt vmcnt(8)
	s_waitcnt lgkmcnt(0)
	s_barrier
	s_setprio 1
	s_waitcnt lgkmcnt(0)
	v_mfma_f32_16x16x32_bf16 v[60:63], v[128:131], v[214:217], v[60:63]
	v_mfma_f32_16x16x32_bf16 v[56:59], v[136:139], v[214:217], v[56:59]
	v_mfma_f32_16x16x32_bf16 v[44:47], v[128:131], v[222:225], v[44:47]
	v_mfma_f32_16x16x32_bf16 v[40:43], v[136:139], v[222:225], v[40:43]
	v_mfma_f32_16x16x32_bf16 v[28:31], v[128:131], v[230:233], v[28:31]
	v_mfma_f32_16x16x32_bf16 v[24:27], v[136:139], v[230:233], v[24:27]
	v_mfma_f32_16x16x32_bf16 v[12:15], v[128:131], v[238:241], v[12:15]
	v_mfma_f32_16x16x32_bf16 v[8:11], v[136:139], v[238:241], v[8:11]
	v_mfma_f32_16x16x32_bf16 v[60:63], v[132:135], v[218:221], v[60:63]
	v_mfma_f32_16x16x32_bf16 v[56:59], v[140:143], v[218:221], v[56:59]
	v_mfma_f32_16x16x32_bf16 v[44:47], v[132:135], v[226:229], v[44:47]
	v_mfma_f32_16x16x32_bf16 v[40:43], v[140:143], v[226:229], v[40:43]
	v_mfma_f32_16x16x32_bf16 v[28:31], v[132:135], v[234:237], v[28:31]
	v_mfma_f32_16x16x32_bf16 v[24:27], v[140:143], v[234:237], v[24:27]
	v_mfma_f32_16x16x32_bf16 v[12:15], v[132:135], v[242:245], v[12:15]
	v_mfma_f32_16x16x32_bf16 v[8:11], v[140:143], v[242:245], v[8:11]
	s_setprio 0
	s_setprio 1
	v_mfma_f32_16x16x32_bf16 v[52:55], v[174:177], v[214:217], v[52:55]
	v_mfma_f32_16x16x32_bf16 v[48:51], v[188:191], v[214:217], v[48:51]
	v_mfma_f32_16x16x32_bf16 v[36:39], v[174:177], v[222:225], v[36:39]
	v_mfma_f32_16x16x32_bf16 v[32:35], v[188:191], v[222:225], v[32:35]
	v_mfma_f32_16x16x32_bf16 v[20:23], v[174:177], v[230:233], v[20:23]
	v_mfma_f32_16x16x32_bf16 v[16:19], v[188:191], v[230:233], v[16:19]
	v_mfma_f32_16x16x32_bf16 v[4:7], v[174:177], v[238:241], v[4:7]
	v_mfma_f32_16x16x32_bf16 v[0:3], v[188:191], v[238:241], v[0:3]
	v_mfma_f32_16x16x32_bf16 v[52:55], v[184:187], v[218:221], v[52:55]
	v_mfma_f32_16x16x32_bf16 v[48:51], v[210:213], v[218:221], v[48:51]
	v_mfma_f32_16x16x32_bf16 v[36:39], v[184:187], v[226:229], v[36:39]
	v_mfma_f32_16x16x32_bf16 v[32:35], v[210:213], v[226:229], v[32:35]
	v_mfma_f32_16x16x32_bf16 v[20:23], v[184:187], v[234:237], v[20:23]
	v_mfma_f32_16x16x32_bf16 v[16:19], v[210:213], v[234:237], v[16:19]
	v_mfma_f32_16x16x32_bf16 v[4:7], v[184:187], v[242:245], v[4:7]
	v_mfma_f32_16x16x32_bf16 v[0:3], v[210:213], v[242:245], v[0:3]
	s_setprio 0
	s_barrier
	s_add_i32 s13, s13, 2
	s_add_u32 s10, s10, 0x100
	s_addc_u32 s11, s11, 0
	s_cmp_gt_u32 s13, 41
	s_mov_b64 s[0:1], s[2:3]
; #define PG8_STAGE(bufoff, gbase, voff) do { _Pragma("unroll") for (int _i = 0; _i < 2; ++_i) \
;         __builtin_amdgcn_global_load_lds((const unsigned*)((const char*)(gbase) + (voff)[_i]), (PG8_LAS unsigned*)(lds + (bufoff) + ldsw + _i * 8192), 16, 0, 0); } while (0)
; #define PG8_LDA(dst, b, h) do { _Pragma("unroll") for (int m = 0; m < 4; ++m) _Pragma("unroll") for (int k = 0; k < 2; ++k) dst[m][k] = *(const PG8_LAS bf16x8*)(lds + PG8_SA(b, h) + aoff + m * 2048 + k * 1024); } while (0)
; #define PG8_LDB(dst, b, h) do { _Pragma("unroll") for (int n = 0; n < 2; ++n) _Pragma("unroll") for (int k = 0; k < 2; ++k) dst[n][k] = *(const PG8_LAS bf16x8*)(lds + PG8_SB(b, h) + boff + n * 2048 + k * 1024); } while (0)
; #define PG8_MMA(ai, bj, At, Bt) do { __builtin_amdgcn_s_setprio(1); _Pragma("unroll") for (int m = 0; m < 4; ++m) _Pragma("unroll") for (int n = 0; n < 2; ++n) _Pragma("unroll") for (int k = 0; k < 2; ++k) \
;         acc[ai][bj][m][n] = __builtin_amdgcn_mfma_f32_16x16x32_bf16(Bt[n][k], At[m][k], acc[ai][bj][m][n], 0, 0, 0); __builtin_amdgcn_s_setprio(0); } while (0)
; #define PG8_WAIT_V(n) asm volatile("s_waitcnt vmcnt(" #n ")" ::: "memory")
; #define PG8_WAIT_L(n) asm volatile("s_waitcnt lgkmcnt(" #n ")" ::: "memory")
; #define PG8_BAR __builtin_amdgcn_s_barrier()
; #define PG8_SCHED __builtin_amdgcn_sched_barrier(0)
; template <class Epi, class Sched, bool ALIGN_EPI = false, bool SP2 = false>
; __device__ __forceinline__ void gemm_phase(PG8_LAS unsigned char* lds, const Gemm g, const Sched& S, const Epi& E) {
;     ...
;             PG8_LDB(B0, 0, 0); PG8_LDB(B1, 0, 1); PG8_SCHED; PG8_LDA(At, 0, 0); PG8_STAGE(PG8_SA(1, 1), a1 + hstep, voffA);
;             PG8_WAIT_V(8); PG8_WAIT_L(0); PG8_BAR; PG8_MMA(0, 0, At, B0); PG8_MMA(0, 1, At, B1); PG8_BAR; PG8_SCHED;
;             PG8_LDA(At, 0, 1); PG8_STAGE(PG8_SB(0, 0), b2, voffB); PG8_STAGE(PG8_SB(0, 1), b2 + hstep, voffB); PG8_STAGE(PG8_SA(0, 0), a2, voffA);
;             PG8_WAIT_V(8); PG8_WAIT_L(0); PG8_BAR; PG8_MMA(1, 0, At, B0); PG8_MMA(1, 1, At, B1); PG8_BAR; PG8_SCHED;
.LBB0_545:
	ds_read_b128 v[128:131], v254
	ds_read_b128 v[132:135], v254 offset:1024
	ds_read_b128 v[136:139], v254 offset:2048
	ds_read_b128 v[140:143], v254 offset:3072
	ds_read_b128 v[174:177], v254 offset:16384
	ds_read_b128 v[184:187], v254 offset:17408
	ds_read_b128 v[188:191], v254 offset:18432
	ds_read_b128 v[210:213], v254 offset:19456
	s_add_u32 s2, s0, 0x100
	s_addc_u32 s3, s1, 0
	s_cmp_eq_u32 s13, 40
	s_cselect_b32 s7, s27, s3
	s_cselect_b32 s6, s26, s2
	s_cselect_b32 s5, s37, s11
	s_cselect_b32 s4, s36, s10
	s_add_i32 m0, s29, 0xc000
	ds_read_b128 v[214:217], v181
	ds_read_b128 v[218:221], v181 offset:1024
	ds_read_b128 v[222:225], v181 offset:2048
	ds_read_b128 v[226:229], v181 offset:3072
	ds_read_b128 v[230:233], v181 offset:4096
	ds_read_b128 v[234:237], v181 offset:5120
	ds_read_b128 v[238:241], v181 offset:6144
	ds_read_b128 v[242:245], v181 offset:7168
	global_load_lds_dwordx4 v170, s[0:1]
	s_add_i32 m0, s29, 0xe000
	s_nop 0
	global_load_lds_dwordx4 v172, s[0:1]
	s_waitcnt vmcnt(8)
	s_waitcnt lgkmcnt(0)
	s_barrier
	s_setprio 1
	s_waitcnt lgkmcnt(0)
	v_mfma_f32_16x16x32_bf16 v[124:127], v[128:131], v[214:217], v[124:127]
	v_mfma_f32_16x16x32_bf16 v[120:123], v[136:139], v[214:217], v[120:123]
	v_mfma_f32_16x16x32_bf16 v[108:111], v[128:131], v[222:225], v[108:111]
	v_mfma_f32_16x16x32_bf16 v[104:107], v[136:139], v[222:225], v[104:107]
	v_mfma_f32_16x16x32_bf16 v[92:95], v[128:131], v[230:233], v[92:95]
	v_mfma_f32_16x16x32_bf16 v[88:91], v[136:139], v[230:233], v[88:91]
	v_mfma_f32_16x16x32_bf16 v[76:79], v[128:131], v[238:241], v[76:79]
	v_mfma_f32_16x16x32_bf16 v[72:75], v[136:139], v[238:241], v[72:75]
	v_mfma_f32_16x16x32_bf16 v[124:127], v[132:135], v[218:221], v[124:127]
	v_mfma_f32_16x16x32_bf16 v[120:123], v[140:143], v[218:221], v[120:123]
	v_mfma_f32_16x16x32_bf16 v[108:111], v[132:135], v[226:229], v[108:111]
	v_mfma_f32_16x16x32_bf16 v[104:107], v[140:143], v[226:229], v[104:107]
	v_mfma_f32_16x16x32_bf16 v[92:95], v[132:135], v[234:237], v[92:95]
	v_mfma_f32_16x16x32_bf16 v[88:91], v[140:143], v[234:237], v[88:91]
	v_mfma_f32_16x16x32_bf16 v[76:79], v[132:135], v[242:245], v[76:79]
	v_mfma_f32_16x16x32_bf16 v[72:75], v[140:143], v[242:245], v[72:75]
	s_setprio 0
	s_setprio 1
	v_mfma_f32_16x16x32_bf16 v[116:119], v[174:177], v[214:217], v[116:119]
	v_mfma_f32_16x16x32_bf16 v[112:115], v[188:191], v[214:217], v[112:115]
	v_mfma_f32_16x16x32_bf16 v[100:103], v[174:177], v[222:225], v[100:103]
	v_mfma_f32_16x16x32_bf16 v[96:99], v[188:191], v[222:225], v[96:99]
	v_mfma_f32_16x16x32_bf16 v[84:87], v[174:177], v[230:233], v[84:87]
	v_mfma_f32_16x16x32_bf16 v[80:83], v[188:191], v[230:233], v[80:83]
	v_mfma_f32_16x16x32_bf16 v[68:71], v[174:177], v[238:241], v[68:71]
	v_mfma_f32_16x16x32_bf16 v[64:67], v[188:191], v[238:241], v[64:67]
	v_mfma_f32_16x16x32_bf16 v[116:119], v[184:187], v[218:221], v[116:119]
	v_mfma_f32_16x16x32_bf16 v[112:115], v[210:213], v[218:221], v[112:115]
	v_mfma_f32_16x16x32_bf16 v[100:103], v[184:187], v[226:229], v[100:103]
	v_mfma_f32_16x16x32_bf16 v[96:99], v[210:213], v[226:229], v[96:99]
	v_mfma_f32_16x16x32_bf16 v[84:87], v[184:187], v[234:237], v[84:87]
	v_mfma_f32_16x16x32_bf16 v[80:83], v[210:213], v[234:237], v[80:83]
	v_mfma_f32_16x16x32_bf16 v[68:71], v[184:187], v[242:245], v[68:71]
	v_mfma_f32_16x16x32_bf16 v[64:67], v[210:213], v[242:245], v[64:67]
	s_setprio 0
	s_barrier
	s_mov_b32 m0, s35
	s_add_u32 s0, s4, 0xb0000
	s_addc_u32 s1, s5, 0
	ds_read_b128 v[214:217], v181 offset:16384
	ds_read_b128 v[218:221], v181 offset:17408
	ds_read_b128 v[222:225], v181 offset:18432
	ds_read_b128 v[226:229], v181 offset:19456
	ds_read_b128 v[230:233], v181 offset:20480
	ds_read_b128 v[234:237], v181 offset:21504
	ds_read_b128 v[238:241], v181 offset:22528
	ds_read_b128 v[242:245], v181 offset:23552
	global_load_lds_dwordx4 v166, s[4:5]
	s_mov_b32 m0, s38
	s_nop 0
	global_load_lds_dwordx4 v162, s[4:5]
	s_mov_b32 m0, s39
	s_nop 0
	global_load_lds_dwordx4 v166, s[0:1]
	s_mov_b32 m0, s40
	s_nop 0
	global_load_lds_dwordx4 v162, s[0:1]
	s_mov_b32 m0, s29
	s_nop 0
	global_load_lds_dwordx4 v168, s[6:7]
	s_mov_b32 m0, s41
	s_nop 0
	global_load_lds_dwordx4 v164, s[6:7]
	s_waitcnt vmcnt(8)
	s_waitcnt lgkmcnt(0)
	s_barrier
	s_setprio 1
	s_waitcnt lgkmcnt(0)
	v_mfma_f32_16x16x32_bf16 v[60:63], v[128:131], v[214:217], v[60:63]
	v_mfma_f32_16x16x32_bf16 v[56:59], v[136:139], v[214:217], v[56:59]
	v_mfma_f32_16x16x32_bf16 v[44:47], v[128:131], v[222:225], v[44:47]
	v_mfma_f32_16x16x32_bf16 v[40:43], v[136:139], v[222:225], v[40:43]
	v_mfma_f32_16x16x32_bf16 v[28:31], v[128:131], v[230:233], v[28:31]
	v_mfma_f32_16x16x32_bf16 v[24:27], v[136:139], v[230:233], v[24:27]
	v_mfma_f32_16x16x32_bf16 v[12:15], v[128:131], v[238:241], v[12:15]
	v_mfma_f32_16x16x32_bf16 v[8:11], v[136:139], v[238:241], v[8:11]
	v_mfma_f32_16x16x32_bf16 v[60:63], v[132:135], v[218:221], v[60:63]
	v_mfma_f32_16x16x32_bf16 v[56:59], v[140:143], v[218:221], v[56:59]
	v_mfma_f32_16x16x32_bf16 v[44:47], v[132:135], v[226:229], v[44:47]
	v_mfma_f32_16x16x32_bf16 v[40:43], v[140:143], v[226:229], v[40:43]
	v_mfma_f32_16x16x32_bf16 v[28:31], v[132:135], v[234:237], v[28:31]
	v_mfma_f32_16x16x32_bf16 v[24:27], v[140:143], v[234:237], v[24:27]
	v_mfma_f32_16x16x32_bf16 v[12:15], v[132:135], v[242:245], v[12:15]
	v_mfma_f32_16x16x32_bf16 v[8:11], v[140:143], v[242:245], v[8:11]
	s_setprio 0
	s_setprio 1
	v_mfma_f32_16x16x32_bf16 v[52:55], v[174:177], v[214:217], v[52:55]
	v_mfma_f32_16x16x32_bf16 v[48:51], v[188:191], v[214:217], v[48:51]
	v_mfma_f32_16x16x32_bf16 v[36:39], v[174:177], v[222:225], v[36:39]
	v_mfma_f32_16x16x32_bf16 v[32:35], v[188:191], v[222:225], v[32:35]
	v_mfma_f32_16x16x32_bf16 v[20:23], v[174:177], v[230:233], v[20:23]
	v_mfma_f32_16x16x32_bf16 v[16:19], v[188:191], v[230:233], v[16:19]
	v_mfma_f32_16x16x32_bf16 v[4:7], v[174:177], v[238:241], v[4:7]
	v_mfma_f32_16x16x32_bf16 v[0:3], v[188:191], v[238:241], v[0:3]
	v_mfma_f32_16x16x32_bf16 v[52:55], v[184:187], v[218:221], v[52:55]
	v_mfma_f32_16x16x32_bf16 v[48:51], v[210:213], v[218:221], v[48:51]
	v_mfma_f32_16x16x32_bf16 v[36:39], v[184:187], v[226:229], v[36:39]
	v_mfma_f32_16x16x32_bf16 v[32:35], v[210:213], v[226:229], v[32:35]
	v_mfma_f32_16x16x32_bf16 v[20:23], v[184:187], v[234:237], v[20:23]
	v_mfma_f32_16x16x32_bf16 v[16:19], v[210:213], v[234:237], v[16:19]
	v_mfma_f32_16x16x32_bf16 v[4:7], v[184:187], v[242:245], v[4:7]
	v_mfma_f32_16x16x32_bf16 v[0:3], v[210:213], v[242:245], v[0:3]
	s_setprio 0
	s_barrier
; #define PG8_STAGE(bufoff, gbase, voff) do { _Pragma("unroll") for (int _i = 0; _i < 2; ++_i) \
;         __builtin_amdgcn_global_load_lds((const unsigned*)((const char*)(gbase) + (voff)[_i]), (PG8_LAS unsigned*)(lds + (bufoff) + ldsw + _i * 8192), 16, 0, 0); } while (0)
; #define PG8_LDA(dst, b, h) do { _Pragma("unroll") for (int m = 0; m < 4; ++m) _Pragma("unroll") for (int k = 0; k < 2; ++k) dst[m][k] = *(const PG8_LAS bf16x8*)(lds + PG8_SA(b, h) + aoff + m * 2048 + k * 1024); } while (0)
; #define PG8_LDB(dst, b, h) do { _Pragma("unroll") for (int n = 0; n < 2; ++n) _Pragma("unroll") for (int k = 0; k < 2; ++k) dst[n][k] = *(const PG8_LAS bf16x8*)(lds + PG8_SB(b, h) + boff + n * 2048 + k * 1024); } while (0)
; #define PG8_MMA(ai, bj, At, Bt) do { __builtin_amdgcn_s_setprio(1); _Pragma("unroll") for (int m = 0; m < 4; ++m) _Pragma("unroll") for (int n = 0; n < 2; ++n) _Pragma("unroll") for (int k = 0; k < 2; ++k) \
;         acc[ai][bj][m][n] = __builtin_amdgcn_mfma_f32_16x16x32_bf16(Bt[n][k], At[m][k], acc[ai][bj][m][n], 0, 0, 0); __builtin_amdgcn_s_setprio(0); } while (0)
; #define PG8_WAIT_V(n) asm volatile("s_waitcnt vmcnt(" #n ")" ::: "memory")
; #define PG8_WAIT_L(n) asm volatile("s_waitcnt lgkmcnt(" #n ")" ::: "memory")
; #define PG8_BAR __builtin_amdgcn_s_barrier()
; #define PG8_SCHED __builtin_amdgcn_sched_barrier(0)
; template <class Epi, class Sched, bool ALIGN_EPI = false, bool SP2 = false>
; __device__ __forceinline__ void gemm_phase(PG8_LAS unsigned char* lds, const Gemm g, const Sched& S, const Epi& E) {
;     ...
;             PG8_LDB(B0, 1, 0); PG8_LDB(B1, 1, 1); PG8_SCHED; PG8_LDA(At, 1, 0); PG8_STAGE(PG8_SA(0, 1), a2 + hstep, voffA);
;             PG8_WAIT_V(8); PG8_WAIT_L(0); PG8_BAR; PG8_MMA(0, 0, At, B0); PG8_MMA(0, 1, At, B1); PG8_BAR; PG8_SCHED;
;             PG8_LDA(At, 1, 1); PG8_STAGE(PG8_SB(1, 0), b3, voffB); PG8_STAGE(PG8_SB(1, 1), b3 + hstep, voffB); PG8_STAGE(PG8_SA(1, 0), a3, voffA);
;             PG8_WAIT_V(8); PG8_WAIT_L(0); PG8_BAR; PG8_MMA(1, 0, At, B0); PG8_MMA(1, 1, At, B1); PG8_BAR; PG8_SCHED;
;     ...
;         if constexpr (ALIGN_EPI) { if (wr == 0) PG8_BAR; }
	ds_read_b128 v[128:131], v254 offset:32768
	ds_read_b128 v[132:135], v254 offset:33792
	ds_read_b128 v[136:139], v254 offset:34816
	ds_read_b128 v[140:143], v254 offset:35840
	ds_read_b128 v[174:177], v254 offset:49152
	ds_read_b128 v[184:187], v254 offset:50176
	ds_read_b128 v[188:191], v254 offset:51200
	ds_read_b128 v[210:213], v254 offset:52224
	s_add_u32 s0, s6, 0xb0000
	s_addc_u32 s1, s7, 0
	s_mov_b32 m0, s42
	ds_read_b128 v[214:217], v181 offset:32768
	ds_read_b128 v[218:221], v181 offset:33792
	ds_read_b128 v[222:225], v181 offset:34816
	ds_read_b128 v[226:229], v181 offset:35840
	ds_read_b128 v[230:233], v181 offset:36864
	ds_read_b128 v[234:237], v181 offset:37888
	ds_read_b128 v[238:241], v181 offset:38912
	ds_read_b128 v[242:245], v181 offset:39936
	global_load_lds_dwordx4 v168, s[0:1]
	s_mov_b32 m0, s43
	s_nop 0
	global_load_lds_dwordx4 v164, s[0:1]
	s_waitcnt vmcnt(8)
	s_waitcnt lgkmcnt(0)
	s_barrier
	s_setprio 1
	s_waitcnt lgkmcnt(0)
	v_mfma_f32_16x16x32_bf16 v[124:127], v[128:131], v[214:217], v[124:127]
	v_mfma_f32_16x16x32_bf16 v[120:123], v[136:139], v[214:217], v[120:123]
	v_mfma_f32_16x16x32_bf16 v[108:111], v[128:131], v[222:225], v[108:111]
	v_mfma_f32_16x16x32_bf16 v[104:107], v[136:139], v[222:225], v[104:107]
	v_mfma_f32_16x16x32_bf16 v[92:95], v[128:131], v[230:233], v[92:95]
	v_mfma_f32_16x16x32_bf16 v[88:91], v[136:139], v[230:233], v[88:91]
	v_mfma_f32_16x16x32_bf16 v[76:79], v[128:131], v[238:241], v[76:79]
	v_mfma_f32_16x16x32_bf16 v[72:75], v[136:139], v[238:241], v[72:75]
	v_mfma_f32_16x16x32_bf16 v[124:127], v[132:135], v[218:221], v[124:127]
	v_mfma_f32_16x16x32_bf16 v[120:123], v[140:143], v[218:221], v[120:123]
	v_mfma_f32_16x16x32_bf16 v[108:111], v[132:135], v[226:229], v[108:111]
	v_mfma_f32_16x16x32_bf16 v[104:107], v[140:143], v[226:229], v[104:107]
	v_mfma_f32_16x16x32_bf16 v[92:95], v[132:135], v[234:237], v[92:95]
	v_mfma_f32_16x16x32_bf16 v[88:91], v[140:143], v[234:237], v[88:91]
	v_mfma_f32_16x16x32_bf16 v[76:79], v[132:135], v[242:245], v[76:79]
	v_mfma_f32_16x16x32_bf16 v[72:75], v[140:143], v[242:245], v[72:75]
	s_setprio 0
	s_setprio 1
	v_mfma_f32_16x16x32_bf16 v[116:119], v[174:177], v[214:217], v[116:119]
	v_mfma_f32_16x16x32_bf16 v[112:115], v[188:191], v[214:217], v[112:115]
	v_mfma_f32_16x16x32_bf16 v[100:103], v[174:177], v[222:225], v[100:103]
	v_mfma_f32_16x16x32_bf16 v[96:99], v[188:191], v[222:225], v[96:99]
	v_mfma_f32_16x16x32_bf16 v[84:87], v[174:177], v[230:233], v[84:87]
	v_mfma_f32_16x16x32_bf16 v[80:83], v[188:191], v[230:233], v[80:83]
	v_mfma_f32_16x16x32_bf16 v[68:71], v[174:177], v[238:241], v[68:71]
	v_mfma_f32_16x16x32_bf16 v[64:67], v[188:191], v[238:241], v[64:67]
	v_mfma_f32_16x16x32_bf16 v[116:119], v[184:187], v[218:221], v[116:119]
	v_mfma_f32_16x16x32_bf16 v[112:115], v[210:213], v[218:221], v[112:115]
	v_mfma_f32_16x16x32_bf16 v[100:103], v[184:187], v[226:229], v[100:103]
	v_mfma_f32_16x16x32_bf16 v[96:99], v[210:213], v[226:229], v[96:99]
	v_mfma_f32_16x16x32_bf16 v[84:87], v[184:187], v[234:237], v[84:87]
	v_mfma_f32_16x16x32_bf16 v[80:83], v[210:213], v[234:237], v[80:83]
	v_mfma_f32_16x16x32_bf16 v[68:71], v[184:187], v[242:245], v[68:71]
	v_mfma_f32_16x16x32_bf16 v[64:67], v[210:213], v[242:245], v[64:67]
	s_setprio 0
	s_barrier
	s_mov_b32 m0, s47
	s_add_u32 s0, s4, 0xb0080
	s_addc_u32 s1, s5, 0
	ds_read_b128 v[214:217], v181 offset:49152
	ds_read_b128 v[218:221], v181 offset:50176
	ds_read_b128 v[222:225], v181 offset:51200
	ds_read_b128 v[226:229], v181 offset:52224
	ds_read_b128 v[230:233], v181 offset:53248
	ds_read_b128 v[234:237], v181 offset:54272
	ds_read_b128 v[238:241], v181 offset:55296
	ds_read_b128 v[242:245], v181 offset:56320
	s_add_u32 s98, s4, 0x80
	s_addc_u32 s99, s5, 0
	global_load_lds_dwordx4 v166, s[98:99]
	s_mov_b32 m0, s48
	s_nop 0
	global_load_lds_dwordx4 v162, s[98:99]
	s_mov_b32 m0, s51
	s_nop 0
	global_load_lds_dwordx4 v166, s[0:1]
	s_mov_b32 m0, s52
	s_nop 0
	global_load_lds_dwordx4 v162, s[0:1]
	s_mov_b32 m0, s49
	s_nop 0
	s_add_u32 s100, s6, 0x80
	s_addc_u32 s101, s7, 0
	global_load_lds_dwordx4 v168, s[100:101]
	s_mov_b32 m0, s50
	s_nop 0
	global_load_lds_dwordx4 v164, s[100:101]
	s_waitcnt vmcnt(8)
	s_waitcnt lgkmcnt(0)
	s_barrier
	s_setprio 1
	s_waitcnt lgkmcnt(0)
	v_mfma_f32_16x16x32_bf16 v[60:63], v[128:131], v[214:217], v[60:63]
	v_mfma_f32_16x16x32_bf16 v[56:59], v[136:139], v[214:217], v[56:59]
	v_mfma_f32_16x16x32_bf16 v[44:47], v[128:131], v[222:225], v[44:47]
	v_mfma_f32_16x16x32_bf16 v[40:43], v[136:139], v[222:225], v[40:43]
	v_mfma_f32_16x16x32_bf16 v[28:31], v[128:131], v[230:233], v[28:31]
	v_mfma_f32_16x16x32_bf16 v[24:27], v[136:139], v[230:233], v[24:27]
	v_mfma_f32_16x16x32_bf16 v[12:15], v[128:131], v[238:241], v[12:15]
	v_mfma_f32_16x16x32_bf16 v[8:11], v[136:139], v[238:241], v[8:11]
	v_mfma_f32_16x16x32_bf16 v[60:63], v[132:135], v[218:221], v[60:63]
	v_mfma_f32_16x16x32_bf16 v[56:59], v[140:143], v[218:221], v[56:59]
	v_mfma_f32_16x16x32_bf16 v[44:47], v[132:135], v[226:229], v[44:47]
	v_mfma_f32_16x16x32_bf16 v[40:43], v[140:143], v[226:229], v[40:43]
	v_mfma_f32_16x16x32_bf16 v[28:31], v[132:135], v[234:237], v[28:31]
	v_mfma_f32_16x16x32_bf16 v[24:27], v[140:143], v[234:237], v[24:27]
	v_mfma_f32_16x16x32_bf16 v[12:15], v[132:135], v[242:245], v[12:15]
	v_mfma_f32_16x16x32_bf16 v[8:11], v[140:143], v[242:245], v[8:11]
	s_setprio 0
	s_setprio 1
	v_mfma_f32_16x16x32_bf16 v[52:55], v[174:177], v[214:217], v[52:55]
	v_mfma_f32_16x16x32_bf16 v[48:51], v[188:191], v[214:217], v[48:51]
	v_mfma_f32_16x16x32_bf16 v[36:39], v[174:177], v[222:225], v[36:39]
	v_mfma_f32_16x16x32_bf16 v[32:35], v[188:191], v[222:225], v[32:35]
	v_mfma_f32_16x16x32_bf16 v[20:23], v[174:177], v[230:233], v[20:23]
	v_mfma_f32_16x16x32_bf16 v[16:19], v[188:191], v[230:233], v[16:19]
	v_mfma_f32_16x16x32_bf16 v[4:7], v[174:177], v[238:241], v[4:7]
	v_mfma_f32_16x16x32_bf16 v[0:3], v[188:191], v[238:241], v[0:3]
	v_mfma_f32_16x16x32_bf16 v[52:55], v[184:187], v[218:221], v[52:55]
	v_mfma_f32_16x16x32_bf16 v[48:51], v[210:213], v[218:221], v[48:51]
	v_mfma_f32_16x16x32_bf16 v[36:39], v[184:187], v[226:229], v[36:39]
	v_mfma_f32_16x16x32_bf16 v[32:35], v[210:213], v[226:229], v[32:35]
	v_mfma_f32_16x16x32_bf16 v[20:23], v[184:187], v[234:237], v[20:23]
	v_mfma_f32_16x16x32_bf16 v[16:19], v[210:213], v[234:237], v[16:19]
	v_mfma_f32_16x16x32_bf16 v[4:7], v[184:187], v[242:245], v[4:7]
	v_mfma_f32_16x16x32_bf16 v[0:3], v[210:213], v[242:245], v[0:3]
	s_setprio 0
	s_barrier
	s_add_i32 s13, s13, 2
	s_add_u32 s10, s10, 0x100
	s_addc_u32 s11, s11, 0
	s_cmp_gt_u32 s13, 41
	s_mov_b64 s[0:1], s[2:3]
	s_cbranch_scc0 .LBB0_545
	s_and_b64 vcc, exec, s[22:23]
	s_cbranch_vccz .LBB0_548
	s_barrier

; #define PG8_STAGE(bufoff, gbase, voff) do { _Pragma("unroll") for (int _i = 0; _i < 2; ++_i) \
;         __builtin_amdgcn_global_load_lds((const unsigned*)((const char*)(gbase) + (voff)[_i]), (PG8_LAS unsigned*)(lds + (bufoff) + ldsw + _i * 8192), 16, 0, 0); } while (0)
; #define PG8_LDA(dst, b, h) do { _Pragma("unroll") for (int m = 0; m < 4; ++m) _Pragma("unroll") for (int k = 0; k < 2; ++k) dst[m][k] = *(const PG8_LAS bf16x8*)(lds + PG8_SA(b, h) + aoff + m * 2048 + k * 1024); } while (0)
; #define PG8_LDB(dst, b, h) do { _Pragma("unroll") for (int n = 0; n < 2; ++n) _Pragma("unroll") for (int k = 0; k < 2; ++k) dst[n][k] = *(const PG8_LAS bf16x8*)(lds + PG8_SB(b, h) + boff + n * 2048 + k * 1024); } while (0)
; #define PG8_MMA(ai, bj, At, Bt) do { __builtin_amdgcn_s_setprio(1); _Pragma("unroll") for (int m = 0; m < 4; ++m) _Pragma("unroll") for (int n = 0; n < 2; ++n) _Pragma("unroll") for (int k = 0; k < 2; ++k) \
;         acc[ai][bj][m][n] = __builtin_amdgcn_mfma_f32_16x16x32_bf16(Bt[n][k], At[m][k], acc[ai][bj][m][n], 0, 0, 0); __builtin_amdgcn_s_setprio(0); } while (0)
; #define PG8_BAR __builtin_amdgcn_s_barrier()
; template <class Epi, class Sched, bool ALIGN_EPI = false, bool SP2 = false>
; __device__ __forceinline__ void gemm_phase(PG8_LAS unsigned char* lds, const Gemm g, const Sched& S, const Epi& E) {
;     ...
;         const bool has_next = S.next(ui + 1, nxt);
;         const char* nA = has_next ? (const char*)g.A + (size_t)nxt.pm * tstep : cA; const char* nB = has_next ? (const char*)g.Bt + (size_t)nxt.pn * tstep : cB;
;         for (int t = 0; t < nt; t += 2) {
;             const bool last = (t == nt - 2);
;             const char* a1 = cA + (size_t)(t + 1) * kstep;
;             const char* a2 = last ? nA : cA + (size_t)(t + 2) * kstep; const char* b2 = last ? nB : cB + (size_t)(t + 2) * kstep;
;             const char* a3 = a2 + kstep; const char* b3 = b2 + kstep;
;             if (last && has_next) S.a_ready(nxt);
;             if constexpr (SP2) {
;             PG8_LDB(B0, 0, 0); PG8_LDB(B1, 0, 1); PG8_SCHED; PG8_LDA(At, 0, 0); PG8_STAGE(PG8_SA(1, 1), a1 + hstep, voffA);
;             PG8_WAIT_V(8); PG8_WAIT_L(0); PG8_BAR; PG8_MMA(0, 0, At, B0); PG8_MMA(0, 1, At, B1); PG8_BAR; PG8_SCHED;
;             PG8_LDA(At, 0, 1); PG8_STAGE(PG8_SB(0, 0), b2, voffB); PG8_STAGE(PG8_SB(0, 1), b2 + hstep, voffB); PG8_STAGE(PG8_SA(0, 0), a2, voffA);
.LBB0_748:
	s_ashr_i32 s25, s24, 31
	s_lshl_b64 s[4:5], s[24:25], 19
	s_add_u32 s26, s7, s4
	s_addc_u32 s27, s28, s5
	s_and_b64 s[4:5], s[8:9], exec
	s_cselect_b32 s13, s27, s1
	s_cselect_b32 s25, s26, s0
	s_ashr_i32 s23, s22, 31
	s_lshl_b64 s[4:5], s[22:23], 19
	s_add_u32 s36, s29, s4
	s_addc_u32 s37, s30, s5
	s_and_b64 s[4:5], s[8:9], exec
	s_cselect_b32 s23, s37, s3
	s_cselect_b32 s33, s36, s2
	s_add_u32 s0, s0, 0x40080
	s_addc_u32 s1, s1, 0
	s_add_u32 s38, s2, 0x100
	v_mov_b32_e32 v0, 0
	s_addc_u32 s39, s3, 0
	s_mov_b32 s55, -2
	s_waitcnt lgkmcnt(0)
	v_add_u32_e32 v254, 0x10000, v179
.Lsgi_peel:
	ds_read_b128 v[140:143], v254
	ds_read_b128 v[162:165], v254 offset:1024
	ds_read_b128 v[166:169], v254 offset:2048
	ds_read_b128 v[170:173], v254 offset:3072
	ds_read_b128 v[180:183], v254 offset:16384
	ds_read_b128 v[184:187], v254 offset:17408
	ds_read_b128 v[188:191], v254 offset:18432
	ds_read_b128 v[210:213], v254 offset:19456
	s_add_u32 s2, s0, 0xfffc0080
	s_addc_u32 s3, s1, -1
	s_cmp_eq_u32 s55, 12
	s_cselect_b32 s5, s13, s3
	s_cselect_b32 s4, s25, s2
	s_cselect_b32 s3, s23, s39
	s_cselect_b32 s2, s33, s38
	s_add_i32 m0, s6, 0xc000
	ds_read_b128 v[214:217], v178
	ds_read_b128 v[218:221], v178 offset:1024
	ds_read_b128 v[222:225], v178 offset:2048
	ds_read_b128 v[226:229], v178 offset:3072
	ds_read_b128 v[230:233], v178 offset:4096
	ds_read_b128 v[234:237], v178 offset:5120
	ds_read_b128 v[238:241], v178 offset:6144
	ds_read_b128 v[242:245], v178 offset:7168
	global_load_lds_dwordx4 v136, s[0:1]
	s_add_i32 m0, s6, 0xe000
	s_nop 0
	global_load_lds_dwordx4 v138, s[0:1]
	s_waitcnt vmcnt(8)
	s_waitcnt lgkmcnt(0)
	s_barrier
	s_setprio 1
	s_waitcnt lgkmcnt(0)
	v_mfma_f32_16x16x32_bf16 v[124:127], v[140:143], v[214:217], 0
	v_mfma_f32_16x16x32_bf16 v[120:123], v[166:169], v[214:217], 0
	v_mfma_f32_16x16x32_bf16 v[108:111], v[140:143], v[222:225], 0
	v_mfma_f32_16x16x32_bf16 v[104:107], v[166:169], v[222:225], 0
	v_mfma_f32_16x16x32_bf16 v[92:95], v[140:143], v[230:233], 0
	v_mfma_f32_16x16x32_bf16 v[88:91], v[166:169], v[230:233], 0
	v_mfma_f32_16x16x32_bf16 v[76:79], v[140:143], v[238:241], 0
	v_mfma_f32_16x16x32_bf16 v[72:75], v[166:169], v[238:241], 0
	v_mfma_f32_16x16x32_bf16 v[124:127], v[162:165], v[218:221], v[124:127]
	v_mfma_f32_16x16x32_bf16 v[120:123], v[170:173], v[218:221], v[120:123]
	v_mfma_f32_16x16x32_bf16 v[108:111], v[162:165], v[226:229], v[108:111]
	v_mfma_f32_16x16x32_bf16 v[104:107], v[170:173], v[226:229], v[104:107]
	v_mfma_f32_16x16x32_bf16 v[92:95], v[162:165], v[234:237], v[92:95]
	v_mfma_f32_16x16x32_bf16 v[88:91], v[170:173], v[234:237], v[88:91]
	v_mfma_f32_16x16x32_bf16 v[76:79], v[162:165], v[242:245], v[76:79]
	v_mfma_f32_16x16x32_bf16 v[72:75], v[170:173], v[242:245], v[72:75]
	s_setprio 0
	s_setprio 1
	v_mfma_f32_16x16x32_bf16 v[116:119], v[180:183], v[214:217], 0
	v_mfma_f32_16x16x32_bf16 v[112:115], v[188:191], v[214:217], 0
	v_mfma_f32_16x16x32_bf16 v[100:103], v[180:183], v[222:225], 0
	v_mfma_f32_16x16x32_bf16 v[96:99], v[188:191], v[222:225], 0
	v_mfma_f32_16x16x32_bf16 v[84:87], v[180:183], v[230:233], 0
	v_mfma_f32_16x16x32_bf16 v[80:83], v[188:191], v[230:233], 0
	v_mfma_f32_16x16x32_bf16 v[68:71], v[180:183], v[238:241], 0
	v_mfma_f32_16x16x32_bf16 v[64:67], v[188:191], v[238:241], 0
	v_mfma_f32_16x16x32_bf16 v[116:119], v[184:187], v[218:221], v[116:119]
	v_mfma_f32_16x16x32_bf16 v[112:115], v[210:213], v[218:221], v[112:115]
	v_mfma_f32_16x16x32_bf16 v[100:103], v[184:187], v[226:229], v[100:103]
	v_mfma_f32_16x16x32_bf16 v[96:99], v[210:213], v[226:229], v[96:99]
	v_mfma_f32_16x16x32_bf16 v[84:87], v[184:187], v[234:237], v[84:87]
	v_mfma_f32_16x16x32_bf16 v[80:83], v[210:213], v[234:237], v[80:83]
	v_mfma_f32_16x16x32_bf16 v[68:71], v[184:187], v[242:245], v[68:71]
	v_mfma_f32_16x16x32_bf16 v[64:67], v[210:213], v[242:245], v[64:67]
	s_setprio 0
	s_barrier
	s_mov_b32 m0, s31
	s_add_u32 s56, s2, 0x40000
	s_addc_u32 s57, s3, 0
	ds_read_b128 v[214:217], v178 offset:16384
	ds_read_b128 v[218:221], v178 offset:17408
	ds_read_b128 v[222:225], v178 offset:18432
	ds_read_b128 v[226:229], v178 offset:19456
	ds_read_b128 v[230:233], v178 offset:20480
	ds_read_b128 v[234:237], v178 offset:21504
	ds_read_b128 v[238:241], v178 offset:22528
	ds_read_b128 v[242:245], v178 offset:23552
	global_load_lds_dwordx4 v132, s[2:3]
	s_mov_b32 m0, s34
	s_nop 0
	global_load_lds_dwordx4 v128, s[2:3]
	s_mov_b32 m0, s35
	s_nop 0
	global_load_lds_dwordx4 v132, s[56:57]
	s_mov_b32 m0, s40
	s_nop 0
	global_load_lds_dwordx4 v128, s[56:57]
	s_mov_b32 m0, s6
	s_nop 0
	global_load_lds_dwordx4 v134, s[4:5]
	s_mov_b32 m0, s41
	s_nop 0
	global_load_lds_dwordx4 v130, s[4:5]
	s_waitcnt vmcnt(8)
	s_waitcnt lgkmcnt(0)
	s_barrier
; #define PG8_STAGE(bufoff, gbase, voff) do { _Pragma("unroll") for (int _i = 0; _i < 2; ++_i) \
;         __builtin_amdgcn_global_load_lds((const unsigned*)((const char*)(gbase) + (voff)[_i]), (PG8_LAS unsigned*)(lds + (bufoff) + ldsw + _i * 8192), 16, 0, 0); } while (0)
; #define PG8_LDA(dst, b, h) do { _Pragma("unroll") for (int m = 0; m < 4; ++m) _Pragma("unroll") for (int k = 0; k < 2; ++k) dst[m][k] = *(const PG8_LAS bf16x8*)(lds + PG8_SA(b, h) + aoff + m * 2048 + k * 1024); } while (0)
; #define PG8_LDB(dst, b, h) do { _Pragma("unroll") for (int n = 0; n < 2; ++n) _Pragma("unroll") for (int k = 0; k < 2; ++k) dst[n][k] = *(const PG8_LAS bf16x8*)(lds + PG8_SB(b, h) + boff + n * 2048 + k * 1024); } while (0)
; #define PG8_MMA(ai, bj, At, Bt) do { __builtin_amdgcn_s_setprio(1); _Pragma("unroll") for (int m = 0; m < 4; ++m) _Pragma("unroll") for (int n = 0; n < 2; ++n) _Pragma("unroll") for (int k = 0; k < 2; ++k) \
;         acc[ai][bj][m][n] = __builtin_amdgcn_mfma_f32_16x16x32_bf16(Bt[n][k], At[m][k], acc[ai][bj][m][n], 0, 0, 0); __builtin_amdgcn_s_setprio(0); } while (0)
; #define PG8_WAIT_V(n) asm volatile("s_waitcnt vmcnt(" #n ")" ::: "memory")
; #define PG8_WAIT_L(n) asm volatile("s_waitcnt lgkmcnt(" #n ")" ::: "memory")
; #define PG8_BAR __builtin_amdgcn_s_barrier()
; #define PG8_SCHED __builtin_amdgcn_sched_barrier(0)
; template <class Epi, class Sched, bool ALIGN_EPI = false, bool SP2 = false>
; __device__ __forceinline__ void gemm_phase(PG8_LAS unsigned char* lds, const Gemm g, const Sched& S, const Epi& E) {
;     ...
;             PG8_WAIT_V(8); PG8_WAIT_L(0); PG8_BAR; PG8_MMA(1, 0, At, B0); PG8_MMA(1, 1, At, B1); PG8_BAR; PG8_SCHED;
;             PG8_LDB(B0, 1, 0); PG8_LDB(B1, 1, 1); PG8_SCHED; PG8_LDA(At, 1, 0); PG8_STAGE(PG8_SA(0, 1), a2 + hstep, voffA);
;             PG8_WAIT_V(8); PG8_WAIT_L(0); PG8_BAR; PG8_MMA(0, 0, At, B0); PG8_MMA(0, 1, At, B1); PG8_BAR; PG8_SCHED;
	s_setprio 1
	s_waitcnt lgkmcnt(0)
	v_mfma_f32_16x16x32_bf16 v[60:63], v[140:143], v[214:217], 0
	v_mfma_f32_16x16x32_bf16 v[56:59], v[166:169], v[214:217], 0
	v_mfma_f32_16x16x32_bf16 v[44:47], v[140:143], v[222:225], 0
	v_mfma_f32_16x16x32_bf16 v[40:43], v[166:169], v[222:225], 0
	v_mfma_f32_16x16x32_bf16 v[28:31], v[140:143], v[230:233], 0
	v_mfma_f32_16x16x32_bf16 v[24:27], v[166:169], v[230:233], 0
	v_mfma_f32_16x16x32_bf16 v[12:15], v[140:143], v[238:241], 0
	v_mfma_f32_16x16x32_bf16 v[8:11], v[166:169], v[238:241], 0
	v_mfma_f32_16x16x32_bf16 v[60:63], v[162:165], v[218:221], v[60:63]
	v_mfma_f32_16x16x32_bf16 v[56:59], v[170:173], v[218:221], v[56:59]
	v_mfma_f32_16x16x32_bf16 v[44:47], v[162:165], v[226:229], v[44:47]
	v_mfma_f32_16x16x32_bf16 v[40:43], v[170:173], v[226:229], v[40:43]
	v_mfma_f32_16x16x32_bf16 v[28:31], v[162:165], v[234:237], v[28:31]
	v_mfma_f32_16x16x32_bf16 v[24:27], v[170:173], v[234:237], v[24:27]
	v_mfma_f32_16x16x32_bf16 v[12:15], v[162:165], v[242:245], v[12:15]
	v_mfma_f32_16x16x32_bf16 v[8:11], v[170:173], v[242:245], v[8:11]
	s_setprio 0
	s_setprio 1
	v_mfma_f32_16x16x32_bf16 v[52:55], v[180:183], v[214:217], 0
	v_mfma_f32_16x16x32_bf16 v[48:51], v[188:191], v[214:217], 0
	v_mfma_f32_16x16x32_bf16 v[36:39], v[180:183], v[222:225], 0
	v_mfma_f32_16x16x32_bf16 v[32:35], v[188:191], v[222:225], 0
	v_mfma_f32_16x16x32_bf16 v[20:23], v[180:183], v[230:233], 0
	v_mfma_f32_16x16x32_bf16 v[16:19], v[188:191], v[230:233], 0
	v_mfma_f32_16x16x32_bf16 v[4:7], v[180:183], v[238:241], 0
	v_mfma_f32_16x16x32_bf16 v[0:3], v[188:191], v[238:241], 0
	v_mfma_f32_16x16x32_bf16 v[52:55], v[184:187], v[218:221], v[52:55]
	v_mfma_f32_16x16x32_bf16 v[48:51], v[210:213], v[218:221], v[48:51]
	v_mfma_f32_16x16x32_bf16 v[36:39], v[184:187], v[226:229], v[36:39]
	v_mfma_f32_16x16x32_bf16 v[32:35], v[210:213], v[226:229], v[32:35]
	v_mfma_f32_16x16x32_bf16 v[20:23], v[184:187], v[234:237], v[20:23]
	v_mfma_f32_16x16x32_bf16 v[16:19], v[210:213], v[234:237], v[16:19]
	v_mfma_f32_16x16x32_bf16 v[4:7], v[184:187], v[242:245], v[4:7]
	v_mfma_f32_16x16x32_bf16 v[0:3], v[210:213], v[242:245], v[0:3]
	s_setprio 0
	s_barrier
	ds_read_b128 v[140:143], v254 offset:32768
	ds_read_b128 v[162:165], v254 offset:33792
	ds_read_b128 v[166:169], v254 offset:34816
	ds_read_b128 v[170:173], v254 offset:35840
	ds_read_b128 v[180:183], v254 offset:49152
	ds_read_b128 v[184:187], v254 offset:50176
	ds_read_b128 v[188:191], v254 offset:51200
	ds_read_b128 v[210:213], v254 offset:52224
	s_add_u32 s4, s4, 0x40000
	s_addc_u32 s5, s5, 0
	s_mov_b32 m0, s42
	ds_read_b128 v[214:217], v178 offset:32768
	ds_read_b128 v[218:221], v178 offset:33792
	ds_read_b128 v[222:225], v178 offset:34816
	ds_read_b128 v[226:229], v178 offset:35840
	ds_read_b128 v[230:233], v178 offset:36864
	ds_read_b128 v[234:237], v178 offset:37888
	ds_read_b128 v[238:241], v178 offset:38912
	ds_read_b128 v[242:245], v178 offset:39936
	global_load_lds_dwordx4 v134, s[4:5]
	s_mov_b32 m0, s43
	s_nop 0
	global_load_lds_dwordx4 v130, s[4:5]
	s_waitcnt vmcnt(8)
	s_waitcnt lgkmcnt(0)
	s_barrier
	s_setprio 1
	s_waitcnt lgkmcnt(0)
	v_mfma_f32_16x16x32_bf16 v[124:127], v[140:143], v[214:217], v[124:127]
	v_mfma_f32_16x16x32_bf16 v[120:123], v[166:169], v[214:217], v[120:123]
	v_mfma_f32_16x16x32_bf16 v[108:111], v[140:143], v[222:225], v[108:111]
	v_mfma_f32_16x16x32_bf16 v[104:107], v[166:169], v[222:225], v[104:107]
	v_mfma_f32_16x16x32_bf16 v[92:95], v[140:143], v[230:233], v[92:95]
	v_mfma_f32_16x16x32_bf16 v[88:91], v[166:169], v[230:233], v[88:91]
	v_mfma_f32_16x16x32_bf16 v[76:79], v[140:143], v[238:241], v[76:79]
	v_mfma_f32_16x16x32_bf16 v[72:75], v[166:169], v[238:241], v[72:75]
	v_mfma_f32_16x16x32_bf16 v[124:127], v[162:165], v[218:221], v[124:127]
	v_mfma_f32_16x16x32_bf16 v[120:123], v[170:173], v[218:221], v[120:123]
	v_mfma_f32_16x16x32_bf16 v[108:111], v[162:165], v[226:229], v[108:111]
	v_mfma_f32_16x16x32_bf16 v[104:107], v[170:173], v[226:229], v[104:107]
	v_mfma_f32_16x16x32_bf16 v[92:95], v[162:165], v[234:237], v[92:95]
	v_mfma_f32_16x16x32_bf16 v[88:91], v[170:173], v[234:237], v[88:91]
	v_mfma_f32_16x16x32_bf16 v[76:79], v[162:165], v[242:245], v[76:79]
	v_mfma_f32_16x16x32_bf16 v[72:75], v[170:173], v[242:245], v[72:75]
	s_setprio 0
	s_setprio 1
	v_mfma_f32_16x16x32_bf16 v[116:119], v[180:183], v[214:217], v[116:119]
	v_mfma_f32_16x16x32_bf16 v[112:115], v[188:191], v[214:217], v[112:115]
	v_mfma_f32_16x16x32_bf16 v[100:103], v[180:183], v[222:225], v[100:103]
	v_mfma_f32_16x16x32_bf16 v[96:99], v[188:191], v[222:225], v[96:99]
	v_mfma_f32_16x16x32_bf16 v[84:87], v[180:183], v[230:233], v[84:87]
	v_mfma_f32_16x16x32_bf16 v[80:83], v[188:191], v[230:233], v[80:83]
	v_mfma_f32_16x16x32_bf16 v[68:71], v[180:183], v[238:241], v[68:71]
	v_mfma_f32_16x16x32_bf16 v[64:67], v[188:191], v[238:241], v[64:67]
	v_mfma_f32_16x16x32_bf16 v[116:119], v[184:187], v[218:221], v[116:119]
	v_mfma_f32_16x16x32_bf16 v[112:115], v[210:213], v[218:221], v[112:115]
	v_mfma_f32_16x16x32_bf16 v[100:103], v[184:187], v[226:229], v[100:103]
	v_mfma_f32_16x16x32_bf16 v[96:99], v[210:213], v[226:229], v[96:99]
	v_mfma_f32_16x16x32_bf16 v[84:87], v[184:187], v[234:237], v[84:87]
	v_mfma_f32_16x16x32_bf16 v[80:83], v[210:213], v[234:237], v[80:83]
	v_mfma_f32_16x16x32_bf16 v[68:71], v[184:187], v[242:245], v[68:71]
	v_mfma_f32_16x16x32_bf16 v[64:67], v[210:213], v[242:245], v[64:67]
	s_setprio 0
	s_barrier
; #define PG8_STAGE(bufoff, gbase, voff) do { _Pragma("unroll") for (int _i = 0; _i < 2; ++_i) \
;         __builtin_amdgcn_global_load_lds((const unsigned*)((const char*)(gbase) + (voff)[_i]), (PG8_LAS unsigned*)(lds + (bufoff) + ldsw + _i * 8192), 16, 0, 0); } while (0)
; #define PG8_LDA(dst, b, h) do { _Pragma("unroll") for (int m = 0; m < 4; ++m) _Pragma("unroll") for (int k = 0; k < 2; ++k) dst[m][k] = *(const PG8_LAS bf16x8*)(lds + PG8_SA(b, h) + aoff + m * 2048 + k * 1024); } while (0)
; #define PG8_LDB(dst, b, h) do { _Pragma("unroll") for (int n = 0; n < 2; ++n) _Pragma("unroll") for (int k = 0; k < 2; ++k) dst[n][k] = *(const PG8_LAS bf16x8*)(lds + PG8_SB(b, h) + boff + n * 2048 + k * 1024); } while (0)
; #define PG8_MMA(ai, bj, At, Bt) do { __builtin_amdgcn_s_setprio(1); _Pragma("unroll") for (int m = 0; m < 4; ++m) _Pragma("unroll") for (int n = 0; n < 2; ++n) _Pragma("unroll") for (int k = 0; k < 2; ++k) \
;         acc[ai][bj][m][n] = __builtin_amdgcn_mfma_f32_16x16x32_bf16(Bt[n][k], At[m][k], acc[ai][bj][m][n], 0, 0, 0); __builtin_amdgcn_s_setprio(0); } while (0)
; #define PG8_WAIT_V(n) asm volatile("s_waitcnt vmcnt(" #n ")" ::: "memory")
; #define PG8_WAIT_L(n) asm volatile("s_waitcnt lgkmcnt(" #n ")" ::: "memory")
; #define PG8_BAR __builtin_amdgcn_s_barrier()
; #define PG8_SCHED __builtin_amdgcn_sched_barrier(0)
; template <class Epi, class Sched, bool ALIGN_EPI = false, bool SP2 = false>
; __device__ __forceinline__ void gemm_phase(PG8_LAS unsigned char* lds, const Gemm g, const Sched& S, const Epi& E) {
;     ...
;             PG8_LDB(B0, 0, 0); PG8_LDB(B1, 0, 1); PG8_SCHED; PG8_LDA(At, 0, 0); PG8_STAGE(PG8_SA(1, 1), a1 + hstep, voffA);
;             PG8_WAIT_V(8); PG8_WAIT_L(0); PG8_BAR; PG8_MMA(0, 0, At, B0); PG8_MMA(0, 1, At, B1); PG8_BAR; PG8_SCHED;
;     ...
;             PG8_LDA(At, 1, 1); PG8_STAGE(PG8_SB(1, 0), b3, voffB); PG8_STAGE(PG8_SB(1, 1), b3 + hstep, voffB); PG8_STAGE(PG8_SA(1, 0), a3, voffA);
;             PG8_WAIT_V(8); PG8_WAIT_L(0); PG8_BAR; PG8_MMA(1, 0, At, B0); PG8_MMA(1, 1, At, B1); PG8_BAR; PG8_SCHED;
	s_mov_b32 m0, s48
	s_add_u32 s2, s2, 0x40080
	s_addc_u32 s3, s3, 0
	ds_read_b128 v[214:217], v178 offset:49152
	ds_read_b128 v[218:221], v178 offset:50176
	ds_read_b128 v[222:225], v178 offset:51200
	ds_read_b128 v[226:229], v178 offset:52224
	ds_read_b128 v[230:233], v178 offset:53248
	ds_read_b128 v[234:237], v178 offset:54272
	ds_read_b128 v[238:241], v178 offset:55296
	ds_read_b128 v[242:245], v178 offset:56320
	s_add_u32 s98, s2, 0xfffc0000
	s_addc_u32 s99, s3, -1
	global_load_lds_dwordx4 v132, s[98:99]
	s_mov_b32 m0, s49
	s_nop 0
	global_load_lds_dwordx4 v128, s[98:99]
	s_mov_b32 m0, s52
	s_nop 0
	global_load_lds_dwordx4 v132, s[2:3]
	s_mov_b32 m0, s53
	s_nop 0
	global_load_lds_dwordx4 v128, s[2:3]
	s_mov_b32 m0, s50
	s_nop 0
	s_add_u32 s100, s4, 0xfffc0080
	s_addc_u32 s101, s5, -1
	global_load_lds_dwordx4 v134, s[100:101]
	s_mov_b32 m0, s51
	s_nop 0
	global_load_lds_dwordx4 v130, s[100:101]
	s_waitcnt vmcnt(8)
	s_waitcnt lgkmcnt(0)
	s_barrier
	s_setprio 1
	s_waitcnt lgkmcnt(0)
	v_mfma_f32_16x16x32_bf16 v[60:63], v[140:143], v[214:217], v[60:63]
	v_mfma_f32_16x16x32_bf16 v[56:59], v[166:169], v[214:217], v[56:59]
	v_mfma_f32_16x16x32_bf16 v[44:47], v[140:143], v[222:225], v[44:47]
	v_mfma_f32_16x16x32_bf16 v[40:43], v[166:169], v[222:225], v[40:43]
	v_mfma_f32_16x16x32_bf16 v[28:31], v[140:143], v[230:233], v[28:31]
	v_mfma_f32_16x16x32_bf16 v[24:27], v[166:169], v[230:233], v[24:27]
	v_mfma_f32_16x16x32_bf16 v[12:15], v[140:143], v[238:241], v[12:15]
	v_mfma_f32_16x16x32_bf16 v[8:11], v[166:169], v[238:241], v[8:11]
	v_mfma_f32_16x16x32_bf16 v[60:63], v[162:165], v[218:221], v[60:63]
	v_mfma_f32_16x16x32_bf16 v[56:59], v[170:173], v[218:221], v[56:59]
	v_mfma_f32_16x16x32_bf16 v[44:47], v[162:165], v[226:229], v[44:47]
	v_mfma_f32_16x16x32_bf16 v[40:43], v[170:173], v[226:229], v[40:43]
	v_mfma_f32_16x16x32_bf16 v[28:31], v[162:165], v[234:237], v[28:31]
	v_mfma_f32_16x16x32_bf16 v[24:27], v[170:173], v[234:237], v[24:27]
	v_mfma_f32_16x16x32_bf16 v[12:15], v[162:165], v[242:245], v[12:15]
	v_mfma_f32_16x16x32_bf16 v[8:11], v[170:173], v[242:245], v[8:11]
	s_setprio 0
	s_setprio 1
	v_mfma_f32_16x16x32_bf16 v[52:55], v[180:183], v[214:217], v[52:55]
	v_mfma_f32_16x16x32_bf16 v[48:51], v[188:191], v[214:217], v[48:51]
	v_mfma_f32_16x16x32_bf16 v[36:39], v[180:183], v[222:225], v[36:39]
	v_mfma_f32_16x16x32_bf16 v[32:35], v[188:191], v[222:225], v[32:35]
	v_mfma_f32_16x16x32_bf16 v[20:23], v[180:183], v[230:233], v[20:23]
	v_mfma_f32_16x16x32_bf16 v[16:19], v[188:191], v[230:233], v[16:19]
	v_mfma_f32_16x16x32_bf16 v[4:7], v[180:183], v[238:241], v[4:7]
	v_mfma_f32_16x16x32_bf16 v[0:3], v[188:191], v[238:241], v[0:3]
	v_mfma_f32_16x16x32_bf16 v[52:55], v[184:187], v[218:221], v[52:55]
	v_mfma_f32_16x16x32_bf16 v[48:51], v[210:213], v[218:221], v[48:51]
	v_mfma_f32_16x16x32_bf16 v[36:39], v[184:187], v[226:229], v[36:39]
	v_mfma_f32_16x16x32_bf16 v[32:35], v[210:213], v[226:229], v[32:35]
	v_mfma_f32_16x16x32_bf16 v[20:23], v[184:187], v[234:237], v[20:23]
	v_mfma_f32_16x16x32_bf16 v[16:19], v[210:213], v[234:237], v[16:19]
	v_mfma_f32_16x16x32_bf16 v[4:7], v[184:187], v[242:245], v[4:7]
	v_mfma_f32_16x16x32_bf16 v[0:3], v[210:213], v[242:245], v[0:3]
	s_setprio 0
	s_barrier
	s_add_i32 s55, s55, 2
	s_add_u32 s0, s0, 0x100
	s_addc_u32 s1, s1, 0
	s_add_u32 s38, s38, 0x100
	s_addc_u32 s39, s39, 0
	s_cmp_gt_u32 s55, 13
.LBB0_749:
	ds_read_b128 v[140:143], v254
	ds_read_b128 v[162:165], v254 offset:1024
	ds_read_b128 v[166:169], v254 offset:2048
	ds_read_b128 v[170:173], v254 offset:3072
	ds_read_b128 v[180:183], v254 offset:16384
	ds_read_b128 v[184:187], v254 offset:17408
	ds_read_b128 v[188:191], v254 offset:18432
	ds_read_b128 v[210:213], v254 offset:19456
	s_add_u32 s2, s0, 0xfffc0080
	s_addc_u32 s3, s1, -1
	s_cmp_eq_u32 s55, 12
	s_cselect_b32 s5, s13, s3
	s_cselect_b32 s4, s25, s2
	s_cselect_b32 s3, s23, s39
	s_cselect_b32 s2, s33, s38
	s_add_i32 m0, s6, 0xc000
	ds_read_b128 v[214:217], v178
	ds_read_b128 v[218:221], v178 offset:1024
	ds_read_b128 v[222:225], v178 offset:2048
	ds_read_b128 v[226:229], v178 offset:3072
	ds_read_b128 v[230:233], v178 offset:4096
	ds_read_b128 v[234:237], v178 offset:5120
	ds_read_b128 v[238:241], v178 offset:6144
	ds_read_b128 v[242:245], v178 offset:7168
	global_load_lds_dwordx4 v136, s[0:1]
	s_add_i32 m0, s6, 0xe000
	s_nop 0
	global_load_lds_dwordx4 v138, s[0:1]
	s_waitcnt vmcnt(8)
	s_waitcnt lgkmcnt(0)
	s_barrier
	s_setprio 1
	s_waitcnt lgkmcnt(0)
	v_mfma_f32_16x16x32_bf16 v[124:127], v[140:143], v[214:217], v[124:127]
	v_mfma_f32_16x16x32_bf16 v[120:123], v[166:169], v[214:217], v[120:123]
	v_mfma_f32_16x16x32_bf16 v[108:111], v[140:143], v[222:225], v[108:111]
	v_mfma_f32_16x16x32_bf16 v[104:107], v[166:169], v[222:225], v[104:107]
	v_mfma_f32_16x16x32_bf16 v[92:95], v[140:143], v[230:233], v[92:95]
	v_mfma_f32_16x16x32_bf16 v[88:91], v[166:169], v[230:233], v[88:91]
	v_mfma_f32_16x16x32_bf16 v[76:79], v[140:143], v[238:241], v[76:79]
	v_mfma_f32_16x16x32_bf16 v[72:75], v[166:169], v[238:241], v[72:75]
	v_mfma_f32_16x16x32_bf16 v[124:127], v[162:165], v[218:221], v[124:127]
	v_mfma_f32_16x16x32_bf16 v[120:123], v[170:173], v[218:221], v[120:123]
	v_mfma_f32_16x16x32_bf16 v[108:111], v[162:165], v[226:229], v[108:111]
	v_mfma_f32_16x16x32_bf16 v[104:107], v[170:173], v[226:229], v[104:107]
	v_mfma_f32_16x16x32_bf16 v[92:95], v[162:165], v[234:237], v[92:95]
	v_mfma_f32_16x16x32_bf16 v[88:91], v[170:173], v[234:237], v[88:91]
	v_mfma_f32_16x16x32_bf16 v[76:79], v[162:165], v[242:245], v[76:79]
	v_mfma_f32_16x16x32_bf16 v[72:75], v[170:173], v[242:245], v[72:75]
	s_setprio 0
	s_setprio 1
	v_mfma_f32_16x16x32_bf16 v[116:119], v[180:183], v[214:217], v[116:119]
	v_mfma_f32_16x16x32_bf16 v[112:115], v[188:191], v[214:217], v[112:115]
	v_mfma_f32_16x16x32_bf16 v[100:103], v[180:183], v[222:225], v[100:103]
	v_mfma_f32_16x16x32_bf16 v[96:99], v[188:191], v[222:225], v[96:99]
	v_mfma_f32_16x16x32_bf16 v[84:87], v[180:183], v[230:233], v[84:87]
	v_mfma_f32_16x16x32_bf16 v[80:83], v[188:191], v[230:233], v[80:83]
	v_mfma_f32_16x16x32_bf16 v[68:71], v[180:183], v[238:241], v[68:71]
	v_mfma_f32_16x16x32_bf16 v[64:67], v[188:191], v[238:241], v[64:67]
	v_mfma_f32_16x16x32_bf16 v[116:119], v[184:187], v[218:221], v[116:119]
	v_mfma_f32_16x16x32_bf16 v[112:115], v[210:213], v[218:221], v[112:115]
	v_mfma_f32_16x16x32_bf16 v[100:103], v[184:187], v[226:229], v[100:103]
	v_mfma_f32_16x16x32_bf16 v[96:99], v[210:213], v[226:229], v[96:99]
	v_mfma_f32_16x16x32_bf16 v[84:87], v[184:187], v[234:237], v[84:87]
	v_mfma_f32_16x16x32_bf16 v[80:83], v[210:213], v[234:237], v[80:83]
	v_mfma_f32_16x16x32_bf16 v[68:71], v[184:187], v[242:245], v[68:71]
	v_mfma_f32_16x16x32_bf16 v[64:67], v[210:213], v[242:245], v[64:67]
	s_setprio 0
	s_barrier
; #define PG8_STAGE(bufoff, gbase, voff) do { _Pragma("unroll") for (int _i = 0; _i < 2; ++_i) \
;         __builtin_amdgcn_global_load_lds((const unsigned*)((const char*)(gbase) + (voff)[_i]), (PG8_LAS unsigned*)(lds + (bufoff) + ldsw + _i * 8192), 16, 0, 0); } while (0)
; #define PG8_LDA(dst, b, h) do { _Pragma("unroll") for (int m = 0; m < 4; ++m) _Pragma("unroll") for (int k = 0; k < 2; ++k) dst[m][k] = *(const PG8_LAS bf16x8*)(lds + PG8_SA(b, h) + aoff + m * 2048 + k * 1024); } while (0)
; #define PG8_LDB(dst, b, h) do { _Pragma("unroll") for (int n = 0; n < 2; ++n) _Pragma("unroll") for (int k = 0; k < 2; ++k) dst[n][k] = *(const PG8_LAS bf16x8*)(lds + PG8_SB(b, h) + boff + n * 2048 + k * 1024); } while (0)
; #define PG8_MMA(ai, bj, At, Bt) do { __builtin_amdgcn_s_setprio(1); _Pragma("unroll") for (int m = 0; m < 4; ++m) _Pragma("unroll") for (int n = 0; n < 2; ++n) _Pragma("unroll") for (int k = 0; k < 2; ++k) \
;         acc[ai][bj][m][n] = __builtin_amdgcn_mfma_f32_16x16x32_bf16(Bt[n][k], At[m][k], acc[ai][bj][m][n], 0, 0, 0); __builtin_amdgcn_s_setprio(0); } while (0)
; #define PG8_WAIT_V(n) asm volatile("s_waitcnt vmcnt(" #n ")" ::: "memory")
; #define PG8_WAIT_L(n) asm volatile("s_waitcnt lgkmcnt(" #n ")" ::: "memory")
; #define PG8_BAR __builtin_amdgcn_s_barrier()
; #define PG8_SCHED __builtin_amdgcn_sched_barrier(0)
; template <class Epi, class Sched, bool ALIGN_EPI = false, bool SP2 = false>
; __device__ __forceinline__ void gemm_phase(PG8_LAS unsigned char* lds, const Gemm g, const Sched& S, const Epi& E) {
;     ...
;             PG8_LDA(At, 0, 1); PG8_STAGE(PG8_SB(0, 0), b2, voffB); PG8_STAGE(PG8_SB(0, 1), b2 + hstep, voffB); PG8_STAGE(PG8_SA(0, 0), a2, voffA);
;             PG8_WAIT_V(8); PG8_WAIT_L(0); PG8_BAR; PG8_MMA(1, 0, At, B0); PG8_MMA(1, 1, At, B1); PG8_BAR; PG8_SCHED;
;             PG8_LDB(B0, 1, 0); PG8_LDB(B1, 1, 1); PG8_SCHED; PG8_LDA(At, 1, 0); PG8_STAGE(PG8_SA(0, 1), a2 + hstep, voffA);
	s_mov_b32 m0, s31
	s_add_u32 s56, s2, 0x40000
	s_addc_u32 s57, s3, 0
	ds_read_b128 v[214:217], v178 offset:16384
	ds_read_b128 v[218:221], v178 offset:17408
	ds_read_b128 v[222:225], v178 offset:18432
	ds_read_b128 v[226:229], v178 offset:19456
	ds_read_b128 v[230:233], v178 offset:20480
	ds_read_b128 v[234:237], v178 offset:21504
	ds_read_b128 v[238:241], v178 offset:22528
	ds_read_b128 v[242:245], v178 offset:23552
	global_load_lds_dwordx4 v132, s[2:3]
	s_mov_b32 m0, s34
	s_nop 0
	global_load_lds_dwordx4 v128, s[2:3]
	s_mov_b32 m0, s35
	s_nop 0
	global_load_lds_dwordx4 v132, s[56:57]
	s_mov_b32 m0, s40
	s_nop 0
	global_load_lds_dwordx4 v128, s[56:57]
	s_mov_b32 m0, s6
	s_nop 0
	global_load_lds_dwordx4 v134, s[4:5]
	s_mov_b32 m0, s41
	s_nop 0
	global_load_lds_dwordx4 v130, s[4:5]
	s_waitcnt vmcnt(8)
	s_waitcnt lgkmcnt(0)
	s_barrier
	s_setprio 1
	s_waitcnt lgkmcnt(0)
	v_mfma_f32_16x16x32_bf16 v[60:63], v[140:143], v[214:217], v[60:63]
	v_mfma_f32_16x16x32_bf16 v[56:59], v[166:169], v[214:217], v[56:59]
	v_mfma_f32_16x16x32_bf16 v[44:47], v[140:143], v[222:225], v[44:47]
	v_mfma_f32_16x16x32_bf16 v[40:43], v[166:169], v[222:225], v[40:43]
	v_mfma_f32_16x16x32_bf16 v[28:31], v[140:143], v[230:233], v[28:31]
	v_mfma_f32_16x16x32_bf16 v[24:27], v[166:169], v[230:233], v[24:27]
	v_mfma_f32_16x16x32_bf16 v[12:15], v[140:143], v[238:241], v[12:15]
	v_mfma_f32_16x16x32_bf16 v[8:11], v[166:169], v[238:241], v[8:11]
	v_mfma_f32_16x16x32_bf16 v[60:63], v[162:165], v[218:221], v[60:63]
	v_mfma_f32_16x16x32_bf16 v[56:59], v[170:173], v[218:221], v[56:59]
	v_mfma_f32_16x16x32_bf16 v[44:47], v[162:165], v[226:229], v[44:47]
	v_mfma_f32_16x16x32_bf16 v[40:43], v[170:173], v[226:229], v[40:43]
	v_mfma_f32_16x16x32_bf16 v[28:31], v[162:165], v[234:237], v[28:31]
	v_mfma_f32_16x16x32_bf16 v[24:27], v[170:173], v[234:237], v[24:27]
	v_mfma_f32_16x16x32_bf16 v[12:15], v[162:165], v[242:245], v[12:15]
	v_mfma_f32_16x16x32_bf16 v[8:11], v[170:173], v[242:245], v[8:11]
	s_setprio 0
	s_setprio 1
	v_mfma_f32_16x16x32_bf16 v[52:55], v[180:183], v[214:217], v[52:55]
	v_mfma_f32_16x16x32_bf16 v[48:51], v[188:191], v[214:217], v[48:51]
	v_mfma_f32_16x16x32_bf16 v[36:39], v[180:183], v[222:225], v[36:39]
	v_mfma_f32_16x16x32_bf16 v[32:35], v[188:191], v[222:225], v[32:35]
	v_mfma_f32_16x16x32_bf16 v[20:23], v[180:183], v[230:233], v[20:23]
	v_mfma_f32_16x16x32_bf16 v[16:19], v[188:191], v[230:233], v[16:19]
	v_mfma_f32_16x16x32_bf16 v[4:7], v[180:183], v[238:241], v[4:7]
	v_mfma_f32_16x16x32_bf16 v[0:3], v[188:191], v[238:241], v[0:3]
	v_mfma_f32_16x16x32_bf16 v[52:55], v[184:187], v[218:221], v[52:55]
	v_mfma_f32_16x16x32_bf16 v[48:51], v[210:213], v[218:221], v[48:51]
	v_mfma_f32_16x16x32_bf16 v[36:39], v[184:187], v[226:229], v[36:39]
	v_mfma_f32_16x16x32_bf16 v[32:35], v[210:213], v[226:229], v[32:35]
	v_mfma_f32_16x16x32_bf16 v[20:23], v[184:187], v[234:237], v[20:23]
	v_mfma_f32_16x16x32_bf16 v[16:19], v[210:213], v[234:237], v[16:19]
	v_mfma_f32_16x16x32_bf16 v[4:7], v[184:187], v[242:245], v[4:7]
	v_mfma_f32_16x16x32_bf16 v[0:3], v[210:213], v[242:245], v[0:3]
	s_setprio 0
	s_barrier
	ds_read_b128 v[140:143], v254 offset:32768
	ds_read_b128 v[162:165], v254 offset:33792
	ds_read_b128 v[166:169], v254 offset:34816
	ds_read_b128 v[170:173], v254 offset:35840
	ds_read_b128 v[180:183], v254 offset:49152
	ds_read_b128 v[184:187], v254 offset:50176
	ds_read_b128 v[188:191], v254 offset:51200
	ds_read_b128 v[210:213], v254 offset:52224
	s_add_u32 s4, s4, 0x40000
	s_addc_u32 s5, s5, 0
	s_mov_b32 m0, s42
	ds_read_b128 v[214:217], v178 offset:32768
	ds_read_b128 v[218:221], v178 offset:33792
	ds_read_b128 v[222:225], v178 offset:34816
	ds_read_b128 v[226:229], v178 offset:35840
	ds_read_b128 v[230:233], v178 offset:36864
	ds_read_b128 v[234:237], v178 offset:37888
	ds_read_b128 v[238:241], v178 offset:38912
	ds_read_b128 v[242:245], v178 offset:39936
	global_load_lds_dwordx4 v134, s[4:5]
	s_mov_b32 m0, s43
	s_nop 0
	global_load_lds_dwordx4 v130, s[4:5]
	s_waitcnt vmcnt(8)
	s_waitcnt lgkmcnt(0)
	s_barrier
; #define PG8_STAGE(bufoff, gbase, voff) do { _Pragma("unroll") for (int _i = 0; _i < 2; ++_i) \
;         __builtin_amdgcn_global_load_lds((const unsigned*)((const char*)(gbase) + (voff)[_i]), (PG8_LAS unsigned*)(lds + (bufoff) + ldsw + _i * 8192), 16, 0, 0); } while (0)
; #define PG8_LDA(dst, b, h) do { _Pragma("unroll") for (int m = 0; m < 4; ++m) _Pragma("unroll") for (int k = 0; k < 2; ++k) dst[m][k] = *(const PG8_LAS bf16x8*)(lds + PG8_SA(b, h) + aoff + m * 2048 + k * 1024); } while (0)
; #define PG8_MMA(ai, bj, At, Bt) do { __builtin_amdgcn_s_setprio(1); _Pragma("unroll") for (int m = 0; m < 4; ++m) _Pragma("unroll") for (int n = 0; n < 2; ++n) _Pragma("unroll") for (int k = 0; k < 2; ++k) \
;         acc[ai][bj][m][n] = __builtin_amdgcn_mfma_f32_16x16x32_bf16(Bt[n][k], At[m][k], acc[ai][bj][m][n], 0, 0, 0); __builtin_amdgcn_s_setprio(0); } while (0)
; #define PG8_WAIT_V(n) asm volatile("s_waitcnt vmcnt(" #n ")" ::: "memory")
; #define PG8_WAIT_L(n) asm volatile("s_waitcnt lgkmcnt(" #n ")" ::: "memory")
; #define PG8_BAR __builtin_amdgcn_s_barrier()
; #define PG8_SCHED __builtin_amdgcn_sched_barrier(0)
; template <class Epi, class Sched, bool ALIGN_EPI = false, bool SP2 = false>
; __device__ __forceinline__ void gemm_phase(PG8_LAS unsigned char* lds, const Gemm g, const Sched& S, const Epi& E) {
;     ...
;             PG8_WAIT_V(8); PG8_WAIT_L(0); PG8_BAR; PG8_MMA(0, 0, At, B0); PG8_MMA(0, 1, At, B1); PG8_BAR; PG8_SCHED;
;             PG8_LDA(At, 1, 1); PG8_STAGE(PG8_SB(1, 0), b3, voffB); PG8_STAGE(PG8_SB(1, 1), b3 + hstep, voffB); PG8_STAGE(PG8_SA(1, 0), a3, voffA);
;             PG8_WAIT_V(8); PG8_WAIT_L(0); PG8_BAR; PG8_MMA(1, 0, At, B0); PG8_MMA(1, 1, At, B1); PG8_BAR; PG8_SCHED;
;     ...
;         if constexpr (ALIGN_EPI) { if (wr == 0) PG8_BAR; }
	s_setprio 1
	s_waitcnt lgkmcnt(0)
	v_mfma_f32_16x16x32_bf16 v[124:127], v[140:143], v[214:217], v[124:127]
	v_mfma_f32_16x16x32_bf16 v[120:123], v[166:169], v[214:217], v[120:123]
	v_mfma_f32_16x16x32_bf16 v[108:111], v[140:143], v[222:225], v[108:111]
	v_mfma_f32_16x16x32_bf16 v[104:107], v[166:169], v[222:225], v[104:107]
	v_mfma_f32_16x16x32_bf16 v[92:95], v[140:143], v[230:233], v[92:95]
	v_mfma_f32_16x16x32_bf16 v[88:91], v[166:169], v[230:233], v[88:91]
	v_mfma_f32_16x16x32_bf16 v[76:79], v[140:143], v[238:241], v[76:79]
	v_mfma_f32_16x16x32_bf16 v[72:75], v[166:169], v[238:241], v[72:75]
	v_mfma_f32_16x16x32_bf16 v[124:127], v[162:165], v[218:221], v[124:127]
	v_mfma_f32_16x16x32_bf16 v[120:123], v[170:173], v[218:221], v[120:123]
	v_mfma_f32_16x16x32_bf16 v[108:111], v[162:165], v[226:229], v[108:111]
	v_mfma_f32_16x16x32_bf16 v[104:107], v[170:173], v[226:229], v[104:107]
	v_mfma_f32_16x16x32_bf16 v[92:95], v[162:165], v[234:237], v[92:95]
	v_mfma_f32_16x16x32_bf16 v[88:91], v[170:173], v[234:237], v[88:91]
	v_mfma_f32_16x16x32_bf16 v[76:79], v[162:165], v[242:245], v[76:79]
	v_mfma_f32_16x16x32_bf16 v[72:75], v[170:173], v[242:245], v[72:75]
	s_setprio 0
	s_setprio 1
	v_mfma_f32_16x16x32_bf16 v[116:119], v[180:183], v[214:217], v[116:119]
	v_mfma_f32_16x16x32_bf16 v[112:115], v[188:191], v[214:217], v[112:115]
	v_mfma_f32_16x16x32_bf16 v[100:103], v[180:183], v[222:225], v[100:103]
	v_mfma_f32_16x16x32_bf16 v[96:99], v[188:191], v[222:225], v[96:99]
	v_mfma_f32_16x16x32_bf16 v[84:87], v[180:183], v[230:233], v[84:87]
	v_mfma_f32_16x16x32_bf16 v[80:83], v[188:191], v[230:233], v[80:83]
	v_mfma_f32_16x16x32_bf16 v[68:71], v[180:183], v[238:241], v[68:71]
	v_mfma_f32_16x16x32_bf16 v[64:67], v[188:191], v[238:241], v[64:67]
	v_mfma_f32_16x16x32_bf16 v[116:119], v[184:187], v[218:221], v[116:119]
	v_mfma_f32_16x16x32_bf16 v[112:115], v[210:213], v[218:221], v[112:115]
	v_mfma_f32_16x16x32_bf16 v[100:103], v[184:187], v[226:229], v[100:103]
	v_mfma_f32_16x16x32_bf16 v[96:99], v[210:213], v[226:229], v[96:99]
	v_mfma_f32_16x16x32_bf16 v[84:87], v[184:187], v[234:237], v[84:87]
	v_mfma_f32_16x16x32_bf16 v[80:83], v[210:213], v[234:237], v[80:83]
	v_mfma_f32_16x16x32_bf16 v[68:71], v[184:187], v[242:245], v[68:71]
	v_mfma_f32_16x16x32_bf16 v[64:67], v[210:213], v[242:245], v[64:67]
	s_setprio 0
	s_barrier
	s_mov_b32 m0, s48
	s_add_u32 s2, s2, 0x40080
	s_addc_u32 s3, s3, 0
	ds_read_b128 v[214:217], v178 offset:49152
	ds_read_b128 v[218:221], v178 offset:50176
	ds_read_b128 v[222:225], v178 offset:51200
	ds_read_b128 v[226:229], v178 offset:52224
	ds_read_b128 v[230:233], v178 offset:53248
	ds_read_b128 v[234:237], v178 offset:54272
	ds_read_b128 v[238:241], v178 offset:55296
	ds_read_b128 v[242:245], v178 offset:56320
	s_add_u32 s98, s2, 0xfffc0000
	s_addc_u32 s99, s3, -1
	global_load_lds_dwordx4 v132, s[98:99]
	s_mov_b32 m0, s49
	s_nop 0
	global_load_lds_dwordx4 v128, s[98:99]
	s_mov_b32 m0, s52
	s_nop 0
	global_load_lds_dwordx4 v132, s[2:3]
	s_mov_b32 m0, s53
	s_nop 0
	global_load_lds_dwordx4 v128, s[2:3]
	s_mov_b32 m0, s50
	s_nop 0
	s_add_u32 s100, s4, 0xfffc0080
	s_addc_u32 s101, s5, -1
	global_load_lds_dwordx4 v134, s[100:101]
	s_mov_b32 m0, s51
	s_nop 0
	global_load_lds_dwordx4 v130, s[100:101]
	s_waitcnt vmcnt(8)
	s_waitcnt lgkmcnt(0)
	s_barrier
	s_setprio 1
	s_waitcnt lgkmcnt(0)
	v_mfma_f32_16x16x32_bf16 v[60:63], v[140:143], v[214:217], v[60:63]
	v_mfma_f32_16x16x32_bf16 v[56:59], v[166:169], v[214:217], v[56:59]
	v_mfma_f32_16x16x32_bf16 v[44:47], v[140:143], v[222:225], v[44:47]
	v_mfma_f32_16x16x32_bf16 v[40:43], v[166:169], v[222:225], v[40:43]
	v_mfma_f32_16x16x32_bf16 v[28:31], v[140:143], v[230:233], v[28:31]
	v_mfma_f32_16x16x32_bf16 v[24:27], v[166:169], v[230:233], v[24:27]
	v_mfma_f32_16x16x32_bf16 v[12:15], v[140:143], v[238:241], v[12:15]
	v_mfma_f32_16x16x32_bf16 v[8:11], v[166:169], v[238:241], v[8:11]
	v_mfma_f32_16x16x32_bf16 v[60:63], v[162:165], v[218:221], v[60:63]
	v_mfma_f32_16x16x32_bf16 v[56:59], v[170:173], v[218:221], v[56:59]
	v_mfma_f32_16x16x32_bf16 v[44:47], v[162:165], v[226:229], v[44:47]
	v_mfma_f32_16x16x32_bf16 v[40:43], v[170:173], v[226:229], v[40:43]
	v_mfma_f32_16x16x32_bf16 v[28:31], v[162:165], v[234:237], v[28:31]
	v_mfma_f32_16x16x32_bf16 v[24:27], v[170:173], v[234:237], v[24:27]
	v_mfma_f32_16x16x32_bf16 v[12:15], v[162:165], v[242:245], v[12:15]
	v_mfma_f32_16x16x32_bf16 v[8:11], v[170:173], v[242:245], v[8:11]
	s_setprio 0
	s_setprio 1
	v_mfma_f32_16x16x32_bf16 v[52:55], v[180:183], v[214:217], v[52:55]
	v_mfma_f32_16x16x32_bf16 v[48:51], v[188:191], v[214:217], v[48:51]
	v_mfma_f32_16x16x32_bf16 v[36:39], v[180:183], v[222:225], v[36:39]
	v_mfma_f32_16x16x32_bf16 v[32:35], v[188:191], v[222:225], v[32:35]
	v_mfma_f32_16x16x32_bf16 v[20:23], v[180:183], v[230:233], v[20:23]
	v_mfma_f32_16x16x32_bf16 v[16:19], v[188:191], v[230:233], v[16:19]
	v_mfma_f32_16x16x32_bf16 v[4:7], v[180:183], v[238:241], v[4:7]
	v_mfma_f32_16x16x32_bf16 v[0:3], v[188:191], v[238:241], v[0:3]
	v_mfma_f32_16x16x32_bf16 v[52:55], v[184:187], v[218:221], v[52:55]
	v_mfma_f32_16x16x32_bf16 v[48:51], v[210:213], v[218:221], v[48:51]
	v_mfma_f32_16x16x32_bf16 v[36:39], v[184:187], v[226:229], v[36:39]
	v_mfma_f32_16x16x32_bf16 v[32:35], v[210:213], v[226:229], v[32:35]
	v_mfma_f32_16x16x32_bf16 v[20:23], v[184:187], v[234:237], v[20:23]
	v_mfma_f32_16x16x32_bf16 v[16:19], v[210:213], v[234:237], v[16:19]
	v_mfma_f32_16x16x32_bf16 v[4:7], v[184:187], v[242:245], v[4:7]
	v_mfma_f32_16x16x32_bf16 v[0:3], v[210:213], v[242:245], v[0:3]
	s_setprio 0
	s_barrier
	s_add_i32 s55, s55, 2
	s_add_u32 s0, s0, 0x100
	s_addc_u32 s1, s1, 0
	s_add_u32 s38, s38, 0x100
	s_addc_u32 s39, s39, 0
	s_cmp_gt_u32 s55, 13
	s_cbranch_scc0 .LBB0_749
	s_and_b64 vcc, exec, s[18:19]
	s_cbranch_vccz .LBB0_752
	s_barrier

; #define PG8_STAGE(bufoff, gbase, voff) do { _Pragma("unroll") for (int _i = 0; _i < 2; ++_i) \
;         __builtin_amdgcn_global_load_lds((const unsigned*)((const char*)(gbase) + (voff)[_i]), (PG8_LAS unsigned*)(lds + (bufoff) + ldsw + _i * 8192), 16, 0, 0); } while (0)
; #define PG8_LDA(dst, b, h) do { _Pragma("unroll") for (int m = 0; m < 4; ++m) _Pragma("unroll") for (int k = 0; k < 2; ++k) dst[m][k] = *(const PG8_LAS bf16x8*)(lds + PG8_SA(b, h) + aoff + m * 2048 + k * 1024); } while (0)
; #define PG8_LDB(dst, b, h) do { _Pragma("unroll") for (int n = 0; n < 2; ++n) _Pragma("unroll") for (int k = 0; k < 2; ++k) dst[n][k] = *(const PG8_LAS bf16x8*)(lds + PG8_SB(b, h) + boff + n * 2048 + k * 1024); } while (0)
; #define PG8_MMA(ai, bj, At, Bt) do { __builtin_amdgcn_s_setprio(1); _Pragma("unroll") for (int m = 0; m < 4; ++m) _Pragma("unroll") for (int n = 0; n < 2; ++n) _Pragma("unroll") for (int k = 0; k < 2; ++k) \
;         acc[ai][bj][m][n] = __builtin_amdgcn_mfma_f32_16x16x32_bf16(Bt[n][k], At[m][k], acc[ai][bj][m][n], 0, 0, 0); __builtin_amdgcn_s_setprio(0); } while (0)
; #define PG8_BAR __builtin_amdgcn_s_barrier()
; template <class Epi, class Sched, bool ALIGN_EPI = false, bool SP2 = false>
; __device__ __forceinline__ void gemm_phase(PG8_LAS unsigned char* lds, const Gemm g, const Sched& S, const Epi& E) {
;     ...
;         const bool has_next = S.next(ui + 1, nxt);
;         const char* nA = has_next ? (const char*)g.A + (size_t)nxt.pm * tstep : cA; const char* nB = has_next ? (const char*)g.Bt + (size_t)nxt.pn * tstep : cB;
;         for (int t = 0; t < nt; t += 2) {
;             const bool last = (t == nt - 2);
;             const char* a1 = cA + (size_t)(t + 1) * kstep;
;             const char* a2 = last ? nA : cA + (size_t)(t + 2) * kstep; const char* b2 = last ? nB : cB + (size_t)(t + 2) * kstep;
;             const char* a3 = a2 + kstep; const char* b3 = b2 + kstep;
;             if (last && has_next) S.a_ready(nxt);
;             if constexpr (SP2) {
;             PG8_LDB(B0, 0, 0); PG8_LDB(B1, 0, 1); PG8_SCHED; PG8_LDA(At, 0, 0); PG8_STAGE(PG8_SA(1, 1), a1 + hstep, voffA);
;             PG8_WAIT_V(8); PG8_WAIT_L(0); PG8_BAR; PG8_MMA(0, 0, At, B0); PG8_MMA(0, 1, At, B1); PG8_BAR; PG8_SCHED;
;             PG8_LDA(At, 0, 1); PG8_STAGE(PG8_SB(0, 0), b2, voffB); PG8_STAGE(PG8_SB(0, 1), b2 + hstep, voffB); PG8_STAGE(PG8_SA(0, 0), a2, voffA);
.LBB0_791:
	s_ashr_i32 s17, s16, 31
	s_lshl_b64 s[4:5], s[16:17], 19
	s_add_u32 s18, s7, s4
	s_addc_u32 s19, s24, s5
	s_and_b64 s[4:5], s[8:9], exec
	s_cselect_b32 s17, s19, s1
	s_cselect_b32 s48, s18, s0
	s_ashr_i32 s15, s14, 31
	s_lshl_b64 s[4:5], s[14:15], 19
	s_add_u32 s22, s25, s4
	s_addc_u32 s23, s26, s5
	s_and_b64 s[4:5], s[8:9], exec
	s_cselect_b32 s15, s23, s3
	s_cselect_b32 s49, s22, s2
	s_add_u32 s0, s0, 0x40080
	s_addc_u32 s1, s1, 0
	s_add_u32 s50, s2, 0x100
	v_mov_b32_e32 v0, 0
	s_addc_u32 s51, s3, 0
	s_mov_b32 s52, -2
	v_add_u32_e32 v254, 0x10000, v174
.Labi_peel:
	s_waitcnt lgkmcnt(0)
	ds_read_b128 v[140:143], v254
	ds_read_b128 v[162:165], v254 offset:1024
	ds_read_b128 v[166:169], v254 offset:2048
	ds_read_b128 v[176:179], v254 offset:3072
	ds_read_b128 v[180:183], v254 offset:16384
	ds_read_b128 v[184:187], v254 offset:17408
	ds_read_b128 v[188:191], v254 offset:18432
	ds_read_b128 v[210:213], v254 offset:19456
	s_add_u32 s2, s0, 0xfffc0080
	s_addc_u32 s3, s1, -1
	s_cmp_eq_u32 s52, 12
	s_cselect_b32 s5, s17, s3
	s_cselect_b32 s4, s48, s2
	s_cselect_b32 s3, s15, s51
	s_cselect_b32 s2, s49, s50
	s_add_i32 m0, s6, 0xc000
	ds_read_b128 v[214:217], v173
	ds_read_b128 v[218:221], v173 offset:1024
	ds_read_b128 v[222:225], v173 offset:2048
	ds_read_b128 v[226:229], v173 offset:3072
	ds_read_b128 v[230:233], v173 offset:4096
	ds_read_b128 v[234:237], v173 offset:5120
	ds_read_b128 v[238:241], v173 offset:6144
	ds_read_b128 v[242:245], v173 offset:7168
	global_load_lds_dwordx4 v136, s[0:1]
	s_add_i32 m0, s6, 0xe000
	s_nop 0
	global_load_lds_dwordx4 v138, s[0:1]
	s_waitcnt vmcnt(8)
	s_waitcnt lgkmcnt(0)
	s_barrier
	s_setprio 1
	s_waitcnt lgkmcnt(0)
	v_mfma_f32_16x16x32_bf16 v[124:127], v[140:143], v[214:217], 0
	v_mfma_f32_16x16x32_bf16 v[120:123], v[166:169], v[214:217], 0
	v_mfma_f32_16x16x32_bf16 v[112:115], v[140:143], v[222:225], 0
	v_mfma_f32_16x16x32_bf16 v[104:107], v[166:169], v[222:225], 0
	v_mfma_f32_16x16x32_bf16 v[96:99], v[140:143], v[230:233], 0
	v_mfma_f32_16x16x32_bf16 v[88:91], v[166:169], v[230:233], 0
	v_mfma_f32_16x16x32_bf16 v[80:83], v[140:143], v[238:241], 0
	v_mfma_f32_16x16x32_bf16 v[72:75], v[166:169], v[238:241], 0
	v_mfma_f32_16x16x32_bf16 v[124:127], v[162:165], v[218:221], v[124:127]
	v_mfma_f32_16x16x32_bf16 v[120:123], v[176:179], v[218:221], v[120:123]
	v_mfma_f32_16x16x32_bf16 v[112:115], v[162:165], v[226:229], v[112:115]
	v_mfma_f32_16x16x32_bf16 v[104:107], v[176:179], v[226:229], v[104:107]
	v_mfma_f32_16x16x32_bf16 v[96:99], v[162:165], v[234:237], v[96:99]
	v_mfma_f32_16x16x32_bf16 v[88:91], v[176:179], v[234:237], v[88:91]
	v_mfma_f32_16x16x32_bf16 v[80:83], v[162:165], v[242:245], v[80:83]
	v_mfma_f32_16x16x32_bf16 v[72:75], v[176:179], v[242:245], v[72:75]
	s_setprio 0
	s_setprio 1
	v_mfma_f32_16x16x32_bf16 v[116:119], v[180:183], v[214:217], 0
	v_mfma_f32_16x16x32_bf16 v[108:111], v[188:191], v[214:217], 0
	v_mfma_f32_16x16x32_bf16 v[100:103], v[180:183], v[222:225], 0
	v_mfma_f32_16x16x32_bf16 v[92:95], v[188:191], v[222:225], 0
	v_mfma_f32_16x16x32_bf16 v[84:87], v[180:183], v[230:233], 0
	v_mfma_f32_16x16x32_bf16 v[76:79], v[188:191], v[230:233], 0
	v_mfma_f32_16x16x32_bf16 v[68:71], v[180:183], v[238:241], 0
	v_mfma_f32_16x16x32_bf16 v[64:67], v[188:191], v[238:241], 0
	v_mfma_f32_16x16x32_bf16 v[116:119], v[184:187], v[218:221], v[116:119]
	v_mfma_f32_16x16x32_bf16 v[108:111], v[210:213], v[218:221], v[108:111]
	v_mfma_f32_16x16x32_bf16 v[100:103], v[184:187], v[226:229], v[100:103]
	v_mfma_f32_16x16x32_bf16 v[92:95], v[210:213], v[226:229], v[92:95]
	v_mfma_f32_16x16x32_bf16 v[84:87], v[184:187], v[234:237], v[84:87]
	v_mfma_f32_16x16x32_bf16 v[76:79], v[210:213], v[234:237], v[76:79]
	v_mfma_f32_16x16x32_bf16 v[68:71], v[184:187], v[242:245], v[68:71]
	v_mfma_f32_16x16x32_bf16 v[64:67], v[210:213], v[242:245], v[64:67]
	s_setprio 0
	s_barrier
	s_mov_b32 m0, s27
	s_add_u32 s54, s2, 0x40000
	s_addc_u32 s55, s3, 0
	ds_read_b128 v[214:217], v173 offset:16384
	ds_read_b128 v[218:221], v173 offset:17408
	ds_read_b128 v[222:225], v173 offset:18432
	ds_read_b128 v[226:229], v173 offset:19456
	ds_read_b128 v[230:233], v173 offset:20480
	ds_read_b128 v[234:237], v173 offset:21504
	ds_read_b128 v[238:241], v173 offset:22528
	ds_read_b128 v[242:245], v173 offset:23552
	global_load_lds_dwordx4 v132, s[2:3]
	s_mov_b32 m0, s28
	s_nop 0
	global_load_lds_dwordx4 v128, s[2:3]
	s_mov_b32 m0, s29
	s_nop 0
	global_load_lds_dwordx4 v132, s[54:55]
	s_mov_b32 m0, s30
	s_nop 0
	global_load_lds_dwordx4 v128, s[54:55]
	s_mov_b32 m0, s6
	s_nop 0
	global_load_lds_dwordx4 v134, s[4:5]
	s_mov_b32 m0, s31
	s_nop 0
	global_load_lds_dwordx4 v130, s[4:5]
	s_waitcnt vmcnt(8)
	s_waitcnt lgkmcnt(0)
	s_barrier
; #define PG8_STAGE(bufoff, gbase, voff) do { _Pragma("unroll") for (int _i = 0; _i < 2; ++_i) \
;         __builtin_amdgcn_global_load_lds((const unsigned*)((const char*)(gbase) + (voff)[_i]), (PG8_LAS unsigned*)(lds + (bufoff) + ldsw + _i * 8192), 16, 0, 0); } while (0)
; #define PG8_LDA(dst, b, h) do { _Pragma("unroll") for (int m = 0; m < 4; ++m) _Pragma("unroll") for (int k = 0; k < 2; ++k) dst[m][k] = *(const PG8_LAS bf16x8*)(lds + PG8_SA(b, h) + aoff + m * 2048 + k * 1024); } while (0)
; #define PG8_LDB(dst, b, h) do { _Pragma("unroll") for (int n = 0; n < 2; ++n) _Pragma("unroll") for (int k = 0; k < 2; ++k) dst[n][k] = *(const PG8_LAS bf16x8*)(lds + PG8_SB(b, h) + boff + n * 2048 + k * 1024); } while (0)
; #define PG8_MMA(ai, bj, At, Bt) do { __builtin_amdgcn_s_setprio(1); _Pragma("unroll") for (int m = 0; m < 4; ++m) _Pragma("unroll") for (int n = 0; n < 2; ++n) _Pragma("unroll") for (int k = 0; k < 2; ++k) \
;         acc[ai][bj][m][n] = __builtin_amdgcn_mfma_f32_16x16x32_bf16(Bt[n][k], At[m][k], acc[ai][bj][m][n], 0, 0, 0); __builtin_amdgcn_s_setprio(0); } while (0)
; #define PG8_WAIT_V(n) asm volatile("s_waitcnt vmcnt(" #n ")" ::: "memory")
; #define PG8_WAIT_L(n) asm volatile("s_waitcnt lgkmcnt(" #n ")" ::: "memory")
; #define PG8_BAR __builtin_amdgcn_s_barrier()
; #define PG8_SCHED __builtin_amdgcn_sched_barrier(0)
; template <class Epi, class Sched, bool ALIGN_EPI = false, bool SP2 = false>
; __device__ __forceinline__ void gemm_phase(PG8_LAS unsigned char* lds, const Gemm g, const Sched& S, const Epi& E) {
;     ...
;             PG8_WAIT_V(8); PG8_WAIT_L(0); PG8_BAR; PG8_MMA(1, 0, At, B0); PG8_MMA(1, 1, At, B1); PG8_BAR; PG8_SCHED;
;             PG8_LDB(B0, 1, 0); PG8_LDB(B1, 1, 1); PG8_SCHED; PG8_LDA(At, 1, 0); PG8_STAGE(PG8_SA(0, 1), a2 + hstep, voffA);
;             PG8_WAIT_V(8); PG8_WAIT_L(0); PG8_BAR; PG8_MMA(0, 0, At, B0); PG8_MMA(0, 1, At, B1); PG8_BAR; PG8_SCHED;
	s_setprio 1
	s_waitcnt lgkmcnt(0)
	v_mfma_f32_16x16x32_bf16 v[60:63], v[140:143], v[214:217], 0
	v_mfma_f32_16x16x32_bf16 v[56:59], v[166:169], v[214:217], 0
	v_mfma_f32_16x16x32_bf16 v[48:51], v[140:143], v[222:225], 0
	v_mfma_f32_16x16x32_bf16 v[40:43], v[166:169], v[222:225], 0
	v_mfma_f32_16x16x32_bf16 v[32:35], v[140:143], v[230:233], 0
	v_mfma_f32_16x16x32_bf16 v[24:27], v[166:169], v[230:233], 0
	v_mfma_f32_16x16x32_bf16 v[16:19], v[140:143], v[238:241], 0
	v_mfma_f32_16x16x32_bf16 v[8:11], v[166:169], v[238:241], 0
	v_mfma_f32_16x16x32_bf16 v[60:63], v[162:165], v[218:221], v[60:63]
	v_mfma_f32_16x16x32_bf16 v[56:59], v[176:179], v[218:221], v[56:59]
	v_mfma_f32_16x16x32_bf16 v[48:51], v[162:165], v[226:229], v[48:51]
	v_mfma_f32_16x16x32_bf16 v[40:43], v[176:179], v[226:229], v[40:43]
	v_mfma_f32_16x16x32_bf16 v[32:35], v[162:165], v[234:237], v[32:35]
	v_mfma_f32_16x16x32_bf16 v[24:27], v[176:179], v[234:237], v[24:27]
	v_mfma_f32_16x16x32_bf16 v[16:19], v[162:165], v[242:245], v[16:19]
	v_mfma_f32_16x16x32_bf16 v[8:11], v[176:179], v[242:245], v[8:11]
	s_setprio 0
	s_setprio 1
	v_mfma_f32_16x16x32_bf16 v[52:55], v[180:183], v[214:217], 0
	v_mfma_f32_16x16x32_bf16 v[44:47], v[188:191], v[214:217], 0
	v_mfma_f32_16x16x32_bf16 v[36:39], v[180:183], v[222:225], 0
	v_mfma_f32_16x16x32_bf16 v[28:31], v[188:191], v[222:225], 0
	v_mfma_f32_16x16x32_bf16 v[20:23], v[180:183], v[230:233], 0
	v_mfma_f32_16x16x32_bf16 v[12:15], v[188:191], v[230:233], 0
	v_mfma_f32_16x16x32_bf16 v[4:7], v[180:183], v[238:241], 0
	v_mfma_f32_16x16x32_bf16 v[0:3], v[188:191], v[238:241], 0
	v_mfma_f32_16x16x32_bf16 v[52:55], v[184:187], v[218:221], v[52:55]
	v_mfma_f32_16x16x32_bf16 v[44:47], v[210:213], v[218:221], v[44:47]
	v_mfma_f32_16x16x32_bf16 v[36:39], v[184:187], v[226:229], v[36:39]
	v_mfma_f32_16x16x32_bf16 v[28:31], v[210:213], v[226:229], v[28:31]
	v_mfma_f32_16x16x32_bf16 v[20:23], v[184:187], v[234:237], v[20:23]
	v_mfma_f32_16x16x32_bf16 v[12:15], v[210:213], v[234:237], v[12:15]
	v_mfma_f32_16x16x32_bf16 v[4:7], v[184:187], v[242:245], v[4:7]
	v_mfma_f32_16x16x32_bf16 v[0:3], v[210:213], v[242:245], v[0:3]
	s_setprio 0
	s_barrier
	ds_read_b128 v[140:143], v254 offset:32768
	ds_read_b128 v[162:165], v254 offset:33792
	ds_read_b128 v[166:169], v254 offset:34816
	ds_read_b128 v[176:179], v254 offset:35840
	ds_read_b128 v[180:183], v254 offset:49152
	ds_read_b128 v[184:187], v254 offset:50176
	ds_read_b128 v[188:191], v254 offset:51200
	ds_read_b128 v[210:213], v254 offset:52224
	s_add_u32 s4, s4, 0x40000
	s_addc_u32 s5, s5, 0
	s_mov_b32 m0, s33
	ds_read_b128 v[214:217], v173 offset:32768
	ds_read_b128 v[218:221], v173 offset:33792
	ds_read_b128 v[222:225], v173 offset:34816
	ds_read_b128 v[226:229], v173 offset:35840
	ds_read_b128 v[230:233], v173 offset:36864
	ds_read_b128 v[234:237], v173 offset:37888
	ds_read_b128 v[238:241], v173 offset:38912
	ds_read_b128 v[242:245], v173 offset:39936
	global_load_lds_dwordx4 v134, s[4:5]
	s_mov_b32 m0, s34
	s_nop 0
	global_load_lds_dwordx4 v130, s[4:5]
	s_waitcnt vmcnt(8)
	s_waitcnt lgkmcnt(0)
	s_barrier
	s_setprio 1
	s_waitcnt lgkmcnt(0)
	v_mfma_f32_16x16x32_bf16 v[124:127], v[140:143], v[214:217], v[124:127]
	v_mfma_f32_16x16x32_bf16 v[120:123], v[166:169], v[214:217], v[120:123]
	v_mfma_f32_16x16x32_bf16 v[112:115], v[140:143], v[222:225], v[112:115]
	v_mfma_f32_16x16x32_bf16 v[104:107], v[166:169], v[222:225], v[104:107]
	v_mfma_f32_16x16x32_bf16 v[96:99], v[140:143], v[230:233], v[96:99]
	v_mfma_f32_16x16x32_bf16 v[88:91], v[166:169], v[230:233], v[88:91]
	v_mfma_f32_16x16x32_bf16 v[80:83], v[140:143], v[238:241], v[80:83]
	v_mfma_f32_16x16x32_bf16 v[72:75], v[166:169], v[238:241], v[72:75]
	v_mfma_f32_16x16x32_bf16 v[124:127], v[162:165], v[218:221], v[124:127]
	v_mfma_f32_16x16x32_bf16 v[120:123], v[176:179], v[218:221], v[120:123]
	v_mfma_f32_16x16x32_bf16 v[112:115], v[162:165], v[226:229], v[112:115]
	v_mfma_f32_16x16x32_bf16 v[104:107], v[176:179], v[226:229], v[104:107]
	v_mfma_f32_16x16x32_bf16 v[96:99], v[162:165], v[234:237], v[96:99]
	v_mfma_f32_16x16x32_bf16 v[88:91], v[176:179], v[234:237], v[88:91]
	v_mfma_f32_16x16x32_bf16 v[80:83], v[162:165], v[242:245], v[80:83]
	v_mfma_f32_16x16x32_bf16 v[72:75], v[176:179], v[242:245], v[72:75]
	s_setprio 0
	s_setprio 1
	v_mfma_f32_16x16x32_bf16 v[116:119], v[180:183], v[214:217], v[116:119]
	v_mfma_f32_16x16x32_bf16 v[108:111], v[188:191], v[214:217], v[108:111]
	v_mfma_f32_16x16x32_bf16 v[100:103], v[180:183], v[222:225], v[100:103]
	v_mfma_f32_16x16x32_bf16 v[92:95], v[188:191], v[222:225], v[92:95]
	v_mfma_f32_16x16x32_bf16 v[84:87], v[180:183], v[230:233], v[84:87]
	v_mfma_f32_16x16x32_bf16 v[76:79], v[188:191], v[230:233], v[76:79]
	v_mfma_f32_16x16x32_bf16 v[68:71], v[180:183], v[238:241], v[68:71]
	v_mfma_f32_16x16x32_bf16 v[64:67], v[188:191], v[238:241], v[64:67]
	v_mfma_f32_16x16x32_bf16 v[116:119], v[184:187], v[218:221], v[116:119]
	v_mfma_f32_16x16x32_bf16 v[108:111], v[210:213], v[218:221], v[108:111]
	v_mfma_f32_16x16x32_bf16 v[100:103], v[184:187], v[226:229], v[100:103]
	v_mfma_f32_16x16x32_bf16 v[92:95], v[210:213], v[226:229], v[92:95]
	v_mfma_f32_16x16x32_bf16 v[84:87], v[184:187], v[234:237], v[84:87]
	v_mfma_f32_16x16x32_bf16 v[76:79], v[210:213], v[234:237], v[76:79]
	v_mfma_f32_16x16x32_bf16 v[68:71], v[184:187], v[242:245], v[68:71]
	v_mfma_f32_16x16x32_bf16 v[64:67], v[210:213], v[242:245], v[64:67]
	s_setprio 0
	s_barrier
; #define PG8_STAGE(bufoff, gbase, voff) do { _Pragma("unroll") for (int _i = 0; _i < 2; ++_i) \
;         __builtin_amdgcn_global_load_lds((const unsigned*)((const char*)(gbase) + (voff)[_i]), (PG8_LAS unsigned*)(lds + (bufoff) + ldsw + _i * 8192), 16, 0, 0); } while (0)
; #define PG8_LDA(dst, b, h) do { _Pragma("unroll") for (int m = 0; m < 4; ++m) _Pragma("unroll") for (int k = 0; k < 2; ++k) dst[m][k] = *(const PG8_LAS bf16x8*)(lds + PG8_SA(b, h) + aoff + m * 2048 + k * 1024); } while (0)
; #define PG8_LDB(dst, b, h) do { _Pragma("unroll") for (int n = 0; n < 2; ++n) _Pragma("unroll") for (int k = 0; k < 2; ++k) dst[n][k] = *(const PG8_LAS bf16x8*)(lds + PG8_SB(b, h) + boff + n * 2048 + k * 1024); } while (0)
; #define PG8_MMA(ai, bj, At, Bt) do { __builtin_amdgcn_s_setprio(1); _Pragma("unroll") for (int m = 0; m < 4; ++m) _Pragma("unroll") for (int n = 0; n < 2; ++n) _Pragma("unroll") for (int k = 0; k < 2; ++k) \
;         acc[ai][bj][m][n] = __builtin_amdgcn_mfma_f32_16x16x32_bf16(Bt[n][k], At[m][k], acc[ai][bj][m][n], 0, 0, 0); __builtin_amdgcn_s_setprio(0); } while (0)
; #define PG8_WAIT_V(n) asm volatile("s_waitcnt vmcnt(" #n ")" ::: "memory")
; #define PG8_WAIT_L(n) asm volatile("s_waitcnt lgkmcnt(" #n ")" ::: "memory")
; #define PG8_BAR __builtin_amdgcn_s_barrier()
; #define PG8_SCHED __builtin_amdgcn_sched_barrier(0)
; template <class Epi, class Sched, bool ALIGN_EPI = false, bool SP2 = false>
; __device__ __forceinline__ void gemm_phase(PG8_LAS unsigned char* lds, const Gemm g, const Sched& S, const Epi& E) {
;     ...
;             PG8_LDB(B0, 0, 0); PG8_LDB(B1, 0, 1); PG8_SCHED; PG8_LDA(At, 0, 0); PG8_STAGE(PG8_SA(1, 1), a1 + hstep, voffA);
;             PG8_WAIT_V(8); PG8_WAIT_L(0); PG8_BAR; PG8_MMA(0, 0, At, B0); PG8_MMA(0, 1, At, B1); PG8_BAR; PG8_SCHED;
;     ...
;             PG8_LDA(At, 1, 1); PG8_STAGE(PG8_SB(1, 0), b3, voffB); PG8_STAGE(PG8_SB(1, 1), b3 + hstep, voffB); PG8_STAGE(PG8_SA(1, 0), a3, voffA);
;             PG8_WAIT_V(8); PG8_WAIT_L(0); PG8_BAR; PG8_MMA(1, 0, At, B0); PG8_MMA(1, 1, At, B1); PG8_BAR; PG8_SCHED;
	s_mov_b32 m0, s37
	s_add_u32 s2, s2, 0x40080
	s_addc_u32 s3, s3, 0
	ds_read_b128 v[214:217], v173 offset:49152
	ds_read_b128 v[218:221], v173 offset:50176
	ds_read_b128 v[222:225], v173 offset:51200
	ds_read_b128 v[226:229], v173 offset:52224
	ds_read_b128 v[230:233], v173 offset:53248
	ds_read_b128 v[234:237], v173 offset:54272
	ds_read_b128 v[238:241], v173 offset:55296
	ds_read_b128 v[242:245], v173 offset:56320
	s_add_u32 s98, s2, 0xfffc0000
	s_addc_u32 s99, s3, -1
	global_load_lds_dwordx4 v132, s[98:99]
	s_mov_b32 m0, s38
	s_nop 0
	global_load_lds_dwordx4 v128, s[98:99]
	s_mov_b32 m0, s41
	s_nop 0
	global_load_lds_dwordx4 v132, s[2:3]
	s_mov_b32 m0, s42
	s_nop 0
	global_load_lds_dwordx4 v128, s[2:3]
	s_mov_b32 m0, s39
	s_nop 0
	s_add_u32 s100, s4, 0xfffc0080
	s_addc_u32 s101, s5, -1
	global_load_lds_dwordx4 v134, s[100:101]
	s_mov_b32 m0, s40
	s_nop 0
	global_load_lds_dwordx4 v130, s[100:101]
	s_waitcnt vmcnt(8)
	s_waitcnt lgkmcnt(0)
	s_barrier
	s_setprio 1
	s_waitcnt lgkmcnt(0)
	v_mfma_f32_16x16x32_bf16 v[60:63], v[140:143], v[214:217], v[60:63]
	v_mfma_f32_16x16x32_bf16 v[56:59], v[166:169], v[214:217], v[56:59]
	v_mfma_f32_16x16x32_bf16 v[48:51], v[140:143], v[222:225], v[48:51]
	v_mfma_f32_16x16x32_bf16 v[40:43], v[166:169], v[222:225], v[40:43]
	v_mfma_f32_16x16x32_bf16 v[32:35], v[140:143], v[230:233], v[32:35]
	v_mfma_f32_16x16x32_bf16 v[24:27], v[166:169], v[230:233], v[24:27]
	v_mfma_f32_16x16x32_bf16 v[16:19], v[140:143], v[238:241], v[16:19]
	v_mfma_f32_16x16x32_bf16 v[8:11], v[166:169], v[238:241], v[8:11]
	v_mfma_f32_16x16x32_bf16 v[60:63], v[162:165], v[218:221], v[60:63]
	v_mfma_f32_16x16x32_bf16 v[56:59], v[176:179], v[218:221], v[56:59]
	v_mfma_f32_16x16x32_bf16 v[48:51], v[162:165], v[226:229], v[48:51]
	v_mfma_f32_16x16x32_bf16 v[40:43], v[176:179], v[226:229], v[40:43]
	v_mfma_f32_16x16x32_bf16 v[32:35], v[162:165], v[234:237], v[32:35]
	v_mfma_f32_16x16x32_bf16 v[24:27], v[176:179], v[234:237], v[24:27]
	v_mfma_f32_16x16x32_bf16 v[16:19], v[162:165], v[242:245], v[16:19]
	v_mfma_f32_16x16x32_bf16 v[8:11], v[176:179], v[242:245], v[8:11]
	s_setprio 0
	s_setprio 1
	v_mfma_f32_16x16x32_bf16 v[52:55], v[180:183], v[214:217], v[52:55]
	v_mfma_f32_16x16x32_bf16 v[44:47], v[188:191], v[214:217], v[44:47]
	v_mfma_f32_16x16x32_bf16 v[36:39], v[180:183], v[222:225], v[36:39]
	v_mfma_f32_16x16x32_bf16 v[28:31], v[188:191], v[222:225], v[28:31]
	v_mfma_f32_16x16x32_bf16 v[20:23], v[180:183], v[230:233], v[20:23]
	v_mfma_f32_16x16x32_bf16 v[12:15], v[188:191], v[230:233], v[12:15]
	v_mfma_f32_16x16x32_bf16 v[4:7], v[180:183], v[238:241], v[4:7]
	v_mfma_f32_16x16x32_bf16 v[0:3], v[188:191], v[238:241], v[0:3]
	v_mfma_f32_16x16x32_bf16 v[52:55], v[184:187], v[218:221], v[52:55]
	v_mfma_f32_16x16x32_bf16 v[44:47], v[210:213], v[218:221], v[44:47]
	v_mfma_f32_16x16x32_bf16 v[36:39], v[184:187], v[226:229], v[36:39]
	v_mfma_f32_16x16x32_bf16 v[28:31], v[210:213], v[226:229], v[28:31]
	v_mfma_f32_16x16x32_bf16 v[20:23], v[184:187], v[234:237], v[20:23]
	v_mfma_f32_16x16x32_bf16 v[12:15], v[210:213], v[234:237], v[12:15]
	v_mfma_f32_16x16x32_bf16 v[4:7], v[184:187], v[242:245], v[4:7]
	v_mfma_f32_16x16x32_bf16 v[0:3], v[210:213], v[242:245], v[0:3]
	s_setprio 0
	s_barrier
	s_add_i32 s52, s52, 2
	s_add_u32 s0, s0, 0x100
	s_addc_u32 s1, s1, 0
	s_add_u32 s50, s50, 0x100
	s_addc_u32 s51, s51, 0
	s_cmp_gt_u32 s52, 13
.LBB0_792:
	s_waitcnt lgkmcnt(0)
	ds_read_b128 v[140:143], v254
	ds_read_b128 v[162:165], v254 offset:1024
	ds_read_b128 v[166:169], v254 offset:2048
	ds_read_b128 v[176:179], v254 offset:3072
	ds_read_b128 v[180:183], v254 offset:16384
	ds_read_b128 v[184:187], v254 offset:17408
	ds_read_b128 v[188:191], v254 offset:18432
	ds_read_b128 v[210:213], v254 offset:19456
	s_add_u32 s2, s0, 0xfffc0080
	s_addc_u32 s3, s1, -1
	s_cmp_eq_u32 s52, 12
	s_cselect_b32 s5, s17, s3
	s_cselect_b32 s4, s48, s2
	s_cselect_b32 s3, s15, s51
	s_cselect_b32 s2, s49, s50
	s_add_i32 m0, s6, 0xc000
	ds_read_b128 v[214:217], v173
	ds_read_b128 v[218:221], v173 offset:1024
	ds_read_b128 v[222:225], v173 offset:2048
	ds_read_b128 v[226:229], v173 offset:3072
	ds_read_b128 v[230:233], v173 offset:4096
	ds_read_b128 v[234:237], v173 offset:5120
	ds_read_b128 v[238:241], v173 offset:6144
	ds_read_b128 v[242:245], v173 offset:7168
	global_load_lds_dwordx4 v136, s[0:1]
	s_add_i32 m0, s6, 0xe000
	s_nop 0
	global_load_lds_dwordx4 v138, s[0:1]
	s_waitcnt vmcnt(8)
	s_waitcnt lgkmcnt(0)
	s_barrier
	s_setprio 1
	s_waitcnt lgkmcnt(0)
	v_mfma_f32_16x16x32_bf16 v[124:127], v[140:143], v[214:217], v[124:127]
	v_mfma_f32_16x16x32_bf16 v[120:123], v[166:169], v[214:217], v[120:123]
	v_mfma_f32_16x16x32_bf16 v[112:115], v[140:143], v[222:225], v[112:115]
	v_mfma_f32_16x16x32_bf16 v[104:107], v[166:169], v[222:225], v[104:107]
	v_mfma_f32_16x16x32_bf16 v[96:99], v[140:143], v[230:233], v[96:99]
	v_mfma_f32_16x16x32_bf16 v[88:91], v[166:169], v[230:233], v[88:91]
	v_mfma_f32_16x16x32_bf16 v[80:83], v[140:143], v[238:241], v[80:83]
	v_mfma_f32_16x16x32_bf16 v[72:75], v[166:169], v[238:241], v[72:75]
	v_mfma_f32_16x16x32_bf16 v[124:127], v[162:165], v[218:221], v[124:127]
	v_mfma_f32_16x16x32_bf16 v[120:123], v[176:179], v[218:221], v[120:123]
	v_mfma_f32_16x16x32_bf16 v[112:115], v[162:165], v[226:229], v[112:115]
	v_mfma_f32_16x16x32_bf16 v[104:107], v[176:179], v[226:229], v[104:107]
	v_mfma_f32_16x16x32_bf16 v[96:99], v[162:165], v[234:237], v[96:99]
	v_mfma_f32_16x16x32_bf16 v[88:91], v[176:179], v[234:237], v[88:91]
	v_mfma_f32_16x16x32_bf16 v[80:83], v[162:165], v[242:245], v[80:83]
	v_mfma_f32_16x16x32_bf16 v[72:75], v[176:179], v[242:245], v[72:75]
	s_setprio 0
	s_setprio 1
	v_mfma_f32_16x16x32_bf16 v[116:119], v[180:183], v[214:217], v[116:119]
	v_mfma_f32_16x16x32_bf16 v[108:111], v[188:191], v[214:217], v[108:111]
	v_mfma_f32_16x16x32_bf16 v[100:103], v[180:183], v[222:225], v[100:103]
	v_mfma_f32_16x16x32_bf16 v[92:95], v[188:191], v[222:225], v[92:95]
	v_mfma_f32_16x16x32_bf16 v[84:87], v[180:183], v[230:233], v[84:87]
	v_mfma_f32_16x16x32_bf16 v[76:79], v[188:191], v[230:233], v[76:79]
	v_mfma_f32_16x16x32_bf16 v[68:71], v[180:183], v[238:241], v[68:71]
	v_mfma_f32_16x16x32_bf16 v[64:67], v[188:191], v[238:241], v[64:67]
	v_mfma_f32_16x16x32_bf16 v[116:119], v[184:187], v[218:221], v[116:119]
	v_mfma_f32_16x16x32_bf16 v[108:111], v[210:213], v[218:221], v[108:111]
	v_mfma_f32_16x16x32_bf16 v[100:103], v[184:187], v[226:229], v[100:103]
	v_mfma_f32_16x16x32_bf16 v[92:95], v[210:213], v[226:229], v[92:95]
	v_mfma_f32_16x16x32_bf16 v[84:87], v[184:187], v[234:237], v[84:87]
	v_mfma_f32_16x16x32_bf16 v[76:79], v[210:213], v[234:237], v[76:79]
	v_mfma_f32_16x16x32_bf16 v[68:71], v[184:187], v[242:245], v[68:71]
	v_mfma_f32_16x16x32_bf16 v[64:67], v[210:213], v[242:245], v[64:67]
	s_setprio 0
	s_barrier
; #define PG8_STAGE(bufoff, gbase, voff) do { _Pragma("unroll") for (int _i = 0; _i < 2; ++_i) \
;         __builtin_amdgcn_global_load_lds((const unsigned*)((const char*)(gbase) + (voff)[_i]), (PG8_LAS unsigned*)(lds + (bufoff) + ldsw + _i * 8192), 16, 0, 0); } while (0)
; #define PG8_LDA(dst, b, h) do { _Pragma("unroll") for (int m = 0; m < 4; ++m) _Pragma("unroll") for (int k = 0; k < 2; ++k) dst[m][k] = *(const PG8_LAS bf16x8*)(lds + PG8_SA(b, h) + aoff + m * 2048 + k * 1024); } while (0)
; #define PG8_LDB(dst, b, h) do { _Pragma("unroll") for (int n = 0; n < 2; ++n) _Pragma("unroll") for (int k = 0; k < 2; ++k) dst[n][k] = *(const PG8_LAS bf16x8*)(lds + PG8_SB(b, h) + boff + n * 2048 + k * 1024); } while (0)
; #define PG8_MMA(ai, bj, At, Bt) do { __builtin_amdgcn_s_setprio(1); _Pragma("unroll") for (int m = 0; m < 4; ++m) _Pragma("unroll") for (int n = 0; n < 2; ++n) _Pragma("unroll") for (int k = 0; k < 2; ++k) \
;         acc[ai][bj][m][n] = __builtin_amdgcn_mfma_f32_16x16x32_bf16(Bt[n][k], At[m][k], acc[ai][bj][m][n], 0, 0, 0); __builtin_amdgcn_s_setprio(0); } while (0)
; #define PG8_WAIT_V(n) asm volatile("s_waitcnt vmcnt(" #n ")" ::: "memory")
; #define PG8_WAIT_L(n) asm volatile("s_waitcnt lgkmcnt(" #n ")" ::: "memory")
; #define PG8_BAR __builtin_amdgcn_s_barrier()
; #define PG8_SCHED __builtin_amdgcn_sched_barrier(0)
; template <class Epi, class Sched, bool ALIGN_EPI = false, bool SP2 = false>
; __device__ __forceinline__ void gemm_phase(PG8_LAS unsigned char* lds, const Gemm g, const Sched& S, const Epi& E) {
;     ...
;             PG8_LDA(At, 0, 1); PG8_STAGE(PG8_SB(0, 0), b2, voffB); PG8_STAGE(PG8_SB(0, 1), b2 + hstep, voffB); PG8_STAGE(PG8_SA(0, 0), a2, voffA);
;             PG8_WAIT_V(8); PG8_WAIT_L(0); PG8_BAR; PG8_MMA(1, 0, At, B0); PG8_MMA(1, 1, At, B1); PG8_BAR; PG8_SCHED;
;             PG8_LDB(B0, 1, 0); PG8_LDB(B1, 1, 1); PG8_SCHED; PG8_LDA(At, 1, 0); PG8_STAGE(PG8_SA(0, 1), a2 + hstep, voffA);
;             PG8_WAIT_V(8); PG8_WAIT_L(0); PG8_BAR; PG8_MMA(0, 0, At, B0); PG8_MMA(0, 1, At, B1); PG8_BAR; PG8_SCHED;
	s_mov_b32 m0, s27
	s_add_u32 s54, s2, 0x40000
	s_addc_u32 s55, s3, 0
	ds_read_b128 v[214:217], v173 offset:16384
	ds_read_b128 v[218:221], v173 offset:17408
	ds_read_b128 v[222:225], v173 offset:18432
	ds_read_b128 v[226:229], v173 offset:19456
	ds_read_b128 v[230:233], v173 offset:20480
	ds_read_b128 v[234:237], v173 offset:21504
	ds_read_b128 v[238:241], v173 offset:22528
	ds_read_b128 v[242:245], v173 offset:23552
	global_load_lds_dwordx4 v132, s[2:3]
	s_mov_b32 m0, s28
	s_nop 0
	global_load_lds_dwordx4 v128, s[2:3]
	s_mov_b32 m0, s29
	s_nop 0
	global_load_lds_dwordx4 v132, s[54:55]
	s_mov_b32 m0, s30
	s_nop 0
	global_load_lds_dwordx4 v128, s[54:55]
	s_mov_b32 m0, s6
	s_nop 0
	global_load_lds_dwordx4 v134, s[4:5]
	s_mov_b32 m0, s31
	s_nop 0
	global_load_lds_dwordx4 v130, s[4:5]
	s_waitcnt vmcnt(8)
	s_waitcnt lgkmcnt(0)
	s_barrier
	s_setprio 1
	s_waitcnt lgkmcnt(0)
	v_mfma_f32_16x16x32_bf16 v[60:63], v[140:143], v[214:217], v[60:63]
	v_mfma_f32_16x16x32_bf16 v[56:59], v[166:169], v[214:217], v[56:59]
	v_mfma_f32_16x16x32_bf16 v[48:51], v[140:143], v[222:225], v[48:51]
	v_mfma_f32_16x16x32_bf16 v[40:43], v[166:169], v[222:225], v[40:43]
	v_mfma_f32_16x16x32_bf16 v[32:35], v[140:143], v[230:233], v[32:35]
	v_mfma_f32_16x16x32_bf16 v[24:27], v[166:169], v[230:233], v[24:27]
	v_mfma_f32_16x16x32_bf16 v[16:19], v[140:143], v[238:241], v[16:19]
	v_mfma_f32_16x16x32_bf16 v[8:11], v[166:169], v[238:241], v[8:11]
	v_mfma_f32_16x16x32_bf16 v[60:63], v[162:165], v[218:221], v[60:63]
	v_mfma_f32_16x16x32_bf16 v[56:59], v[176:179], v[218:221], v[56:59]
	v_mfma_f32_16x16x32_bf16 v[48:51], v[162:165], v[226:229], v[48:51]
	v_mfma_f32_16x16x32_bf16 v[40:43], v[176:179], v[226:229], v[40:43]
	v_mfma_f32_16x16x32_bf16 v[32:35], v[162:165], v[234:237], v[32:35]
	v_mfma_f32_16x16x32_bf16 v[24:27], v[176:179], v[234:237], v[24:27]
	v_mfma_f32_16x16x32_bf16 v[16:19], v[162:165], v[242:245], v[16:19]
	v_mfma_f32_16x16x32_bf16 v[8:11], v[176:179], v[242:245], v[8:11]
	s_setprio 0
	s_setprio 1
	v_mfma_f32_16x16x32_bf16 v[52:55], v[180:183], v[214:217], v[52:55]
	v_mfma_f32_16x16x32_bf16 v[44:47], v[188:191], v[214:217], v[44:47]
	v_mfma_f32_16x16x32_bf16 v[36:39], v[180:183], v[222:225], v[36:39]
	v_mfma_f32_16x16x32_bf16 v[28:31], v[188:191], v[222:225], v[28:31]
	v_mfma_f32_16x16x32_bf16 v[20:23], v[180:183], v[230:233], v[20:23]
	v_mfma_f32_16x16x32_bf16 v[12:15], v[188:191], v[230:233], v[12:15]
	v_mfma_f32_16x16x32_bf16 v[4:7], v[180:183], v[238:241], v[4:7]
	v_mfma_f32_16x16x32_bf16 v[0:3], v[188:191], v[238:241], v[0:3]
	v_mfma_f32_16x16x32_bf16 v[52:55], v[184:187], v[218:221], v[52:55]
	v_mfma_f32_16x16x32_bf16 v[44:47], v[210:213], v[218:221], v[44:47]
	v_mfma_f32_16x16x32_bf16 v[36:39], v[184:187], v[226:229], v[36:39]
	v_mfma_f32_16x16x32_bf16 v[28:31], v[210:213], v[226:229], v[28:31]
	v_mfma_f32_16x16x32_bf16 v[20:23], v[184:187], v[234:237], v[20:23]
	v_mfma_f32_16x16x32_bf16 v[12:15], v[210:213], v[234:237], v[12:15]
	v_mfma_f32_16x16x32_bf16 v[4:7], v[184:187], v[242:245], v[4:7]
	v_mfma_f32_16x16x32_bf16 v[0:3], v[210:213], v[242:245], v[0:3]
	s_setprio 0
	s_barrier
	ds_read_b128 v[140:143], v254 offset:32768
	ds_read_b128 v[162:165], v254 offset:33792
	ds_read_b128 v[166:169], v254 offset:34816
	ds_read_b128 v[176:179], v254 offset:35840
	ds_read_b128 v[180:183], v254 offset:49152
	ds_read_b128 v[184:187], v254 offset:50176
	ds_read_b128 v[188:191], v254 offset:51200
	ds_read_b128 v[210:213], v254 offset:52224
	s_add_u32 s4, s4, 0x40000
	s_addc_u32 s5, s5, 0
	s_mov_b32 m0, s33
	ds_read_b128 v[214:217], v173 offset:32768
	ds_read_b128 v[218:221], v173 offset:33792
	ds_read_b128 v[222:225], v173 offset:34816
	ds_read_b128 v[226:229], v173 offset:35840
	ds_read_b128 v[230:233], v173 offset:36864
	ds_read_b128 v[234:237], v173 offset:37888
	ds_read_b128 v[238:241], v173 offset:38912
	ds_read_b128 v[242:245], v173 offset:39936
	global_load_lds_dwordx4 v134, s[4:5]
	s_mov_b32 m0, s34
	s_nop 0
	global_load_lds_dwordx4 v130, s[4:5]
	s_waitcnt vmcnt(8)
	s_waitcnt lgkmcnt(0)
	s_barrier
; #define PG8_STAGE(bufoff, gbase, voff) do { _Pragma("unroll") for (int _i = 0; _i < 2; ++_i) \
;         __builtin_amdgcn_global_load_lds((const unsigned*)((const char*)(gbase) + (voff)[_i]), (PG8_LAS unsigned*)(lds + (bufoff) + ldsw + _i * 8192), 16, 0, 0); } while (0)
; #define PG8_LDA(dst, b, h) do { _Pragma("unroll") for (int m = 0; m < 4; ++m) _Pragma("unroll") for (int k = 0; k < 2; ++k) dst[m][k] = *(const PG8_LAS bf16x8*)(lds + PG8_SA(b, h) + aoff + m * 2048 + k * 1024); } while (0)
; #define PG8_MMA(ai, bj, At, Bt) do { __builtin_amdgcn_s_setprio(1); _Pragma("unroll") for (int m = 0; m < 4; ++m) _Pragma("unroll") for (int n = 0; n < 2; ++n) _Pragma("unroll") for (int k = 0; k < 2; ++k) \
;         acc[ai][bj][m][n] = __builtin_amdgcn_mfma_f32_16x16x32_bf16(Bt[n][k], At[m][k], acc[ai][bj][m][n], 0, 0, 0); __builtin_amdgcn_s_setprio(0); } while (0)
; #define PG8_WAIT_V(n) asm volatile("s_waitcnt vmcnt(" #n ")" ::: "memory")
; #define PG8_WAIT_L(n) asm volatile("s_waitcnt lgkmcnt(" #n ")" ::: "memory")
; #define PG8_BAR __builtin_amdgcn_s_barrier()
; #define PG8_SCHED __builtin_amdgcn_sched_barrier(0)
; template <class Epi, class Sched, bool ALIGN_EPI = false, bool SP2 = false>
; __device__ __forceinline__ void gemm_phase(PG8_LAS unsigned char* lds, const Gemm g, const Sched& S, const Epi& E) {
;     ...
;         for (int t = 0; t < nt; t += 2) {
;     ...
;             PG8_WAIT_V(8); PG8_WAIT_L(0); PG8_BAR; PG8_MMA(0, 0, At, B0); PG8_MMA(0, 1, At, B1); PG8_BAR; PG8_SCHED;
;             PG8_LDA(At, 1, 1); PG8_STAGE(PG8_SB(1, 0), b3, voffB); PG8_STAGE(PG8_SB(1, 1), b3 + hstep, voffB); PG8_STAGE(PG8_SA(1, 0), a3, voffA);
;             PG8_WAIT_V(8); PG8_WAIT_L(0); PG8_BAR; PG8_MMA(1, 0, At, B0); PG8_MMA(1, 1, At, B1); PG8_BAR; PG8_SCHED;
	s_setprio 1
	s_waitcnt lgkmcnt(0)
	v_mfma_f32_16x16x32_bf16 v[124:127], v[140:143], v[214:217], v[124:127]
	v_mfma_f32_16x16x32_bf16 v[120:123], v[166:169], v[214:217], v[120:123]
	v_mfma_f32_16x16x32_bf16 v[112:115], v[140:143], v[222:225], v[112:115]
	v_mfma_f32_16x16x32_bf16 v[104:107], v[166:169], v[222:225], v[104:107]
	v_mfma_f32_16x16x32_bf16 v[96:99], v[140:143], v[230:233], v[96:99]
	v_mfma_f32_16x16x32_bf16 v[88:91], v[166:169], v[230:233], v[88:91]
	v_mfma_f32_16x16x32_bf16 v[80:83], v[140:143], v[238:241], v[80:83]
	v_mfma_f32_16x16x32_bf16 v[72:75], v[166:169], v[238:241], v[72:75]
	v_mfma_f32_16x16x32_bf16 v[124:127], v[162:165], v[218:221], v[124:127]
	v_mfma_f32_16x16x32_bf16 v[120:123], v[176:179], v[218:221], v[120:123]
	v_mfma_f32_16x16x32_bf16 v[112:115], v[162:165], v[226:229], v[112:115]
	v_mfma_f32_16x16x32_bf16 v[104:107], v[176:179], v[226:229], v[104:107]
	v_mfma_f32_16x16x32_bf16 v[96:99], v[162:165], v[234:237], v[96:99]
	v_mfma_f32_16x16x32_bf16 v[88:91], v[176:179], v[234:237], v[88:91]
	v_mfma_f32_16x16x32_bf16 v[80:83], v[162:165], v[242:245], v[80:83]
	v_mfma_f32_16x16x32_bf16 v[72:75], v[176:179], v[242:245], v[72:75]
	s_setprio 0
	s_setprio 1
	v_mfma_f32_16x16x32_bf16 v[116:119], v[180:183], v[214:217], v[116:119]
	v_mfma_f32_16x16x32_bf16 v[108:111], v[188:191], v[214:217], v[108:111]
	v_mfma_f32_16x16x32_bf16 v[100:103], v[180:183], v[222:225], v[100:103]
	v_mfma_f32_16x16x32_bf16 v[92:95], v[188:191], v[222:225], v[92:95]
	v_mfma_f32_16x16x32_bf16 v[84:87], v[180:183], v[230:233], v[84:87]
	v_mfma_f32_16x16x32_bf16 v[76:79], v[188:191], v[230:233], v[76:79]
	v_mfma_f32_16x16x32_bf16 v[68:71], v[180:183], v[238:241], v[68:71]
	v_mfma_f32_16x16x32_bf16 v[64:67], v[188:191], v[238:241], v[64:67]
	v_mfma_f32_16x16x32_bf16 v[116:119], v[184:187], v[218:221], v[116:119]
	v_mfma_f32_16x16x32_bf16 v[108:111], v[210:213], v[218:221], v[108:111]
	v_mfma_f32_16x16x32_bf16 v[100:103], v[184:187], v[226:229], v[100:103]
	v_mfma_f32_16x16x32_bf16 v[92:95], v[210:213], v[226:229], v[92:95]
	v_mfma_f32_16x16x32_bf16 v[84:87], v[184:187], v[234:237], v[84:87]
	v_mfma_f32_16x16x32_bf16 v[76:79], v[210:213], v[234:237], v[76:79]
	v_mfma_f32_16x16x32_bf16 v[68:71], v[184:187], v[242:245], v[68:71]
	v_mfma_f32_16x16x32_bf16 v[64:67], v[210:213], v[242:245], v[64:67]
	s_setprio 0
	s_barrier
	s_mov_b32 m0, s37
	s_add_u32 s2, s2, 0x40080
	s_addc_u32 s3, s3, 0
	ds_read_b128 v[214:217], v173 offset:49152
	ds_read_b128 v[218:221], v173 offset:50176
	ds_read_b128 v[222:225], v173 offset:51200
	ds_read_b128 v[226:229], v173 offset:52224
	ds_read_b128 v[230:233], v173 offset:53248
	ds_read_b128 v[234:237], v173 offset:54272
	ds_read_b128 v[238:241], v173 offset:55296
	ds_read_b128 v[242:245], v173 offset:56320
	s_add_u32 s98, s2, 0xfffc0000
	s_addc_u32 s99, s3, -1
	global_load_lds_dwordx4 v132, s[98:99]
	s_mov_b32 m0, s38
	s_nop 0
	global_load_lds_dwordx4 v128, s[98:99]
	s_mov_b32 m0, s41
	s_nop 0
	global_load_lds_dwordx4 v132, s[2:3]
	s_mov_b32 m0, s42
	s_nop 0
	global_load_lds_dwordx4 v128, s[2:3]
	s_mov_b32 m0, s39
	s_nop 0
	s_add_u32 s100, s4, 0xfffc0080
	s_addc_u32 s101, s5, -1
	global_load_lds_dwordx4 v134, s[100:101]
	s_mov_b32 m0, s40
	s_nop 0
	global_load_lds_dwordx4 v130, s[100:101]
	s_waitcnt vmcnt(8)
	s_waitcnt lgkmcnt(0)
	s_barrier
	s_setprio 1
	s_waitcnt lgkmcnt(0)
	v_mfma_f32_16x16x32_bf16 v[60:63], v[140:143], v[214:217], v[60:63]
	v_mfma_f32_16x16x32_bf16 v[56:59], v[166:169], v[214:217], v[56:59]
	v_mfma_f32_16x16x32_bf16 v[48:51], v[140:143], v[222:225], v[48:51]
	v_mfma_f32_16x16x32_bf16 v[40:43], v[166:169], v[222:225], v[40:43]
	v_mfma_f32_16x16x32_bf16 v[32:35], v[140:143], v[230:233], v[32:35]
	v_mfma_f32_16x16x32_bf16 v[24:27], v[166:169], v[230:233], v[24:27]
	v_mfma_f32_16x16x32_bf16 v[16:19], v[140:143], v[238:241], v[16:19]
	v_mfma_f32_16x16x32_bf16 v[8:11], v[166:169], v[238:241], v[8:11]
	v_mfma_f32_16x16x32_bf16 v[60:63], v[162:165], v[218:221], v[60:63]
	v_mfma_f32_16x16x32_bf16 v[56:59], v[176:179], v[218:221], v[56:59]
	v_mfma_f32_16x16x32_bf16 v[48:51], v[162:165], v[226:229], v[48:51]
	v_mfma_f32_16x16x32_bf16 v[40:43], v[176:179], v[226:229], v[40:43]
	v_mfma_f32_16x16x32_bf16 v[32:35], v[162:165], v[234:237], v[32:35]
	v_mfma_f32_16x16x32_bf16 v[24:27], v[176:179], v[234:237], v[24:27]
	v_mfma_f32_16x16x32_bf16 v[16:19], v[162:165], v[242:245], v[16:19]
	v_mfma_f32_16x16x32_bf16 v[8:11], v[176:179], v[242:245], v[8:11]
	s_setprio 0
	s_setprio 1
	v_mfma_f32_16x16x32_bf16 v[52:55], v[180:183], v[214:217], v[52:55]
	v_mfma_f32_16x16x32_bf16 v[44:47], v[188:191], v[214:217], v[44:47]
	v_mfma_f32_16x16x32_bf16 v[36:39], v[180:183], v[222:225], v[36:39]
	v_mfma_f32_16x16x32_bf16 v[28:31], v[188:191], v[222:225], v[28:31]
	v_mfma_f32_16x16x32_bf16 v[20:23], v[180:183], v[230:233], v[20:23]
	v_mfma_f32_16x16x32_bf16 v[12:15], v[188:191], v[230:233], v[12:15]
	v_mfma_f32_16x16x32_bf16 v[4:7], v[180:183], v[238:241], v[4:7]
	v_mfma_f32_16x16x32_bf16 v[0:3], v[188:191], v[238:241], v[0:3]
	v_mfma_f32_16x16x32_bf16 v[52:55], v[184:187], v[218:221], v[52:55]
	v_mfma_f32_16x16x32_bf16 v[44:47], v[210:213], v[218:221], v[44:47]
	v_mfma_f32_16x16x32_bf16 v[36:39], v[184:187], v[226:229], v[36:39]
	v_mfma_f32_16x16x32_bf16 v[28:31], v[210:213], v[226:229], v[28:31]
	v_mfma_f32_16x16x32_bf16 v[20:23], v[184:187], v[234:237], v[20:23]
	v_mfma_f32_16x16x32_bf16 v[12:15], v[210:213], v[234:237], v[12:15]
	v_mfma_f32_16x16x32_bf16 v[4:7], v[184:187], v[242:245], v[4:7]
	v_mfma_f32_16x16x32_bf16 v[0:3], v[210:213], v[242:245], v[0:3]
	s_setprio 0
	s_barrier
	s_add_i32 s52, s52, 2
	s_add_u32 s0, s0, 0x100
	s_addc_u32 s1, s1, 0
	s_add_u32 s50, s50, 0x100
	s_addc_u32 s51, s51, 0
	s_cmp_gt_u32 s52, 13
	s_cbranch_scc0 .LBB0_792
	s_and_b64 vcc, exec, s[12:13]
	s_cbranch_vccz .LBB0_795
	s_barrier

; #define PG8_STAGE(bufoff, gbase, voff) do { _Pragma("unroll") for (int _i = 0; _i < 2; ++_i) \
;         __builtin_amdgcn_global_load_lds((const unsigned*)((const char*)(gbase) + (voff)[_i]), (PG8_LAS unsigned*)(lds + (bufoff) + ldsw + _i * 8192), 16, 0, 0); } while (0)
; #define PG8_LDA(dst, b, h) do { _Pragma("unroll") for (int m = 0; m < 4; ++m) _Pragma("unroll") for (int k = 0; k < 2; ++k) dst[m][k] = *(const PG8_LAS bf16x8*)(lds + PG8_SA(b, h) + aoff + m * 2048 + k * 1024); } while (0)
; #define PG8_LDB(dst, b, h) do { _Pragma("unroll") for (int n = 0; n < 2; ++n) _Pragma("unroll") for (int k = 0; k < 2; ++k) dst[n][k] = *(const PG8_LAS bf16x8*)(lds + PG8_SB(b, h) + boff + n * 2048 + k * 1024); } while (0)
; #define PG8_MMA(ai, bj, At, Bt) do { __builtin_amdgcn_s_setprio(1); _Pragma("unroll") for (int m = 0; m < 4; ++m) _Pragma("unroll") for (int n = 0; n < 2; ++n) _Pragma("unroll") for (int k = 0; k < 2; ++k) \
;         acc[ai][bj][m][n] = __builtin_amdgcn_mfma_f32_16x16x32_bf16(Bt[n][k], At[m][k], acc[ai][bj][m][n], 0, 0, 0); __builtin_amdgcn_s_setprio(0); } while (0)
; #define PG8_BAR __builtin_amdgcn_s_barrier()
; template <class Epi, class Sched, bool ALIGN_EPI = false, bool SP2 = false>
; __device__ __forceinline__ void gemm_phase(PG8_LAS unsigned char* lds, const Gemm g, const Sched& S, const Epi& E) {
;     ...
;         const bool has_next = S.next(ui + 1, nxt);
;         const char* nA = has_next ? (const char*)g.A + (size_t)nxt.pm * tstep : cA; const char* nB = has_next ? (const char*)g.Bt + (size_t)nxt.pn * tstep : cB;
;         for (int t = 0; t < nt; t += 2) {
;             const bool last = (t == nt - 2);
;             const char* a1 = cA + (size_t)(t + 1) * kstep;
;             const char* a2 = last ? nA : cA + (size_t)(t + 2) * kstep; const char* b2 = last ? nB : cB + (size_t)(t + 2) * kstep;
;             const char* a3 = a2 + kstep; const char* b3 = b2 + kstep;
;             if (last && has_next) S.a_ready(nxt);
;             if constexpr (SP2) {
;             PG8_LDB(B0, 0, 0); PG8_LDB(B1, 0, 1); PG8_SCHED; PG8_LDA(At, 0, 0); PG8_STAGE(PG8_SA(1, 1), a1 + hstep, voffA);
;             PG8_WAIT_V(8); PG8_WAIT_L(0); PG8_BAR; PG8_MMA(0, 0, At, B0); PG8_MMA(0, 1, At, B1); PG8_BAR; PG8_SCHED;
;             PG8_LDA(At, 0, 1); PG8_STAGE(PG8_SB(0, 0), b2, voffB); PG8_STAGE(PG8_SB(0, 1), b2 + hstep, voffB); PG8_STAGE(PG8_SA(0, 0), a2, voffA);
.LBB0_1041:
	s_ashr_i32 s23, s22, 31
	s_lshl_b64 s[4:5], s[22:23], 19
	s_add_u32 s24, s7, s4
	s_addc_u32 s25, s28, s5
	s_and_b64 s[4:5], s[8:9], exec
	s_cselect_b32 s23, s25, s1
	s_cselect_b32 s51, s24, s0
	s_ashr_i32 s21, s20, 31
	s_lshl_b64 s[4:5], s[20:21], 19
	s_add_u32 s26, s29, s4
	s_addc_u32 s27, s30, s5
	s_and_b64 s[4:5], s[8:9], exec
	s_cselect_b32 s21, s27, s3
	s_cselect_b32 s52, s26, s2
	s_add_u32 s0, s0, 0x40080
	s_addc_u32 s1, s1, 0
	s_add_u32 s53, s2, 0x100
	v_mov_b32_e32 v0, 0
	s_addc_u32 s54, s3, 0
	s_mov_b32 s55, -2
	s_waitcnt lgkmcnt(0)
	v_add_u32_e32 v254, 0x10000, v164
.Lsgo_peel:
	ds_read_b128 v[140:143], v254
	ds_read_b128 v[166:169], v254 offset:1024
	ds_read_b128 v[170:173], v254 offset:2048
	ds_read_b128 v[174:177], v254 offset:3072
	ds_read_b128 v[178:181], v254 offset:16384
	ds_read_b128 v[182:185], v254 offset:17408
	ds_read_b128 v[186:189], v254 offset:18432
	ds_read_b128 v[210:213], v254 offset:19456
	s_add_u32 s2, s0, 0xfffc0080
	s_addc_u32 s3, s1, -1
	s_cmp_eq_u32 s55, 12
	s_cselect_b32 s5, s23, s3
	s_cselect_b32 s4, s51, s2
	s_cselect_b32 s3, s21, s54
	s_cselect_b32 s2, s52, s53
	s_add_i32 m0, s31, 0xc000
	ds_read_b128 v[214:217], v163
	ds_read_b128 v[218:221], v163 offset:1024
	ds_read_b128 v[222:225], v163 offset:2048
	ds_read_b128 v[226:229], v163 offset:3072
	ds_read_b128 v[230:233], v163 offset:4096
	ds_read_b128 v[234:237], v163 offset:5120
	ds_read_b128 v[238:241], v163 offset:6144
	ds_read_b128 v[242:245], v163 offset:7168
	global_load_lds_dwordx4 v136, s[0:1]
	s_add_i32 m0, s31, 0xe000
	s_nop 0
	global_load_lds_dwordx4 v138, s[0:1]
	s_waitcnt vmcnt(8)
	s_waitcnt lgkmcnt(0)
	s_barrier
	s_setprio 1
	s_waitcnt lgkmcnt(0)
	v_mfma_f32_16x16x32_bf16 v[124:127], v[140:143], v[214:217], 0
	v_mfma_f32_16x16x32_bf16 v[120:123], v[170:173], v[214:217], 0
	v_mfma_f32_16x16x32_bf16 v[108:111], v[140:143], v[222:225], 0
	v_mfma_f32_16x16x32_bf16 v[104:107], v[170:173], v[222:225], 0
	v_mfma_f32_16x16x32_bf16 v[92:95], v[140:143], v[230:233], 0
	v_mfma_f32_16x16x32_bf16 v[88:91], v[170:173], v[230:233], 0
	v_mfma_f32_16x16x32_bf16 v[76:79], v[140:143], v[238:241], 0
	v_mfma_f32_16x16x32_bf16 v[72:75], v[170:173], v[238:241], 0
	v_mfma_f32_16x16x32_bf16 v[124:127], v[166:169], v[218:221], v[124:127]
	v_mfma_f32_16x16x32_bf16 v[120:123], v[174:177], v[218:221], v[120:123]
	v_mfma_f32_16x16x32_bf16 v[108:111], v[166:169], v[226:229], v[108:111]
	v_mfma_f32_16x16x32_bf16 v[104:107], v[174:177], v[226:229], v[104:107]
	v_mfma_f32_16x16x32_bf16 v[92:95], v[166:169], v[234:237], v[92:95]
	v_mfma_f32_16x16x32_bf16 v[88:91], v[174:177], v[234:237], v[88:91]
	v_mfma_f32_16x16x32_bf16 v[76:79], v[166:169], v[242:245], v[76:79]
	v_mfma_f32_16x16x32_bf16 v[72:75], v[174:177], v[242:245], v[72:75]
	s_setprio 0
	s_setprio 1
	v_mfma_f32_16x16x32_bf16 v[116:119], v[178:181], v[214:217], 0
	v_mfma_f32_16x16x32_bf16 v[112:115], v[186:189], v[214:217], 0
	v_mfma_f32_16x16x32_bf16 v[100:103], v[178:181], v[222:225], 0
	v_mfma_f32_16x16x32_bf16 v[96:99], v[186:189], v[222:225], 0
	v_mfma_f32_16x16x32_bf16 v[84:87], v[178:181], v[230:233], 0
	v_mfma_f32_16x16x32_bf16 v[80:83], v[186:189], v[230:233], 0
	v_mfma_f32_16x16x32_bf16 v[68:71], v[178:181], v[238:241], 0
	v_mfma_f32_16x16x32_bf16 v[64:67], v[186:189], v[238:241], 0
	v_mfma_f32_16x16x32_bf16 v[116:119], v[182:185], v[218:221], v[116:119]
	v_mfma_f32_16x16x32_bf16 v[112:115], v[210:213], v[218:221], v[112:115]
	v_mfma_f32_16x16x32_bf16 v[100:103], v[182:185], v[226:229], v[100:103]
	v_mfma_f32_16x16x32_bf16 v[96:99], v[210:213], v[226:229], v[96:99]
	v_mfma_f32_16x16x32_bf16 v[84:87], v[182:185], v[234:237], v[84:87]
	v_mfma_f32_16x16x32_bf16 v[80:83], v[210:213], v[234:237], v[80:83]
	v_mfma_f32_16x16x32_bf16 v[68:71], v[182:185], v[242:245], v[68:71]
	v_mfma_f32_16x16x32_bf16 v[64:67], v[210:213], v[242:245], v[64:67]
	s_setprio 0
	s_barrier
	s_mov_b32 m0, s33
	s_add_u32 s56, s2, 0x40000
	s_addc_u32 s57, s3, 0
	ds_read_b128 v[214:217], v163 offset:16384
	ds_read_b128 v[218:221], v163 offset:17408
	ds_read_b128 v[222:225], v163 offset:18432
	ds_read_b128 v[226:229], v163 offset:19456
	ds_read_b128 v[230:233], v163 offset:20480
	ds_read_b128 v[234:237], v163 offset:21504
	ds_read_b128 v[238:241], v163 offset:22528
	ds_read_b128 v[242:245], v163 offset:23552
	global_load_lds_dwordx4 v132, s[2:3]
	s_mov_b32 m0, s34
	s_nop 0
	global_load_lds_dwordx4 v128, s[2:3]
	s_mov_b32 m0, s35
	s_nop 0
	global_load_lds_dwordx4 v132, s[56:57]
	s_mov_b32 m0, s36
	s_nop 0
	global_load_lds_dwordx4 v128, s[56:57]
	s_mov_b32 m0, s31
	s_nop 0
	global_load_lds_dwordx4 v134, s[4:5]
	s_mov_b32 m0, s37
	s_nop 0
	global_load_lds_dwordx4 v130, s[4:5]
	s_waitcnt vmcnt(8)
	s_waitcnt lgkmcnt(0)
	s_barrier
; #define PG8_STAGE(bufoff, gbase, voff) do { _Pragma("unroll") for (int _i = 0; _i < 2; ++_i) \
;         __builtin_amdgcn_global_load_lds((const unsigned*)((const char*)(gbase) + (voff)[_i]), (PG8_LAS unsigned*)(lds + (bufoff) + ldsw + _i * 8192), 16, 0, 0); } while (0)
; #define PG8_LDA(dst, b, h) do { _Pragma("unroll") for (int m = 0; m < 4; ++m) _Pragma("unroll") for (int k = 0; k < 2; ++k) dst[m][k] = *(const PG8_LAS bf16x8*)(lds + PG8_SA(b, h) + aoff + m * 2048 + k * 1024); } while (0)
; #define PG8_LDB(dst, b, h) do { _Pragma("unroll") for (int n = 0; n < 2; ++n) _Pragma("unroll") for (int k = 0; k < 2; ++k) dst[n][k] = *(const PG8_LAS bf16x8*)(lds + PG8_SB(b, h) + boff + n * 2048 + k * 1024); } while (0)
; #define PG8_MMA(ai, bj, At, Bt) do { __builtin_amdgcn_s_setprio(1); _Pragma("unroll") for (int m = 0; m < 4; ++m) _Pragma("unroll") for (int n = 0; n < 2; ++n) _Pragma("unroll") for (int k = 0; k < 2; ++k) \
;         acc[ai][bj][m][n] = __builtin_amdgcn_mfma_f32_16x16x32_bf16(Bt[n][k], At[m][k], acc[ai][bj][m][n], 0, 0, 0); __builtin_amdgcn_s_setprio(0); } while (0)
; #define PG8_WAIT_V(n) asm volatile("s_waitcnt vmcnt(" #n ")" ::: "memory")
; #define PG8_WAIT_L(n) asm volatile("s_waitcnt lgkmcnt(" #n ")" ::: "memory")
; #define PG8_BAR __builtin_amdgcn_s_barrier()
; #define PG8_SCHED __builtin_amdgcn_sched_barrier(0)
; template <class Epi, class Sched, bool ALIGN_EPI = false, bool SP2 = false>
; __device__ __forceinline__ void gemm_phase(PG8_LAS unsigned char* lds, const Gemm g, const Sched& S, const Epi& E) {
;     ...
;             PG8_WAIT_V(8); PG8_WAIT_L(0); PG8_BAR; PG8_MMA(1, 0, At, B0); PG8_MMA(1, 1, At, B1); PG8_BAR; PG8_SCHED;
;             PG8_LDB(B0, 1, 0); PG8_LDB(B1, 1, 1); PG8_SCHED; PG8_LDA(At, 1, 0); PG8_STAGE(PG8_SA(0, 1), a2 + hstep, voffA);
;             PG8_WAIT_V(8); PG8_WAIT_L(0); PG8_BAR; PG8_MMA(0, 0, At, B0); PG8_MMA(0, 1, At, B1); PG8_BAR; PG8_SCHED;
	s_setprio 1
	s_waitcnt lgkmcnt(0)
	v_mfma_f32_16x16x32_bf16 v[60:63], v[140:143], v[214:217], 0
	v_mfma_f32_16x16x32_bf16 v[56:59], v[170:173], v[214:217], 0
	v_mfma_f32_16x16x32_bf16 v[44:47], v[140:143], v[222:225], 0
	v_mfma_f32_16x16x32_bf16 v[40:43], v[170:173], v[222:225], 0
	v_mfma_f32_16x16x32_bf16 v[28:31], v[140:143], v[230:233], 0
	v_mfma_f32_16x16x32_bf16 v[24:27], v[170:173], v[230:233], 0
	v_mfma_f32_16x16x32_bf16 v[12:15], v[140:143], v[238:241], 0
	v_mfma_f32_16x16x32_bf16 v[8:11], v[170:173], v[238:241], 0
	v_mfma_f32_16x16x32_bf16 v[60:63], v[166:169], v[218:221], v[60:63]
	v_mfma_f32_16x16x32_bf16 v[56:59], v[174:177], v[218:221], v[56:59]
	v_mfma_f32_16x16x32_bf16 v[44:47], v[166:169], v[226:229], v[44:47]
	v_mfma_f32_16x16x32_bf16 v[40:43], v[174:177], v[226:229], v[40:43]
	v_mfma_f32_16x16x32_bf16 v[28:31], v[166:169], v[234:237], v[28:31]
	v_mfma_f32_16x16x32_bf16 v[24:27], v[174:177], v[234:237], v[24:27]
	v_mfma_f32_16x16x32_bf16 v[12:15], v[166:169], v[242:245], v[12:15]
	v_mfma_f32_16x16x32_bf16 v[8:11], v[174:177], v[242:245], v[8:11]
	s_setprio 0
	s_setprio 1
	v_mfma_f32_16x16x32_bf16 v[52:55], v[178:181], v[214:217], 0
	v_mfma_f32_16x16x32_bf16 v[48:51], v[186:189], v[214:217], 0
	v_mfma_f32_16x16x32_bf16 v[36:39], v[178:181], v[222:225], 0
	v_mfma_f32_16x16x32_bf16 v[32:35], v[186:189], v[222:225], 0
	v_mfma_f32_16x16x32_bf16 v[20:23], v[178:181], v[230:233], 0
	v_mfma_f32_16x16x32_bf16 v[16:19], v[186:189], v[230:233], 0
	v_mfma_f32_16x16x32_bf16 v[4:7], v[178:181], v[238:241], 0
	v_mfma_f32_16x16x32_bf16 v[0:3], v[186:189], v[238:241], 0
	v_mfma_f32_16x16x32_bf16 v[52:55], v[182:185], v[218:221], v[52:55]
	v_mfma_f32_16x16x32_bf16 v[48:51], v[210:213], v[218:221], v[48:51]
	v_mfma_f32_16x16x32_bf16 v[36:39], v[182:185], v[226:229], v[36:39]
	v_mfma_f32_16x16x32_bf16 v[32:35], v[210:213], v[226:229], v[32:35]
	v_mfma_f32_16x16x32_bf16 v[20:23], v[182:185], v[234:237], v[20:23]
	v_mfma_f32_16x16x32_bf16 v[16:19], v[210:213], v[234:237], v[16:19]
	v_mfma_f32_16x16x32_bf16 v[4:7], v[182:185], v[242:245], v[4:7]
	v_mfma_f32_16x16x32_bf16 v[0:3], v[210:213], v[242:245], v[0:3]
	s_setprio 0
	s_barrier
	ds_read_b128 v[140:143], v254 offset:32768
	ds_read_b128 v[166:169], v254 offset:33792
	ds_read_b128 v[170:173], v254 offset:34816
	ds_read_b128 v[174:177], v254 offset:35840
	ds_read_b128 v[178:181], v254 offset:49152
	ds_read_b128 v[182:185], v254 offset:50176
	ds_read_b128 v[186:189], v254 offset:51200
	ds_read_b128 v[210:213], v254 offset:52224
	s_add_u32 s4, s4, 0x40000
	s_addc_u32 s5, s5, 0
	s_mov_b32 m0, s38
	ds_read_b128 v[214:217], v163 offset:32768
	ds_read_b128 v[218:221], v163 offset:33792
	ds_read_b128 v[222:225], v163 offset:34816
	ds_read_b128 v[226:229], v163 offset:35840
	ds_read_b128 v[230:233], v163 offset:36864
	ds_read_b128 v[234:237], v163 offset:37888
	ds_read_b128 v[238:241], v163 offset:38912
	ds_read_b128 v[242:245], v163 offset:39936
	global_load_lds_dwordx4 v134, s[4:5]
	s_mov_b32 m0, s39
	s_nop 0
	global_load_lds_dwordx4 v130, s[4:5]
	s_waitcnt vmcnt(8)
	s_waitcnt lgkmcnt(0)
	s_barrier
	s_setprio 1
	s_waitcnt lgkmcnt(0)
	v_mfma_f32_16x16x32_bf16 v[124:127], v[140:143], v[214:217], v[124:127]
	v_mfma_f32_16x16x32_bf16 v[120:123], v[170:173], v[214:217], v[120:123]
	v_mfma_f32_16x16x32_bf16 v[108:111], v[140:143], v[222:225], v[108:111]
	v_mfma_f32_16x16x32_bf16 v[104:107], v[170:173], v[222:225], v[104:107]
	v_mfma_f32_16x16x32_bf16 v[92:95], v[140:143], v[230:233], v[92:95]
	v_mfma_f32_16x16x32_bf16 v[88:91], v[170:173], v[230:233], v[88:91]
	v_mfma_f32_16x16x32_bf16 v[76:79], v[140:143], v[238:241], v[76:79]
	v_mfma_f32_16x16x32_bf16 v[72:75], v[170:173], v[238:241], v[72:75]
	v_mfma_f32_16x16x32_bf16 v[124:127], v[166:169], v[218:221], v[124:127]
	v_mfma_f32_16x16x32_bf16 v[120:123], v[174:177], v[218:221], v[120:123]
	v_mfma_f32_16x16x32_bf16 v[108:111], v[166:169], v[226:229], v[108:111]
	v_mfma_f32_16x16x32_bf16 v[104:107], v[174:177], v[226:229], v[104:107]
	v_mfma_f32_16x16x32_bf16 v[92:95], v[166:169], v[234:237], v[92:95]
	v_mfma_f32_16x16x32_bf16 v[88:91], v[174:177], v[234:237], v[88:91]
	v_mfma_f32_16x16x32_bf16 v[76:79], v[166:169], v[242:245], v[76:79]
	v_mfma_f32_16x16x32_bf16 v[72:75], v[174:177], v[242:245], v[72:75]
	s_setprio 0
	s_setprio 1
	v_mfma_f32_16x16x32_bf16 v[116:119], v[178:181], v[214:217], v[116:119]
	v_mfma_f32_16x16x32_bf16 v[112:115], v[186:189], v[214:217], v[112:115]
	v_mfma_f32_16x16x32_bf16 v[100:103], v[178:181], v[222:225], v[100:103]
	v_mfma_f32_16x16x32_bf16 v[96:99], v[186:189], v[222:225], v[96:99]
	v_mfma_f32_16x16x32_bf16 v[84:87], v[178:181], v[230:233], v[84:87]
	v_mfma_f32_16x16x32_bf16 v[80:83], v[186:189], v[230:233], v[80:83]
	v_mfma_f32_16x16x32_bf16 v[68:71], v[178:181], v[238:241], v[68:71]
	v_mfma_f32_16x16x32_bf16 v[64:67], v[186:189], v[238:241], v[64:67]
	v_mfma_f32_16x16x32_bf16 v[116:119], v[182:185], v[218:221], v[116:119]
	v_mfma_f32_16x16x32_bf16 v[112:115], v[210:213], v[218:221], v[112:115]
	v_mfma_f32_16x16x32_bf16 v[100:103], v[182:185], v[226:229], v[100:103]
	v_mfma_f32_16x16x32_bf16 v[96:99], v[210:213], v[226:229], v[96:99]
	v_mfma_f32_16x16x32_bf16 v[84:87], v[182:185], v[234:237], v[84:87]
	v_mfma_f32_16x16x32_bf16 v[80:83], v[210:213], v[234:237], v[80:83]
	v_mfma_f32_16x16x32_bf16 v[68:71], v[182:185], v[242:245], v[68:71]
	v_mfma_f32_16x16x32_bf16 v[64:67], v[210:213], v[242:245], v[64:67]
	s_setprio 0
	s_barrier
; #define PG8_STAGE(bufoff, gbase, voff) do { _Pragma("unroll") for (int _i = 0; _i < 2; ++_i) \
;         __builtin_amdgcn_global_load_lds((const unsigned*)((const char*)(gbase) + (voff)[_i]), (PG8_LAS unsigned*)(lds + (bufoff) + ldsw + _i * 8192), 16, 0, 0); } while (0)
; #define PG8_LDA(dst, b, h) do { _Pragma("unroll") for (int m = 0; m < 4; ++m) _Pragma("unroll") for (int k = 0; k < 2; ++k) dst[m][k] = *(const PG8_LAS bf16x8*)(lds + PG8_SA(b, h) + aoff + m * 2048 + k * 1024); } while (0)
; #define PG8_LDB(dst, b, h) do { _Pragma("unroll") for (int n = 0; n < 2; ++n) _Pragma("unroll") for (int k = 0; k < 2; ++k) dst[n][k] = *(const PG8_LAS bf16x8*)(lds + PG8_SB(b, h) + boff + n * 2048 + k * 1024); } while (0)
; #define PG8_MMA(ai, bj, At, Bt) do { __builtin_amdgcn_s_setprio(1); _Pragma("unroll") for (int m = 0; m < 4; ++m) _Pragma("unroll") for (int n = 0; n < 2; ++n) _Pragma("unroll") for (int k = 0; k < 2; ++k) \
;         acc[ai][bj][m][n] = __builtin_amdgcn_mfma_f32_16x16x32_bf16(Bt[n][k], At[m][k], acc[ai][bj][m][n], 0, 0, 0); __builtin_amdgcn_s_setprio(0); } while (0)
; #define PG8_WAIT_V(n) asm volatile("s_waitcnt vmcnt(" #n ")" ::: "memory")
; #define PG8_WAIT_L(n) asm volatile("s_waitcnt lgkmcnt(" #n ")" ::: "memory")
; #define PG8_BAR __builtin_amdgcn_s_barrier()
; #define PG8_SCHED __builtin_amdgcn_sched_barrier(0)
; template <class Epi, class Sched, bool ALIGN_EPI = false, bool SP2 = false>
; __device__ __forceinline__ void gemm_phase(PG8_LAS unsigned char* lds, const Gemm g, const Sched& S, const Epi& E) {
;     ...
;         for (int t = 0; t < nt; t += 2) {
;     ...
;             PG8_LDB(B0, 0, 0); PG8_LDB(B1, 0, 1); PG8_SCHED; PG8_LDA(At, 0, 0); PG8_STAGE(PG8_SA(1, 1), a1 + hstep, voffA);
;             PG8_WAIT_V(8); PG8_WAIT_L(0); PG8_BAR; PG8_MMA(0, 0, At, B0); PG8_MMA(0, 1, At, B1); PG8_BAR; PG8_SCHED;
;     ...
;             PG8_LDA(At, 1, 1); PG8_STAGE(PG8_SB(1, 0), b3, voffB); PG8_STAGE(PG8_SB(1, 1), b3 + hstep, voffB); PG8_STAGE(PG8_SA(1, 0), a3, voffA);
;             PG8_WAIT_V(8); PG8_WAIT_L(0); PG8_BAR; PG8_MMA(1, 0, At, B0); PG8_MMA(1, 1, At, B1); PG8_BAR; PG8_SCHED;
	s_mov_b32 m0, s43
	s_add_u32 s2, s2, 0x40080
	s_addc_u32 s3, s3, 0
	ds_read_b128 v[214:217], v163 offset:49152
	ds_read_b128 v[218:221], v163 offset:50176
	ds_read_b128 v[222:225], v163 offset:51200
	ds_read_b128 v[226:229], v163 offset:52224
	ds_read_b128 v[230:233], v163 offset:53248
	ds_read_b128 v[234:237], v163 offset:54272
	ds_read_b128 v[238:241], v163 offset:55296
	ds_read_b128 v[242:245], v163 offset:56320
	s_add_u32 s98, s2, 0xfffc0000
	s_addc_u32 s99, s3, -1
	global_load_lds_dwordx4 v132, s[98:99]
	s_mov_b32 m0, s44
	s_nop 0
	global_load_lds_dwordx4 v128, s[98:99]
	s_mov_b32 m0, s48
	s_nop 0
	global_load_lds_dwordx4 v132, s[2:3]
	s_mov_b32 m0, s49
	s_nop 0
	global_load_lds_dwordx4 v128, s[2:3]
	s_mov_b32 m0, s45
	s_nop 0
	s_add_u32 s100, s4, 0xfffc0080
	s_addc_u32 s101, s5, -1
	global_load_lds_dwordx4 v134, s[100:101]
	s_mov_b32 m0, s47
	s_nop 0
	global_load_lds_dwordx4 v130, s[100:101]
	s_waitcnt vmcnt(8)
	s_waitcnt lgkmcnt(0)
	s_barrier
	s_setprio 1
	s_waitcnt lgkmcnt(0)
	v_mfma_f32_16x16x32_bf16 v[60:63], v[140:143], v[214:217], v[60:63]
	v_mfma_f32_16x16x32_bf16 v[56:59], v[170:173], v[214:217], v[56:59]
	v_mfma_f32_16x16x32_bf16 v[44:47], v[140:143], v[222:225], v[44:47]
	v_mfma_f32_16x16x32_bf16 v[40:43], v[170:173], v[222:225], v[40:43]
	v_mfma_f32_16x16x32_bf16 v[28:31], v[140:143], v[230:233], v[28:31]
	v_mfma_f32_16x16x32_bf16 v[24:27], v[170:173], v[230:233], v[24:27]
	v_mfma_f32_16x16x32_bf16 v[12:15], v[140:143], v[238:241], v[12:15]
	v_mfma_f32_16x16x32_bf16 v[8:11], v[170:173], v[238:241], v[8:11]
	v_mfma_f32_16x16x32_bf16 v[60:63], v[166:169], v[218:221], v[60:63]
	v_mfma_f32_16x16x32_bf16 v[56:59], v[174:177], v[218:221], v[56:59]
	v_mfma_f32_16x16x32_bf16 v[44:47], v[166:169], v[226:229], v[44:47]
	v_mfma_f32_16x16x32_bf16 v[40:43], v[174:177], v[226:229], v[40:43]
	v_mfma_f32_16x16x32_bf16 v[28:31], v[166:169], v[234:237], v[28:31]
	v_mfma_f32_16x16x32_bf16 v[24:27], v[174:177], v[234:237], v[24:27]
	v_mfma_f32_16x16x32_bf16 v[12:15], v[166:169], v[242:245], v[12:15]
	v_mfma_f32_16x16x32_bf16 v[8:11], v[174:177], v[242:245], v[8:11]
	s_setprio 0
	s_setprio 1
	v_mfma_f32_16x16x32_bf16 v[52:55], v[178:181], v[214:217], v[52:55]
	v_mfma_f32_16x16x32_bf16 v[48:51], v[186:189], v[214:217], v[48:51]
	v_mfma_f32_16x16x32_bf16 v[36:39], v[178:181], v[222:225], v[36:39]
	v_mfma_f32_16x16x32_bf16 v[32:35], v[186:189], v[222:225], v[32:35]
	v_mfma_f32_16x16x32_bf16 v[20:23], v[178:181], v[230:233], v[20:23]
	v_mfma_f32_16x16x32_bf16 v[16:19], v[186:189], v[230:233], v[16:19]
	v_mfma_f32_16x16x32_bf16 v[4:7], v[178:181], v[238:241], v[4:7]
	v_mfma_f32_16x16x32_bf16 v[0:3], v[186:189], v[238:241], v[0:3]
	v_mfma_f32_16x16x32_bf16 v[52:55], v[182:185], v[218:221], v[52:55]
	v_mfma_f32_16x16x32_bf16 v[48:51], v[210:213], v[218:221], v[48:51]
	v_mfma_f32_16x16x32_bf16 v[36:39], v[182:185], v[226:229], v[36:39]
	v_mfma_f32_16x16x32_bf16 v[32:35], v[210:213], v[226:229], v[32:35]
	v_mfma_f32_16x16x32_bf16 v[20:23], v[182:185], v[234:237], v[20:23]
	v_mfma_f32_16x16x32_bf16 v[16:19], v[210:213], v[234:237], v[16:19]
	v_mfma_f32_16x16x32_bf16 v[4:7], v[182:185], v[242:245], v[4:7]
	v_mfma_f32_16x16x32_bf16 v[0:3], v[210:213], v[242:245], v[0:3]
	s_setprio 0
	s_barrier
	s_add_i32 s55, s55, 2
	s_add_u32 s0, s0, 0x100
	s_addc_u32 s1, s1, 0
	s_add_u32 s53, s53, 0x100
	s_addc_u32 s54, s54, 0
	s_cmp_gt_u32 s55, 13
.LBB0_1042:
	ds_read_b128 v[140:143], v254
	ds_read_b128 v[166:169], v254 offset:1024
	ds_read_b128 v[170:173], v254 offset:2048
	ds_read_b128 v[174:177], v254 offset:3072
	ds_read_b128 v[178:181], v254 offset:16384
	ds_read_b128 v[182:185], v254 offset:17408
	ds_read_b128 v[186:189], v254 offset:18432
	ds_read_b128 v[210:213], v254 offset:19456
	s_add_u32 s2, s0, 0xfffc0080
	s_addc_u32 s3, s1, -1
	s_cmp_eq_u32 s55, 12
	s_cselect_b32 s5, s23, s3
	s_cselect_b32 s4, s51, s2
	s_cselect_b32 s3, s21, s54
	s_cselect_b32 s2, s52, s53
	s_add_i32 m0, s31, 0xc000
	ds_read_b128 v[214:217], v163
	ds_read_b128 v[218:221], v163 offset:1024
	ds_read_b128 v[222:225], v163 offset:2048
	ds_read_b128 v[226:229], v163 offset:3072
	ds_read_b128 v[230:233], v163 offset:4096
	ds_read_b128 v[234:237], v163 offset:5120
	ds_read_b128 v[238:241], v163 offset:6144
	ds_read_b128 v[242:245], v163 offset:7168
	global_load_lds_dwordx4 v136, s[0:1]
	s_add_i32 m0, s31, 0xe000
	s_nop 0
	global_load_lds_dwordx4 v138, s[0:1]
	s_waitcnt vmcnt(8)
	s_waitcnt lgkmcnt(0)
	s_barrier
	s_setprio 1
	s_waitcnt lgkmcnt(0)
	v_mfma_f32_16x16x32_bf16 v[124:127], v[140:143], v[214:217], v[124:127]
	v_mfma_f32_16x16x32_bf16 v[120:123], v[170:173], v[214:217], v[120:123]
	v_mfma_f32_16x16x32_bf16 v[108:111], v[140:143], v[222:225], v[108:111]
	v_mfma_f32_16x16x32_bf16 v[104:107], v[170:173], v[222:225], v[104:107]
	v_mfma_f32_16x16x32_bf16 v[92:95], v[140:143], v[230:233], v[92:95]
	v_mfma_f32_16x16x32_bf16 v[88:91], v[170:173], v[230:233], v[88:91]
	v_mfma_f32_16x16x32_bf16 v[76:79], v[140:143], v[238:241], v[76:79]
	v_mfma_f32_16x16x32_bf16 v[72:75], v[170:173], v[238:241], v[72:75]
	v_mfma_f32_16x16x32_bf16 v[124:127], v[166:169], v[218:221], v[124:127]
	v_mfma_f32_16x16x32_bf16 v[120:123], v[174:177], v[218:221], v[120:123]
	v_mfma_f32_16x16x32_bf16 v[108:111], v[166:169], v[226:229], v[108:111]
	v_mfma_f32_16x16x32_bf16 v[104:107], v[174:177], v[226:229], v[104:107]
	v_mfma_f32_16x16x32_bf16 v[92:95], v[166:169], v[234:237], v[92:95]
	v_mfma_f32_16x16x32_bf16 v[88:91], v[174:177], v[234:237], v[88:91]
	v_mfma_f32_16x16x32_bf16 v[76:79], v[166:169], v[242:245], v[76:79]
	v_mfma_f32_16x16x32_bf16 v[72:75], v[174:177], v[242:245], v[72:75]
	s_setprio 0
	s_setprio 1
	v_mfma_f32_16x16x32_bf16 v[116:119], v[178:181], v[214:217], v[116:119]
	v_mfma_f32_16x16x32_bf16 v[112:115], v[186:189], v[214:217], v[112:115]
	v_mfma_f32_16x16x32_bf16 v[100:103], v[178:181], v[222:225], v[100:103]
	v_mfma_f32_16x16x32_bf16 v[96:99], v[186:189], v[222:225], v[96:99]
	v_mfma_f32_16x16x32_bf16 v[84:87], v[178:181], v[230:233], v[84:87]
	v_mfma_f32_16x16x32_bf16 v[80:83], v[186:189], v[230:233], v[80:83]
	v_mfma_f32_16x16x32_bf16 v[68:71], v[178:181], v[238:241], v[68:71]
	v_mfma_f32_16x16x32_bf16 v[64:67], v[186:189], v[238:241], v[64:67]
	v_mfma_f32_16x16x32_bf16 v[116:119], v[182:185], v[218:221], v[116:119]
	v_mfma_f32_16x16x32_bf16 v[112:115], v[210:213], v[218:221], v[112:115]
	v_mfma_f32_16x16x32_bf16 v[100:103], v[182:185], v[226:229], v[100:103]
	v_mfma_f32_16x16x32_bf16 v[96:99], v[210:213], v[226:229], v[96:99]
	v_mfma_f32_16x16x32_bf16 v[84:87], v[182:185], v[234:237], v[84:87]
	v_mfma_f32_16x16x32_bf16 v[80:83], v[210:213], v[234:237], v[80:83]
	v_mfma_f32_16x16x32_bf16 v[68:71], v[182:185], v[242:245], v[68:71]
	v_mfma_f32_16x16x32_bf16 v[64:67], v[210:213], v[242:245], v[64:67]
	s_setprio 0
	s_barrier
; #define PG8_STAGE(bufoff, gbase, voff) do { _Pragma("unroll") for (int _i = 0; _i < 2; ++_i) \
;         __builtin_amdgcn_global_load_lds((const unsigned*)((const char*)(gbase) + (voff)[_i]), (PG8_LAS unsigned*)(lds + (bufoff) + ldsw + _i * 8192), 16, 0, 0); } while (0)
; #define PG8_LDA(dst, b, h) do { _Pragma("unroll") for (int m = 0; m < 4; ++m) _Pragma("unroll") for (int k = 0; k < 2; ++k) dst[m][k] = *(const PG8_LAS bf16x8*)(lds + PG8_SA(b, h) + aoff + m * 2048 + k * 1024); } while (0)
; #define PG8_LDB(dst, b, h) do { _Pragma("unroll") for (int n = 0; n < 2; ++n) _Pragma("unroll") for (int k = 0; k < 2; ++k) dst[n][k] = *(const PG8_LAS bf16x8*)(lds + PG8_SB(b, h) + boff + n * 2048 + k * 1024); } while (0)
; #define PG8_MMA(ai, bj, At, Bt) do { __builtin_amdgcn_s_setprio(1); _Pragma("unroll") for (int m = 0; m < 4; ++m) _Pragma("unroll") for (int n = 0; n < 2; ++n) _Pragma("unroll") for (int k = 0; k < 2; ++k) \
;         acc[ai][bj][m][n] = __builtin_amdgcn_mfma_f32_16x16x32_bf16(Bt[n][k], At[m][k], acc[ai][bj][m][n], 0, 0, 0); __builtin_amdgcn_s_setprio(0); } while (0)
; #define PG8_WAIT_V(n) asm volatile("s_waitcnt vmcnt(" #n ")" ::: "memory")
; #define PG8_WAIT_L(n) asm volatile("s_waitcnt lgkmcnt(" #n ")" ::: "memory")
; #define PG8_BAR __builtin_amdgcn_s_barrier()
; #define PG8_SCHED __builtin_amdgcn_sched_barrier(0)
; template <class Epi, class Sched, bool ALIGN_EPI = false, bool SP2 = false>
; __device__ __forceinline__ void gemm_phase(PG8_LAS unsigned char* lds, const Gemm g, const Sched& S, const Epi& E) {
;     ...
;             PG8_LDA(At, 0, 1); PG8_STAGE(PG8_SB(0, 0), b2, voffB); PG8_STAGE(PG8_SB(0, 1), b2 + hstep, voffB); PG8_STAGE(PG8_SA(0, 0), a2, voffA);
;             PG8_WAIT_V(8); PG8_WAIT_L(0); PG8_BAR; PG8_MMA(1, 0, At, B0); PG8_MMA(1, 1, At, B1); PG8_BAR; PG8_SCHED;
;             PG8_LDB(B0, 1, 0); PG8_LDB(B1, 1, 1); PG8_SCHED; PG8_LDA(At, 1, 0); PG8_STAGE(PG8_SA(0, 1), a2 + hstep, voffA);
;             PG8_WAIT_V(8); PG8_WAIT_L(0); PG8_BAR; PG8_MMA(0, 0, At, B0); PG8_MMA(0, 1, At, B1); PG8_BAR; PG8_SCHED;
	s_mov_b32 m0, s33
	s_add_u32 s56, s2, 0x40000
	s_addc_u32 s57, s3, 0
	ds_read_b128 v[214:217], v163 offset:16384
	ds_read_b128 v[218:221], v163 offset:17408
	ds_read_b128 v[222:225], v163 offset:18432
	ds_read_b128 v[226:229], v163 offset:19456
	ds_read_b128 v[230:233], v163 offset:20480
	ds_read_b128 v[234:237], v163 offset:21504
	ds_read_b128 v[238:241], v163 offset:22528
	ds_read_b128 v[242:245], v163 offset:23552
	global_load_lds_dwordx4 v132, s[2:3]
	s_mov_b32 m0, s34
	s_nop 0
	global_load_lds_dwordx4 v128, s[2:3]
	s_mov_b32 m0, s35
	s_nop 0
	global_load_lds_dwordx4 v132, s[56:57]
	s_mov_b32 m0, s36
	s_nop 0
	global_load_lds_dwordx4 v128, s[56:57]
	s_mov_b32 m0, s31
	s_nop 0
	global_load_lds_dwordx4 v134, s[4:5]
	s_mov_b32 m0, s37
	s_nop 0
	global_load_lds_dwordx4 v130, s[4:5]
	s_waitcnt vmcnt(8)
	s_waitcnt lgkmcnt(0)
	s_barrier
	s_setprio 1
	s_waitcnt lgkmcnt(0)
	v_mfma_f32_16x16x32_bf16 v[60:63], v[140:143], v[214:217], v[60:63]
	v_mfma_f32_16x16x32_bf16 v[56:59], v[170:173], v[214:217], v[56:59]
	v_mfma_f32_16x16x32_bf16 v[44:47], v[140:143], v[222:225], v[44:47]
	v_mfma_f32_16x16x32_bf16 v[40:43], v[170:173], v[222:225], v[40:43]
	v_mfma_f32_16x16x32_bf16 v[28:31], v[140:143], v[230:233], v[28:31]
	v_mfma_f32_16x16x32_bf16 v[24:27], v[170:173], v[230:233], v[24:27]
	v_mfma_f32_16x16x32_bf16 v[12:15], v[140:143], v[238:241], v[12:15]
	v_mfma_f32_16x16x32_bf16 v[8:11], v[170:173], v[238:241], v[8:11]
	v_mfma_f32_16x16x32_bf16 v[60:63], v[166:169], v[218:221], v[60:63]
	v_mfma_f32_16x16x32_bf16 v[56:59], v[174:177], v[218:221], v[56:59]
	v_mfma_f32_16x16x32_bf16 v[44:47], v[166:169], v[226:229], v[44:47]
	v_mfma_f32_16x16x32_bf16 v[40:43], v[174:177], v[226:229], v[40:43]
	v_mfma_f32_16x16x32_bf16 v[28:31], v[166:169], v[234:237], v[28:31]
	v_mfma_f32_16x16x32_bf16 v[24:27], v[174:177], v[234:237], v[24:27]
	v_mfma_f32_16x16x32_bf16 v[12:15], v[166:169], v[242:245], v[12:15]
	v_mfma_f32_16x16x32_bf16 v[8:11], v[174:177], v[242:245], v[8:11]
	s_setprio 0
	s_setprio 1
	v_mfma_f32_16x16x32_bf16 v[52:55], v[178:181], v[214:217], v[52:55]
	v_mfma_f32_16x16x32_bf16 v[48:51], v[186:189], v[214:217], v[48:51]
	v_mfma_f32_16x16x32_bf16 v[36:39], v[178:181], v[222:225], v[36:39]
	v_mfma_f32_16x16x32_bf16 v[32:35], v[186:189], v[222:225], v[32:35]
	v_mfma_f32_16x16x32_bf16 v[20:23], v[178:181], v[230:233], v[20:23]
	v_mfma_f32_16x16x32_bf16 v[16:19], v[186:189], v[230:233], v[16:19]
	v_mfma_f32_16x16x32_bf16 v[4:7], v[178:181], v[238:241], v[4:7]
	v_mfma_f32_16x16x32_bf16 v[0:3], v[186:189], v[238:241], v[0:3]
	v_mfma_f32_16x16x32_bf16 v[52:55], v[182:185], v[218:221], v[52:55]
	v_mfma_f32_16x16x32_bf16 v[48:51], v[210:213], v[218:221], v[48:51]
	v_mfma_f32_16x16x32_bf16 v[36:39], v[182:185], v[226:229], v[36:39]
	v_mfma_f32_16x16x32_bf16 v[32:35], v[210:213], v[226:229], v[32:35]
	v_mfma_f32_16x16x32_bf16 v[20:23], v[182:185], v[234:237], v[20:23]
	v_mfma_f32_16x16x32_bf16 v[16:19], v[210:213], v[234:237], v[16:19]
	v_mfma_f32_16x16x32_bf16 v[4:7], v[182:185], v[242:245], v[4:7]
	v_mfma_f32_16x16x32_bf16 v[0:3], v[210:213], v[242:245], v[0:3]
	s_setprio 0
	s_barrier
	ds_read_b128 v[140:143], v254 offset:32768
	ds_read_b128 v[166:169], v254 offset:33792
	ds_read_b128 v[170:173], v254 offset:34816
	ds_read_b128 v[174:177], v254 offset:35840
	ds_read_b128 v[178:181], v254 offset:49152
	ds_read_b128 v[182:185], v254 offset:50176
	ds_read_b128 v[186:189], v254 offset:51200
	ds_read_b128 v[210:213], v254 offset:52224
	s_add_u32 s4, s4, 0x40000
	s_addc_u32 s5, s5, 0
	s_mov_b32 m0, s38
	ds_read_b128 v[214:217], v163 offset:32768
	ds_read_b128 v[218:221], v163 offset:33792
	ds_read_b128 v[222:225], v163 offset:34816
	ds_read_b128 v[226:229], v163 offset:35840
	ds_read_b128 v[230:233], v163 offset:36864
	ds_read_b128 v[234:237], v163 offset:37888
	ds_read_b128 v[238:241], v163 offset:38912
	ds_read_b128 v[242:245], v163 offset:39936
	global_load_lds_dwordx4 v134, s[4:5]
	s_mov_b32 m0, s39
	s_nop 0
	global_load_lds_dwordx4 v130, s[4:5]
	s_waitcnt vmcnt(8)
	s_waitcnt lgkmcnt(0)
	s_barrier
; #define PG8_STAGE(bufoff, gbase, voff) do { _Pragma("unroll") for (int _i = 0; _i < 2; ++_i) \
;         __builtin_amdgcn_global_load_lds((const unsigned*)((const char*)(gbase) + (voff)[_i]), (PG8_LAS unsigned*)(lds + (bufoff) + ldsw + _i * 8192), 16, 0, 0); } while (0)
; #define PG8_LDA(dst, b, h) do { _Pragma("unroll") for (int m = 0; m < 4; ++m) _Pragma("unroll") for (int k = 0; k < 2; ++k) dst[m][k] = *(const PG8_LAS bf16x8*)(lds + PG8_SA(b, h) + aoff + m * 2048 + k * 1024); } while (0)
; #define PG8_MMA(ai, bj, At, Bt) do { __builtin_amdgcn_s_setprio(1); _Pragma("unroll") for (int m = 0; m < 4; ++m) _Pragma("unroll") for (int n = 0; n < 2; ++n) _Pragma("unroll") for (int k = 0; k < 2; ++k) \
;         acc[ai][bj][m][n] = __builtin_amdgcn_mfma_f32_16x16x32_bf16(Bt[n][k], At[m][k], acc[ai][bj][m][n], 0, 0, 0); __builtin_amdgcn_s_setprio(0); } while (0)
; #define PG8_WAIT_V(n) asm volatile("s_waitcnt vmcnt(" #n ")" ::: "memory")
; #define PG8_WAIT_L(n) asm volatile("s_waitcnt lgkmcnt(" #n ")" ::: "memory")
; #define PG8_BAR __builtin_amdgcn_s_barrier()
; #define PG8_SCHED __builtin_amdgcn_sched_barrier(0)
; template <class Epi, class Sched, bool ALIGN_EPI = false, bool SP2 = false>
; __device__ __forceinline__ void gemm_phase(PG8_LAS unsigned char* lds, const Gemm g, const Sched& S, const Epi& E) {
;     ...
;         for (int t = 0; t < nt; t += 2) {
;     ...
;             PG8_WAIT_V(8); PG8_WAIT_L(0); PG8_BAR; PG8_MMA(0, 0, At, B0); PG8_MMA(0, 1, At, B1); PG8_BAR; PG8_SCHED;
;             PG8_LDA(At, 1, 1); PG8_STAGE(PG8_SB(1, 0), b3, voffB); PG8_STAGE(PG8_SB(1, 1), b3 + hstep, voffB); PG8_STAGE(PG8_SA(1, 0), a3, voffA);
;             PG8_WAIT_V(8); PG8_WAIT_L(0); PG8_BAR; PG8_MMA(1, 0, At, B0); PG8_MMA(1, 1, At, B1); PG8_BAR; PG8_SCHED;
	s_setprio 1
	s_waitcnt lgkmcnt(0)
	v_mfma_f32_16x16x32_bf16 v[124:127], v[140:143], v[214:217], v[124:127]
	v_mfma_f32_16x16x32_bf16 v[120:123], v[170:173], v[214:217], v[120:123]
	v_mfma_f32_16x16x32_bf16 v[108:111], v[140:143], v[222:225], v[108:111]
	v_mfma_f32_16x16x32_bf16 v[104:107], v[170:173], v[222:225], v[104:107]
	v_mfma_f32_16x16x32_bf16 v[92:95], v[140:143], v[230:233], v[92:95]
	v_mfma_f32_16x16x32_bf16 v[88:91], v[170:173], v[230:233], v[88:91]
	v_mfma_f32_16x16x32_bf16 v[76:79], v[140:143], v[238:241], v[76:79]
	v_mfma_f32_16x16x32_bf16 v[72:75], v[170:173], v[238:241], v[72:75]
	v_mfma_f32_16x16x32_bf16 v[124:127], v[166:169], v[218:221], v[124:127]
	v_mfma_f32_16x16x32_bf16 v[120:123], v[174:177], v[218:221], v[120:123]
	v_mfma_f32_16x16x32_bf16 v[108:111], v[166:169], v[226:229], v[108:111]
	v_mfma_f32_16x16x32_bf16 v[104:107], v[174:177], v[226:229], v[104:107]
	v_mfma_f32_16x16x32_bf16 v[92:95], v[166:169], v[234:237], v[92:95]
	v_mfma_f32_16x16x32_bf16 v[88:91], v[174:177], v[234:237], v[88:91]
	v_mfma_f32_16x16x32_bf16 v[76:79], v[166:169], v[242:245], v[76:79]
	v_mfma_f32_16x16x32_bf16 v[72:75], v[174:177], v[242:245], v[72:75]
	s_setprio 0
	s_setprio 1
	v_mfma_f32_16x16x32_bf16 v[116:119], v[178:181], v[214:217], v[116:119]
	v_mfma_f32_16x16x32_bf16 v[112:115], v[186:189], v[214:217], v[112:115]
	v_mfma_f32_16x16x32_bf16 v[100:103], v[178:181], v[222:225], v[100:103]
	v_mfma_f32_16x16x32_bf16 v[96:99], v[186:189], v[222:225], v[96:99]
	v_mfma_f32_16x16x32_bf16 v[84:87], v[178:181], v[230:233], v[84:87]
	v_mfma_f32_16x16x32_bf16 v[80:83], v[186:189], v[230:233], v[80:83]
	v_mfma_f32_16x16x32_bf16 v[68:71], v[178:181], v[238:241], v[68:71]
	v_mfma_f32_16x16x32_bf16 v[64:67], v[186:189], v[238:241], v[64:67]
	v_mfma_f32_16x16x32_bf16 v[116:119], v[182:185], v[218:221], v[116:119]
	v_mfma_f32_16x16x32_bf16 v[112:115], v[210:213], v[218:221], v[112:115]
	v_mfma_f32_16x16x32_bf16 v[100:103], v[182:185], v[226:229], v[100:103]
	v_mfma_f32_16x16x32_bf16 v[96:99], v[210:213], v[226:229], v[96:99]
	v_mfma_f32_16x16x32_bf16 v[84:87], v[182:185], v[234:237], v[84:87]
	v_mfma_f32_16x16x32_bf16 v[80:83], v[210:213], v[234:237], v[80:83]
	v_mfma_f32_16x16x32_bf16 v[68:71], v[182:185], v[242:245], v[68:71]
	v_mfma_f32_16x16x32_bf16 v[64:67], v[210:213], v[242:245], v[64:67]
	s_setprio 0
	s_barrier
	s_mov_b32 m0, s43
	s_add_u32 s2, s2, 0x40080
	s_addc_u32 s3, s3, 0
	ds_read_b128 v[214:217], v163 offset:49152
	ds_read_b128 v[218:221], v163 offset:50176
	ds_read_b128 v[222:225], v163 offset:51200
	ds_read_b128 v[226:229], v163 offset:52224
	ds_read_b128 v[230:233], v163 offset:53248
	ds_read_b128 v[234:237], v163 offset:54272
	ds_read_b128 v[238:241], v163 offset:55296
	ds_read_b128 v[242:245], v163 offset:56320
	s_add_u32 s98, s2, 0xfffc0000
	s_addc_u32 s99, s3, -1
	global_load_lds_dwordx4 v132, s[98:99]
	s_mov_b32 m0, s44
	s_nop 0
	global_load_lds_dwordx4 v128, s[98:99]
	s_mov_b32 m0, s48
	s_nop 0
	global_load_lds_dwordx4 v132, s[2:3]
	s_mov_b32 m0, s49
	s_nop 0
	global_load_lds_dwordx4 v128, s[2:3]
	s_mov_b32 m0, s45
	s_nop 0
	s_add_u32 s100, s4, 0xfffc0080
	s_addc_u32 s101, s5, -1
	global_load_lds_dwordx4 v134, s[100:101]
	s_mov_b32 m0, s47
	s_nop 0
	global_load_lds_dwordx4 v130, s[100:101]
	s_waitcnt vmcnt(8)
	s_waitcnt lgkmcnt(0)
	s_barrier
	s_setprio 1
	s_waitcnt lgkmcnt(0)
	v_mfma_f32_16x16x32_bf16 v[60:63], v[140:143], v[214:217], v[60:63]
	v_mfma_f32_16x16x32_bf16 v[56:59], v[170:173], v[214:217], v[56:59]
	v_mfma_f32_16x16x32_bf16 v[44:47], v[140:143], v[222:225], v[44:47]
	v_mfma_f32_16x16x32_bf16 v[40:43], v[170:173], v[222:225], v[40:43]
	v_mfma_f32_16x16x32_bf16 v[28:31], v[140:143], v[230:233], v[28:31]
	v_mfma_f32_16x16x32_bf16 v[24:27], v[170:173], v[230:233], v[24:27]
	v_mfma_f32_16x16x32_bf16 v[12:15], v[140:143], v[238:241], v[12:15]
	v_mfma_f32_16x16x32_bf16 v[8:11], v[170:173], v[238:241], v[8:11]
	v_mfma_f32_16x16x32_bf16 v[60:63], v[166:169], v[218:221], v[60:63]
	v_mfma_f32_16x16x32_bf16 v[56:59], v[174:177], v[218:221], v[56:59]
	v_mfma_f32_16x16x32_bf16 v[44:47], v[166:169], v[226:229], v[44:47]
	v_mfma_f32_16x16x32_bf16 v[40:43], v[174:177], v[226:229], v[40:43]
	v_mfma_f32_16x16x32_bf16 v[28:31], v[166:169], v[234:237], v[28:31]
	v_mfma_f32_16x16x32_bf16 v[24:27], v[174:177], v[234:237], v[24:27]
	v_mfma_f32_16x16x32_bf16 v[12:15], v[166:169], v[242:245], v[12:15]
	v_mfma_f32_16x16x32_bf16 v[8:11], v[174:177], v[242:245], v[8:11]
	s_setprio 0
	s_setprio 1
	v_mfma_f32_16x16x32_bf16 v[52:55], v[178:181], v[214:217], v[52:55]
	v_mfma_f32_16x16x32_bf16 v[48:51], v[186:189], v[214:217], v[48:51]
	v_mfma_f32_16x16x32_bf16 v[36:39], v[178:181], v[222:225], v[36:39]
	v_mfma_f32_16x16x32_bf16 v[32:35], v[186:189], v[222:225], v[32:35]
	v_mfma_f32_16x16x32_bf16 v[20:23], v[178:181], v[230:233], v[20:23]
	v_mfma_f32_16x16x32_bf16 v[16:19], v[186:189], v[230:233], v[16:19]
	v_mfma_f32_16x16x32_bf16 v[4:7], v[178:181], v[238:241], v[4:7]
	v_mfma_f32_16x16x32_bf16 v[0:3], v[186:189], v[238:241], v[0:3]
	v_mfma_f32_16x16x32_bf16 v[52:55], v[182:185], v[218:221], v[52:55]
	v_mfma_f32_16x16x32_bf16 v[48:51], v[210:213], v[218:221], v[48:51]
	v_mfma_f32_16x16x32_bf16 v[36:39], v[182:185], v[226:229], v[36:39]
	v_mfma_f32_16x16x32_bf16 v[32:35], v[210:213], v[226:229], v[32:35]
	v_mfma_f32_16x16x32_bf16 v[20:23], v[182:185], v[234:237], v[20:23]
	v_mfma_f32_16x16x32_bf16 v[16:19], v[210:213], v[234:237], v[16:19]
	v_mfma_f32_16x16x32_bf16 v[4:7], v[182:185], v[242:245], v[4:7]
	v_mfma_f32_16x16x32_bf16 v[0:3], v[210:213], v[242:245], v[0:3]
	s_setprio 0
	s_barrier
	s_add_i32 s55, s55, 2
	s_add_u32 s0, s0, 0x100
	s_addc_u32 s1, s1, 0
	s_add_u32 s53, s53, 0x100
	s_addc_u32 s54, s54, 0
	s_cmp_gt_u32 s55, 13
	s_cbranch_scc0 .LBB0_1042
	s_and_b64 vcc, exec, s[18:19]
	s_cbranch_vccz .LBB0_1045
	s_barrier
